# LayerNorm row loads marked nt (rows are read once; keeps them from displacing the next phase's operands in L2)
# speedup vs baseline: 1.0227x; 1.0227x over previous
; __device__ __forceinline__ int otid() { int t = threadIdx.x; asm volatile("" : "+v"(t)); return t; }
; __device__ __forceinline__ void phase_ln(float* R, const float* __restrict__ g, const float* __restrict__ b, bf16_t* xbf, float samp_scale, const float* __restrict__ part, int nsplit, bool f32_all) {
;   const int tid = otid(), lane = tid & 63, gw = blockIdx.x * 8 + (tid >> 6), nw = gridDim.x * 8;
;   f32x4 gv[4], bv[4];
; #pragma unroll
;   for (int i = 0; i < 4; ++i) { gv[i] = *(const f32x4*)(g + i * 256 + lane * 4); bv[i] = *(const f32x4*)(b + i * 256 + lane * 4); }
;   for (int r = gw; r < MT; r += nw) {
;     float* row = R + (size_t)r * 1024;
;     f32x4 v[4];
; #pragma unroll
;     for (int i = 0; i < 4; ++i) v[i] = *(const f32x4*)(row + i * 256 + lane * 4);
;     if (r >= MP) {
;       for (int sp = 0; sp < nsplit; ++sp) {
;         const float* prow = part + ((size_t)sp * MS + (r - MP)) * 1024;
; #pragma unroll
;         for (int i = 0; i < 4; ++i) v[i] = v[i] + *(const f32x4*)(prow + i * 256 + lane * 4);
;       }
;     }
;     float s = 0.f;
; #pragma unroll
;     for (int i = 0; i < 4; ++i) s += v[i][0] + v[i][1] + v[i][2] + v[i][3];
; #pragma unroll
;     for (int o = 32; o >= 1; o >>= 1) s += __shfl_xor(s, o);
;     const float mean = s * (1.f / 1024.f);
;     float ss = 0.f;
; #pragma unroll
;     for (int i = 0; i < 4; ++i) { v[i] = v[i] - mean; ss += v[i][0] * v[i][0] + v[i][1] * v[i][1] + v[i][2] * v[i][2] + v[i][3] * v[i][3]; }
; #pragma unroll
;     for (int o = 32; o >= 1; o >>= 1) ss += __shfl_xor(ss, o);
;     const float rstd = rsqrtf(ss * (1.f / 1024.f) + LN_EPS);
; #pragma unroll
;     for (int i = 0; i < 4; ++i) {
;       const f32x4 y = v[i] * rstd * gv[i] + bv[i];
;       if (r >= MP) *(f32x4*)(row + i * 256 + lane * 4) = y * samp_scale;
;       else if (f32_all) *(f32x4*)(row + i * 256 + lane * 4) = y;
;       if (xbf) {
;         u32x2 wv;
;         wv[0] = cvt_pk_bf16(y[0], y[1]); wv[1] = cvt_pk_bf16(y[2], y[3]);
;         *(u32x2*)(xbf + (size_t)r * 1024 + i * 256 + lane * 4) = wv;
;       }
;     }
.LBB0_3720:
	s_or_b64 exec, exec, s[0:1]
	v_readlane_b32 s0, v254, 51
	s_nop 0
	s_cmp_lg_u32 s0, 0
	s_cbranch_scc1 .Lln1_orig
	v_readlane_b32 s6, v254, 2
	v_readlane_b32 s7, v254, 3
	v_readlane_b32 s8, v255, 22
	s_waitcnt lgkmcnt(0)
	s_barrier
	s_load_dwordx4 s[0:3], s[6:7], 0x78
	s_load_dwordx4 s[4:7], s[6:7], 0xa8
	v_readlane_b32 s9, v254, 15
	v_readfirstlane_b32 s10, v244
	v_lshlrev_b32_e32 v114, 4, v252
	v_lshlrev_b32_e32 v115, 3, v252
	s_lshr_b32 s10, s10, 6
	s_add_i32 s9, s9, s10
	s_lshl_b32 s11, s8, 12
	s_waitcnt lgkmcnt(0)
	s_add_u32 s0, s0, s11
	s_addc_u32 s1, s1, 0
	s_add_u32 s2, s2, s11
	s_addc_u32 s3, s3, 0
	global_load_dwordx4 v[34:37], v114, s[0:1] offset:0 nt
	global_load_dwordx4 v[38:41], v114, s[0:1] offset:1024 nt
	global_load_dwordx4 v[42:45], v114, s[0:1] offset:2048 nt
	global_load_dwordx4 v[46:49], v114, s[0:1] offset:3072 nt
	global_load_dwordx4 v[50:53], v114, s[2:3] offset:0
	global_load_dwordx4 v[54:57], v114, s[2:3] offset:1024
	global_load_dwordx4 v[58:61], v114, s[2:3] offset:2048
	global_load_dwordx4 v[62:65], v114, s[2:3] offset:3072
	s_lshl_b32 s11, s9, 12
	s_add_u32 s0, s4, s11
	s_addc_u32 s1, s5, 0
	s_lshl_b32 s11, s9, 11
	s_add_u32 s11, s11, 0x39c0000
	s_add_u32 s2, s6, s11
	s_addc_u32 s3, s7, 0
	global_load_dwordx4 v[0:3], v114, s[0:1] offset:0 nt
	global_load_dwordx4 v[4:7], v114, s[0:1] offset:1024 nt
	global_load_dwordx4 v[8:11], v114, s[0:1] offset:2048 nt
	global_load_dwordx4 v[12:15], v114, s[0:1] offset:3072 nt
	s_add_u32 s0, s0, 0x800000
	s_addc_u32 s1, s1, 0
	global_load_dwordx4 v[18:21], v114, s[0:1] offset:0 nt
	global_load_dwordx4 v[22:25], v114, s[0:1] offset:1024 nt
	global_load_dwordx4 v[26:29], v114, s[0:1] offset:2048 nt
	global_load_dwordx4 v[30:33], v114, s[0:1] offset:3072 nt
	s_waitcnt vmcnt(4)
	v_pk_add_f32 v[66:67], v[0:1], v[2:3]
	v_pk_add_f32 v[68:69], v[4:5], v[6:7]
	v_pk_add_f32 v[70:71], v[8:9], v[10:11]
	v_pk_add_f32 v[72:73], v[12:13], v[14:15]
	v_pk_add_f32 v[66:67], v[66:67], v[68:69]
	v_pk_add_f32 v[70:71], v[70:71], v[72:73]
	v_pk_add_f32 v[66:67], v[66:67], v[70:71]
	v_add_f32_e32 v66, v66, v67
	s_nop 1
	v_add_f32_dpp v66, v66, v66 row_shr:1 row_mask:0xf bank_mask:0xf bound_ctrl:1
	s_nop 1
	v_add_f32_dpp v66, v66, v66 row_shr:2 row_mask:0xf bank_mask:0xf bound_ctrl:1
	s_nop 1
	v_add_f32_dpp v66, v66, v66 row_shr:4 row_mask:0xf bank_mask:0xf bound_ctrl:1
	s_nop 1
	v_add_f32_dpp v66, v66, v66 row_shr:8 row_mask:0xf bank_mask:0xf bound_ctrl:1
	s_nop 0
	v_readlane_b32 s9, v66, 15
	v_readlane_b32 s10, v66, 31
	v_readlane_b32 s11, v66, 47
	v_readlane_b32 vcc_lo, v66, 63
	s_nop 1
	v_mov_b32_e32 v66, s9
	v_add_f32_e32 v66, s10, v66
	v_add_f32_e32 v66, s11, v66
	v_add_f32_e32 v66, vcc_lo, v66
	v_mul_f32_e32 v116, 0x3a800000, v66
	v_mov_b32_e32 v117, v116
	v_pk_add_f32 v[0:1], v[0:1], v[116:117] neg_lo:[0,1] neg_hi:[0,1]
	v_pk_add_f32 v[2:3], v[2:3], v[116:117] neg_lo:[0,1] neg_hi:[0,1]
	v_pk_add_f32 v[4:5], v[4:5], v[116:117] neg_lo:[0,1] neg_hi:[0,1]
	v_pk_add_f32 v[6:7], v[6:7], v[116:117] neg_lo:[0,1] neg_hi:[0,1]
	v_pk_add_f32 v[8:9], v[8:9], v[116:117] neg_lo:[0,1] neg_hi:[0,1]
	v_pk_add_f32 v[10:11], v[10:11], v[116:117] neg_lo:[0,1] neg_hi:[0,1]
	v_pk_add_f32 v[12:13], v[12:13], v[116:117] neg_lo:[0,1] neg_hi:[0,1]
	v_pk_add_f32 v[14:15], v[14:15], v[116:117] neg_lo:[0,1] neg_hi:[0,1]
	v_pk_mul_f32 v[66:67], v[0:1], v[0:1]
	v_pk_mul_f32 v[68:69], v[2:3], v[2:3]
	v_pk_fma_f32 v[66:67], v[4:5], v[4:5], v[66:67]
	v_pk_fma_f32 v[68:69], v[6:7], v[6:7], v[68:69]
	v_pk_fma_f32 v[66:67], v[8:9], v[8:9], v[66:67]
	v_pk_fma_f32 v[68:69], v[10:11], v[10:11], v[68:69]
	v_pk_fma_f32 v[66:67], v[12:13], v[12:13], v[66:67]
	v_pk_fma_f32 v[68:69], v[14:15], v[14:15], v[68:69]
	v_pk_add_f32 v[66:67], v[66:67], v[68:69]
	v_add_f32_e32 v66, v66, v67
	s_nop 1
	v_add_f32_dpp v66, v66, v66 row_shr:1 row_mask:0xf bank_mask:0xf bound_ctrl:1
	s_nop 1
	v_add_f32_dpp v66, v66, v66 row_shr:2 row_mask:0xf bank_mask:0xf bound_ctrl:1
	s_nop 1
	v_add_f32_dpp v66, v66, v66 row_shr:4 row_mask:0xf bank_mask:0xf bound_ctrl:1
	s_nop 1
	v_add_f32_dpp v66, v66, v66 row_shr:8 row_mask:0xf bank_mask:0xf bound_ctrl:1
	s_nop 0
	v_readlane_b32 s9, v66, 15
	v_readlane_b32 s10, v66, 31
	v_readlane_b32 s11, v66, 47
	v_readlane_b32 vcc_lo, v66, 63
	s_nop 1
	v_mov_b32_e32 v66, s9
	v_add_f32_e32 v66, s10, v66
	v_add_f32_e32 v66, s11, v66
	v_add_f32_e32 v66, vcc_lo, v66
	v_mul_f32_e32 v66, 0x3a800000, v66
	v_add_f32_e32 v66, 0x3727c5ac, v66
	v_rsq_f32_e32 v118, v66
	s_nop 0
	v_mov_b32_e32 v119, v118
	v_pk_mul_f32 v[0:1], v[0:1], v[118:119]
	v_pk_mul_f32 v[2:3], v[2:3], v[118:119]
	v_pk_mul_f32 v[4:5], v[4:5], v[118:119]
	v_pk_mul_f32 v[6:7], v[6:7], v[118:119]
	v_pk_mul_f32 v[8:9], v[8:9], v[118:119]
	v_pk_mul_f32 v[10:11], v[10:11], v[118:119]
	v_pk_mul_f32 v[12:13], v[12:13], v[118:119]
	v_pk_mul_f32 v[14:15], v[14:15], v[118:119]
	v_pk_fma_f32 v[76:77], v[0:1], v[34:35], v[50:51]
	v_pk_fma_f32 v[78:79], v[2:3], v[36:37], v[52:53]
	v_pk_fma_f32 v[80:81], v[4:5], v[38:39], v[54:55]
	v_pk_fma_f32 v[82:83], v[6:7], v[40:41], v[56:57]
	v_pk_fma_f32 v[84:85], v[8:9], v[42:43], v[58:59]
	v_pk_fma_f32 v[86:87], v[10:11], v[44:45], v[60:61]
	v_pk_fma_f32 v[88:89], v[12:13], v[46:47], v[62:63]
	v_pk_fma_f32 v[90:91], v[14:15], v[48:49], v[64:65]
	v_cvt_pk_bf16_f32 v92, v76, v77
	v_cvt_pk_bf16_f32 v93, v78, v79
	v_cvt_pk_bf16_f32 v94, v80, v81
	v_cvt_pk_bf16_f32 v95, v82, v83
	v_cvt_pk_bf16_f32 v96, v84, v85
	v_cvt_pk_bf16_f32 v97, v86, v87
	v_cvt_pk_bf16_f32 v98, v88, v89
	v_cvt_pk_bf16_f32 v99, v90, v91
	global_store_dwordx2 v115, v[92:93], s[2:3] offset:0 sc1
	global_store_dwordx2 v115, v[94:95], s[2:3] offset:512 sc1
	global_store_dwordx2 v115, v[96:97], s[2:3] offset:1024 sc1
	global_store_dwordx2 v115, v[98:99], s[2:3] offset:1536 sc1
	s_add_u32 s2, s2, 0x400000
	s_addc_u32 s3, s3, 0
	s_add_u32 s0, s0, 0x800000
	s_addc_u32 s1, s1, 0
	global_load_dwordx4 v[0:3], v114, s[0:1] offset:0 nt
	global_load_dwordx4 v[4:7], v114, s[0:1] offset:1024 nt
	global_load_dwordx4 v[8:11], v114, s[0:1] offset:2048 nt
	global_load_dwordx4 v[12:15], v114, s[0:1] offset:3072 nt
	s_waitcnt vmcnt(8)
; __device__ __forceinline__ void phase_ln(float* R, const float* __restrict__ g, const float* __restrict__ b, bf16_t* xbf, float samp_scale, const float* __restrict__ part, int nsplit, bool f32_all) {
;     ...
;   for (int r = gw; r < MT; r += nw) {
;     float* row = R + (size_t)r * 1024;
;     f32x4 v[4];
; #pragma unroll
;     for (int i = 0; i < 4; ++i) v[i] = *(const f32x4*)(row + i * 256 + lane * 4);
;     if (r >= MP) {
;       for (int sp = 0; sp < nsplit; ++sp) {
;         const float* prow = part + ((size_t)sp * MS + (r - MP)) * 1024;
; #pragma unroll
;         for (int i = 0; i < 4; ++i) v[i] = v[i] + *(const f32x4*)(prow + i * 256 + lane * 4);
;       }
;     }
;     float s = 0.f;
; #pragma unroll
;     for (int i = 0; i < 4; ++i) s += v[i][0] + v[i][1] + v[i][2] + v[i][3];
; #pragma unroll
;     for (int o = 32; o >= 1; o >>= 1) s += __shfl_xor(s, o);
;     const float mean = s * (1.f / 1024.f);
;     float ss = 0.f;
; #pragma unroll
;     for (int i = 0; i < 4; ++i) { v[i] = v[i] - mean; ss += v[i][0] * v[i][0] + v[i][1] * v[i][1] + v[i][2] * v[i][2] + v[i][3] * v[i][3]; }
; #pragma unroll
;     for (int o = 32; o >= 1; o >>= 1) ss += __shfl_xor(ss, o);
;     const float rstd = rsqrtf(ss * (1.f / 1024.f) + LN_EPS);
; #pragma unroll
;     for (int i = 0; i < 4; ++i) {
;       const f32x4 y = v[i] * rstd * gv[i] + bv[i];
;       if (r >= MP) *(f32x4*)(row + i * 256 + lane * 4) = y * samp_scale;
;       else if (f32_all) *(f32x4*)(row + i * 256 + lane * 4) = y;
;       if (xbf) {
;         u32x2 wv;
;         wv[0] = cvt_pk_bf16(y[0], y[1]); wv[1] = cvt_pk_bf16(y[2], y[3]);
;         *(u32x2*)(xbf + (size_t)r * 1024 + i * 256 + lane * 4) = wv;
;       }
;     }
	v_pk_add_f32 v[66:67], v[18:19], v[20:21]
	v_pk_add_f32 v[68:69], v[22:23], v[24:25]
	v_pk_add_f32 v[70:71], v[26:27], v[28:29]
	v_pk_add_f32 v[72:73], v[30:31], v[32:33]
	v_pk_add_f32 v[66:67], v[66:67], v[68:69]
	v_pk_add_f32 v[70:71], v[70:71], v[72:73]
	v_pk_add_f32 v[66:67], v[66:67], v[70:71]
	v_add_f32_e32 v66, v66, v67
	s_nop 1
	v_add_f32_dpp v66, v66, v66 row_shr:1 row_mask:0xf bank_mask:0xf bound_ctrl:1
	s_nop 1
	v_add_f32_dpp v66, v66, v66 row_shr:2 row_mask:0xf bank_mask:0xf bound_ctrl:1
	s_nop 1
	v_add_f32_dpp v66, v66, v66 row_shr:4 row_mask:0xf bank_mask:0xf bound_ctrl:1
	s_nop 1
	v_add_f32_dpp v66, v66, v66 row_shr:8 row_mask:0xf bank_mask:0xf bound_ctrl:1
	s_nop 0
	v_readlane_b32 s9, v66, 15
	v_readlane_b32 s10, v66, 31
	v_readlane_b32 s11, v66, 47
	v_readlane_b32 vcc_lo, v66, 63
	s_nop 1
	v_mov_b32_e32 v66, s9
	v_add_f32_e32 v66, s10, v66
	v_add_f32_e32 v66, s11, v66
	v_add_f32_e32 v66, vcc_lo, v66
	v_mul_f32_e32 v116, 0x3a800000, v66
	v_mov_b32_e32 v117, v116
	v_pk_add_f32 v[18:19], v[18:19], v[116:117] neg_lo:[0,1] neg_hi:[0,1]
	v_pk_add_f32 v[20:21], v[20:21], v[116:117] neg_lo:[0,1] neg_hi:[0,1]
	v_pk_add_f32 v[22:23], v[22:23], v[116:117] neg_lo:[0,1] neg_hi:[0,1]
	v_pk_add_f32 v[24:25], v[24:25], v[116:117] neg_lo:[0,1] neg_hi:[0,1]
	v_pk_add_f32 v[26:27], v[26:27], v[116:117] neg_lo:[0,1] neg_hi:[0,1]
	v_pk_add_f32 v[28:29], v[28:29], v[116:117] neg_lo:[0,1] neg_hi:[0,1]
	v_pk_add_f32 v[30:31], v[30:31], v[116:117] neg_lo:[0,1] neg_hi:[0,1]
	v_pk_add_f32 v[32:33], v[32:33], v[116:117] neg_lo:[0,1] neg_hi:[0,1]
	v_pk_mul_f32 v[66:67], v[18:19], v[18:19]
	v_pk_mul_f32 v[68:69], v[20:21], v[20:21]
	v_pk_fma_f32 v[66:67], v[22:23], v[22:23], v[66:67]
	v_pk_fma_f32 v[68:69], v[24:25], v[24:25], v[68:69]
	v_pk_fma_f32 v[66:67], v[26:27], v[26:27], v[66:67]
	v_pk_fma_f32 v[68:69], v[28:29], v[28:29], v[68:69]
	v_pk_fma_f32 v[66:67], v[30:31], v[30:31], v[66:67]
	v_pk_fma_f32 v[68:69], v[32:33], v[32:33], v[68:69]
	v_pk_add_f32 v[66:67], v[66:67], v[68:69]
	v_add_f32_e32 v66, v66, v67
	s_nop 1
	v_add_f32_dpp v66, v66, v66 row_shr:1 row_mask:0xf bank_mask:0xf bound_ctrl:1
	s_nop 1
	v_add_f32_dpp v66, v66, v66 row_shr:2 row_mask:0xf bank_mask:0xf bound_ctrl:1
	s_nop 1
	v_add_f32_dpp v66, v66, v66 row_shr:4 row_mask:0xf bank_mask:0xf bound_ctrl:1
	s_nop 1
	v_add_f32_dpp v66, v66, v66 row_shr:8 row_mask:0xf bank_mask:0xf bound_ctrl:1
	s_nop 0
	v_readlane_b32 s9, v66, 15
	v_readlane_b32 s10, v66, 31
	v_readlane_b32 s11, v66, 47
	v_readlane_b32 vcc_lo, v66, 63
	s_nop 1
	v_mov_b32_e32 v66, s9
	v_add_f32_e32 v66, s10, v66
	v_add_f32_e32 v66, s11, v66
	v_add_f32_e32 v66, vcc_lo, v66
	v_mul_f32_e32 v66, 0x3a800000, v66
	v_add_f32_e32 v66, 0x3727c5ac, v66
	v_rsq_f32_e32 v118, v66
	s_nop 0
	v_mov_b32_e32 v119, v118
	v_pk_mul_f32 v[18:19], v[18:19], v[118:119]
	v_pk_mul_f32 v[20:21], v[20:21], v[118:119]
	v_pk_mul_f32 v[22:23], v[22:23], v[118:119]
	v_pk_mul_f32 v[24:25], v[24:25], v[118:119]
	v_pk_mul_f32 v[26:27], v[26:27], v[118:119]
	v_pk_mul_f32 v[28:29], v[28:29], v[118:119]
	v_pk_mul_f32 v[30:31], v[30:31], v[118:119]
	v_pk_mul_f32 v[32:33], v[32:33], v[118:119]
	v_pk_fma_f32 v[76:77], v[18:19], v[34:35], v[50:51]
	v_pk_fma_f32 v[78:79], v[20:21], v[36:37], v[52:53]
	v_pk_fma_f32 v[80:81], v[22:23], v[38:39], v[54:55]
	v_pk_fma_f32 v[82:83], v[24:25], v[40:41], v[56:57]
	v_pk_fma_f32 v[84:85], v[26:27], v[42:43], v[58:59]
	v_pk_fma_f32 v[86:87], v[28:29], v[44:45], v[60:61]
	v_pk_fma_f32 v[88:89], v[30:31], v[46:47], v[62:63]
	v_pk_fma_f32 v[90:91], v[32:33], v[48:49], v[64:65]
	v_cvt_pk_bf16_f32 v92, v76, v77
	v_cvt_pk_bf16_f32 v93, v78, v79
	v_cvt_pk_bf16_f32 v94, v80, v81
	v_cvt_pk_bf16_f32 v95, v82, v83
	v_cvt_pk_bf16_f32 v96, v84, v85
	v_cvt_pk_bf16_f32 v97, v86, v87
	v_cvt_pk_bf16_f32 v98, v88, v89
	v_cvt_pk_bf16_f32 v99, v90, v91
	global_store_dwordx2 v115, v[92:93], s[2:3] offset:0 sc1
	global_store_dwordx2 v115, v[94:95], s[2:3] offset:512 sc1
	global_store_dwordx2 v115, v[96:97], s[2:3] offset:1024 sc1
	global_store_dwordx2 v115, v[98:99], s[2:3] offset:1536 sc1
	s_add_u32 s2, s2, 0x400000
	s_addc_u32 s3, s3, 0
	s_add_u32 s0, s0, 0x800000
	s_addc_u32 s1, s1, 0
	global_load_dwordx4 v[18:21], v114, s[0:1] offset:0 nt
	global_load_dwordx4 v[22:25], v114, s[0:1] offset:1024 nt
	global_load_dwordx4 v[26:29], v114, s[0:1] offset:2048 nt
	global_load_dwordx4 v[30:33], v114, s[0:1] offset:3072 nt
	s_waitcnt vmcnt(8)
; __device__ __forceinline__ void phase_ln(float* R, const float* __restrict__ g, const float* __restrict__ b, bf16_t* xbf, float samp_scale, const float* __restrict__ part, int nsplit, bool f32_all) {
;     ...
;   for (int r = gw; r < MT; r += nw) {
;     float* row = R + (size_t)r * 1024;
;     f32x4 v[4];
; #pragma unroll
;     for (int i = 0; i < 4; ++i) v[i] = *(const f32x4*)(row + i * 256 + lane * 4);
;     if (r >= MP) {
;       for (int sp = 0; sp < nsplit; ++sp) {
;         const float* prow = part + ((size_t)sp * MS + (r - MP)) * 1024;
; #pragma unroll
;         for (int i = 0; i < 4; ++i) v[i] = v[i] + *(const f32x4*)(prow + i * 256 + lane * 4);
;       }
;     }
;     float s = 0.f;
; #pragma unroll
;     for (int i = 0; i < 4; ++i) s += v[i][0] + v[i][1] + v[i][2] + v[i][3];
; #pragma unroll
;     for (int o = 32; o >= 1; o >>= 1) s += __shfl_xor(s, o);
;     const float mean = s * (1.f / 1024.f);
;     float ss = 0.f;
; #pragma unroll
;     for (int i = 0; i < 4; ++i) { v[i] = v[i] - mean; ss += v[i][0] * v[i][0] + v[i][1] * v[i][1] + v[i][2] * v[i][2] + v[i][3] * v[i][3]; }
; #pragma unroll
;     for (int o = 32; o >= 1; o >>= 1) ss += __shfl_xor(ss, o);
;     const float rstd = rsqrtf(ss * (1.f / 1024.f) + LN_EPS);
; #pragma unroll
;     for (int i = 0; i < 4; ++i) {
;       const f32x4 y = v[i] * rstd * gv[i] + bv[i];
;       if (r >= MP) *(f32x4*)(row + i * 256 + lane * 4) = y * samp_scale;
;       else if (f32_all) *(f32x4*)(row + i * 256 + lane * 4) = y;
;       if (xbf) {
;         u32x2 wv;
;         wv[0] = cvt_pk_bf16(y[0], y[1]); wv[1] = cvt_pk_bf16(y[2], y[3]);
;         *(u32x2*)(xbf + (size_t)r * 1024 + i * 256 + lane * 4) = wv;
;       }
;     }
	v_pk_add_f32 v[66:67], v[0:1], v[2:3]
	v_pk_add_f32 v[68:69], v[4:5], v[6:7]
	v_pk_add_f32 v[70:71], v[8:9], v[10:11]
	v_pk_add_f32 v[72:73], v[12:13], v[14:15]
	v_pk_add_f32 v[66:67], v[66:67], v[68:69]
	v_pk_add_f32 v[70:71], v[70:71], v[72:73]
	v_pk_add_f32 v[66:67], v[66:67], v[70:71]
	v_add_f32_e32 v66, v66, v67
	s_nop 1
	v_add_f32_dpp v66, v66, v66 row_shr:1 row_mask:0xf bank_mask:0xf bound_ctrl:1
	s_nop 1
	v_add_f32_dpp v66, v66, v66 row_shr:2 row_mask:0xf bank_mask:0xf bound_ctrl:1
	s_nop 1
	v_add_f32_dpp v66, v66, v66 row_shr:4 row_mask:0xf bank_mask:0xf bound_ctrl:1
	s_nop 1
	v_add_f32_dpp v66, v66, v66 row_shr:8 row_mask:0xf bank_mask:0xf bound_ctrl:1
	s_nop 0
	v_readlane_b32 s9, v66, 15
	v_readlane_b32 s10, v66, 31
	v_readlane_b32 s11, v66, 47
	v_readlane_b32 vcc_lo, v66, 63
	s_nop 1
	v_mov_b32_e32 v66, s9
	v_add_f32_e32 v66, s10, v66
	v_add_f32_e32 v66, s11, v66
	v_add_f32_e32 v66, vcc_lo, v66
	v_mul_f32_e32 v116, 0x3a800000, v66
	v_mov_b32_e32 v117, v116
	v_pk_add_f32 v[0:1], v[0:1], v[116:117] neg_lo:[0,1] neg_hi:[0,1]
	v_pk_add_f32 v[2:3], v[2:3], v[116:117] neg_lo:[0,1] neg_hi:[0,1]
	v_pk_add_f32 v[4:5], v[4:5], v[116:117] neg_lo:[0,1] neg_hi:[0,1]
	v_pk_add_f32 v[6:7], v[6:7], v[116:117] neg_lo:[0,1] neg_hi:[0,1]
	v_pk_add_f32 v[8:9], v[8:9], v[116:117] neg_lo:[0,1] neg_hi:[0,1]
	v_pk_add_f32 v[10:11], v[10:11], v[116:117] neg_lo:[0,1] neg_hi:[0,1]
	v_pk_add_f32 v[12:13], v[12:13], v[116:117] neg_lo:[0,1] neg_hi:[0,1]
	v_pk_add_f32 v[14:15], v[14:15], v[116:117] neg_lo:[0,1] neg_hi:[0,1]
	v_pk_mul_f32 v[66:67], v[0:1], v[0:1]
	v_pk_mul_f32 v[68:69], v[2:3], v[2:3]
	v_pk_fma_f32 v[66:67], v[4:5], v[4:5], v[66:67]
	v_pk_fma_f32 v[68:69], v[6:7], v[6:7], v[68:69]
	v_pk_fma_f32 v[66:67], v[8:9], v[8:9], v[66:67]
	v_pk_fma_f32 v[68:69], v[10:11], v[10:11], v[68:69]
	v_pk_fma_f32 v[66:67], v[12:13], v[12:13], v[66:67]
	v_pk_fma_f32 v[68:69], v[14:15], v[14:15], v[68:69]
	v_pk_add_f32 v[66:67], v[66:67], v[68:69]
	v_add_f32_e32 v66, v66, v67
	s_nop 1
	v_add_f32_dpp v66, v66, v66 row_shr:1 row_mask:0xf bank_mask:0xf bound_ctrl:1
	s_nop 1
	v_add_f32_dpp v66, v66, v66 row_shr:2 row_mask:0xf bank_mask:0xf bound_ctrl:1
	s_nop 1
	v_add_f32_dpp v66, v66, v66 row_shr:4 row_mask:0xf bank_mask:0xf bound_ctrl:1
	s_nop 1
	v_add_f32_dpp v66, v66, v66 row_shr:8 row_mask:0xf bank_mask:0xf bound_ctrl:1
	s_nop 0
	v_readlane_b32 s9, v66, 15
	v_readlane_b32 s10, v66, 31
	v_readlane_b32 s11, v66, 47
	v_readlane_b32 vcc_lo, v66, 63
	s_nop 1
	v_mov_b32_e32 v66, s9
	v_add_f32_e32 v66, s10, v66
	v_add_f32_e32 v66, s11, v66
	v_add_f32_e32 v66, vcc_lo, v66
	v_mul_f32_e32 v66, 0x3a800000, v66
	v_add_f32_e32 v66, 0x3727c5ac, v66
	v_rsq_f32_e32 v118, v66
	s_nop 0
	v_mov_b32_e32 v119, v118
	v_pk_mul_f32 v[0:1], v[0:1], v[118:119]
	v_pk_mul_f32 v[2:3], v[2:3], v[118:119]
	v_pk_mul_f32 v[4:5], v[4:5], v[118:119]
	v_pk_mul_f32 v[6:7], v[6:7], v[118:119]
	v_pk_mul_f32 v[8:9], v[8:9], v[118:119]
	v_pk_mul_f32 v[10:11], v[10:11], v[118:119]
	v_pk_mul_f32 v[12:13], v[12:13], v[118:119]
	v_pk_mul_f32 v[14:15], v[14:15], v[118:119]
	v_pk_fma_f32 v[76:77], v[0:1], v[34:35], v[50:51]
	v_pk_fma_f32 v[78:79], v[2:3], v[36:37], v[52:53]
	v_pk_fma_f32 v[80:81], v[4:5], v[38:39], v[54:55]
	v_pk_fma_f32 v[82:83], v[6:7], v[40:41], v[56:57]
	v_pk_fma_f32 v[84:85], v[8:9], v[42:43], v[58:59]
	v_pk_fma_f32 v[86:87], v[10:11], v[44:45], v[60:61]
	v_pk_fma_f32 v[88:89], v[12:13], v[46:47], v[62:63]
	v_pk_fma_f32 v[90:91], v[14:15], v[48:49], v[64:65]
	v_cvt_pk_bf16_f32 v92, v76, v77
	v_cvt_pk_bf16_f32 v93, v78, v79
	v_cvt_pk_bf16_f32 v94, v80, v81
	v_cvt_pk_bf16_f32 v95, v82, v83
	v_cvt_pk_bf16_f32 v96, v84, v85
	v_cvt_pk_bf16_f32 v97, v86, v87
	v_cvt_pk_bf16_f32 v98, v88, v89
	v_cvt_pk_bf16_f32 v99, v90, v91
	global_store_dwordx2 v115, v[92:93], s[2:3] offset:0 sc1
	global_store_dwordx2 v115, v[94:95], s[2:3] offset:512 sc1
	global_store_dwordx2 v115, v[96:97], s[2:3] offset:1024 sc1
	global_store_dwordx2 v115, v[98:99], s[2:3] offset:1536 sc1
	s_add_u32 s2, s2, 0x400000
	s_addc_u32 s3, s3, 0
	s_add_u32 s0, s0, 0x800000
	s_addc_u32 s1, s1, 0
	global_load_dwordx4 v[0:3], v114, s[0:1] offset:0 nt
	global_load_dwordx4 v[4:7], v114, s[0:1] offset:1024 nt
	global_load_dwordx4 v[8:11], v114, s[0:1] offset:2048 nt
	global_load_dwordx4 v[12:15], v114, s[0:1] offset:3072 nt
	s_waitcnt vmcnt(8)
; __device__ __forceinline__ void phase_ln(float* R, const float* __restrict__ g, const float* __restrict__ b, bf16_t* xbf, float samp_scale, const float* __restrict__ part, int nsplit, bool f32_all) {
;     ...
;   for (int r = gw; r < MT; r += nw) {
;     float* row = R + (size_t)r * 1024;
;     f32x4 v[4];
; #pragma unroll
;     for (int i = 0; i < 4; ++i) v[i] = *(const f32x4*)(row + i * 256 + lane * 4);
;     if (r >= MP) {
;       for (int sp = 0; sp < nsplit; ++sp) {
;         const float* prow = part + ((size_t)sp * MS + (r - MP)) * 1024;
; #pragma unroll
;         for (int i = 0; i < 4; ++i) v[i] = v[i] + *(const f32x4*)(prow + i * 256 + lane * 4);
;       }
;     }
;     float s = 0.f;
; #pragma unroll
;     for (int i = 0; i < 4; ++i) s += v[i][0] + v[i][1] + v[i][2] + v[i][3];
; #pragma unroll
;     for (int o = 32; o >= 1; o >>= 1) s += __shfl_xor(s, o);
;     const float mean = s * (1.f / 1024.f);
;     float ss = 0.f;
; #pragma unroll
;     for (int i = 0; i < 4; ++i) { v[i] = v[i] - mean; ss += v[i][0] * v[i][0] + v[i][1] * v[i][1] + v[i][2] * v[i][2] + v[i][3] * v[i][3]; }
; #pragma unroll
;     for (int o = 32; o >= 1; o >>= 1) ss += __shfl_xor(ss, o);
;     const float rstd = rsqrtf(ss * (1.f / 1024.f) + LN_EPS);
; #pragma unroll
;     for (int i = 0; i < 4; ++i) {
;       const f32x4 y = v[i] * rstd * gv[i] + bv[i];
;       if (r >= MP) *(f32x4*)(row + i * 256 + lane * 4) = y * samp_scale;
;       else if (f32_all) *(f32x4*)(row + i * 256 + lane * 4) = y;
;       if (xbf) {
;         u32x2 wv;
;         wv[0] = cvt_pk_bf16(y[0], y[1]); wv[1] = cvt_pk_bf16(y[2], y[3]);
;         *(u32x2*)(xbf + (size_t)r * 1024 + i * 256 + lane * 4) = wv;
;       }
;     }
	v_pk_add_f32 v[66:67], v[18:19], v[20:21]
	v_pk_add_f32 v[68:69], v[22:23], v[24:25]
	v_pk_add_f32 v[70:71], v[26:27], v[28:29]
	v_pk_add_f32 v[72:73], v[30:31], v[32:33]
	v_pk_add_f32 v[66:67], v[66:67], v[68:69]
	v_pk_add_f32 v[70:71], v[70:71], v[72:73]
	v_pk_add_f32 v[66:67], v[66:67], v[70:71]
	v_add_f32_e32 v66, v66, v67
	s_nop 1
	v_add_f32_dpp v66, v66, v66 row_shr:1 row_mask:0xf bank_mask:0xf bound_ctrl:1
	s_nop 1
	v_add_f32_dpp v66, v66, v66 row_shr:2 row_mask:0xf bank_mask:0xf bound_ctrl:1
	s_nop 1
	v_add_f32_dpp v66, v66, v66 row_shr:4 row_mask:0xf bank_mask:0xf bound_ctrl:1
	s_nop 1
	v_add_f32_dpp v66, v66, v66 row_shr:8 row_mask:0xf bank_mask:0xf bound_ctrl:1
	s_nop 0
	v_readlane_b32 s9, v66, 15
	v_readlane_b32 s10, v66, 31
	v_readlane_b32 s11, v66, 47
	v_readlane_b32 vcc_lo, v66, 63
	s_nop 1
	v_mov_b32_e32 v66, s9
	v_add_f32_e32 v66, s10, v66
	v_add_f32_e32 v66, s11, v66
	v_add_f32_e32 v66, vcc_lo, v66
	v_mul_f32_e32 v116, 0x3a800000, v66
	v_mov_b32_e32 v117, v116
	v_pk_add_f32 v[18:19], v[18:19], v[116:117] neg_lo:[0,1] neg_hi:[0,1]
	v_pk_add_f32 v[20:21], v[20:21], v[116:117] neg_lo:[0,1] neg_hi:[0,1]
	v_pk_add_f32 v[22:23], v[22:23], v[116:117] neg_lo:[0,1] neg_hi:[0,1]
	v_pk_add_f32 v[24:25], v[24:25], v[116:117] neg_lo:[0,1] neg_hi:[0,1]
	v_pk_add_f32 v[26:27], v[26:27], v[116:117] neg_lo:[0,1] neg_hi:[0,1]
	v_pk_add_f32 v[28:29], v[28:29], v[116:117] neg_lo:[0,1] neg_hi:[0,1]
	v_pk_add_f32 v[30:31], v[30:31], v[116:117] neg_lo:[0,1] neg_hi:[0,1]
	v_pk_add_f32 v[32:33], v[32:33], v[116:117] neg_lo:[0,1] neg_hi:[0,1]
	v_pk_mul_f32 v[66:67], v[18:19], v[18:19]
	v_pk_mul_f32 v[68:69], v[20:21], v[20:21]
	v_pk_fma_f32 v[66:67], v[22:23], v[22:23], v[66:67]
	v_pk_fma_f32 v[68:69], v[24:25], v[24:25], v[68:69]
	v_pk_fma_f32 v[66:67], v[26:27], v[26:27], v[66:67]
	v_pk_fma_f32 v[68:69], v[28:29], v[28:29], v[68:69]
	v_pk_fma_f32 v[66:67], v[30:31], v[30:31], v[66:67]
	v_pk_fma_f32 v[68:69], v[32:33], v[32:33], v[68:69]
	v_pk_add_f32 v[66:67], v[66:67], v[68:69]
	v_add_f32_e32 v66, v66, v67
	s_nop 1
	v_add_f32_dpp v66, v66, v66 row_shr:1 row_mask:0xf bank_mask:0xf bound_ctrl:1
	s_nop 1
	v_add_f32_dpp v66, v66, v66 row_shr:2 row_mask:0xf bank_mask:0xf bound_ctrl:1
	s_nop 1
	v_add_f32_dpp v66, v66, v66 row_shr:4 row_mask:0xf bank_mask:0xf bound_ctrl:1
	s_nop 1
	v_add_f32_dpp v66, v66, v66 row_shr:8 row_mask:0xf bank_mask:0xf bound_ctrl:1
	s_nop 0
	v_readlane_b32 s9, v66, 15
	v_readlane_b32 s10, v66, 31
	v_readlane_b32 s11, v66, 47
	v_readlane_b32 vcc_lo, v66, 63
	s_nop 1
	v_mov_b32_e32 v66, s9
	v_add_f32_e32 v66, s10, v66
	v_add_f32_e32 v66, s11, v66
	v_add_f32_e32 v66, vcc_lo, v66
	v_mul_f32_e32 v66, 0x3a800000, v66
	v_add_f32_e32 v66, 0x3727c5ac, v66
	v_rsq_f32_e32 v118, v66
	s_nop 0
	v_mov_b32_e32 v119, v118
	v_pk_mul_f32 v[18:19], v[18:19], v[118:119]
	v_pk_mul_f32 v[20:21], v[20:21], v[118:119]
	v_pk_mul_f32 v[22:23], v[22:23], v[118:119]
	v_pk_mul_f32 v[24:25], v[24:25], v[118:119]
	v_pk_mul_f32 v[26:27], v[26:27], v[118:119]
	v_pk_mul_f32 v[28:29], v[28:29], v[118:119]
	v_pk_mul_f32 v[30:31], v[30:31], v[118:119]
	v_pk_mul_f32 v[32:33], v[32:33], v[118:119]
	v_pk_fma_f32 v[76:77], v[18:19], v[34:35], v[50:51]
	v_pk_fma_f32 v[78:79], v[20:21], v[36:37], v[52:53]
	v_pk_fma_f32 v[80:81], v[22:23], v[38:39], v[54:55]
	v_pk_fma_f32 v[82:83], v[24:25], v[40:41], v[56:57]
	v_pk_fma_f32 v[84:85], v[26:27], v[42:43], v[58:59]
	v_pk_fma_f32 v[86:87], v[28:29], v[44:45], v[60:61]
	v_pk_fma_f32 v[88:89], v[30:31], v[46:47], v[62:63]
	v_pk_fma_f32 v[90:91], v[32:33], v[48:49], v[64:65]
	v_cvt_pk_bf16_f32 v92, v76, v77
	v_cvt_pk_bf16_f32 v93, v78, v79
	v_cvt_pk_bf16_f32 v94, v80, v81
	v_cvt_pk_bf16_f32 v95, v82, v83
	v_cvt_pk_bf16_f32 v96, v84, v85
	v_cvt_pk_bf16_f32 v97, v86, v87
	v_cvt_pk_bf16_f32 v98, v88, v89
	v_cvt_pk_bf16_f32 v99, v90, v91
	global_store_dwordx2 v115, v[92:93], s[2:3] offset:0 sc1
	global_store_dwordx2 v115, v[94:95], s[2:3] offset:512 sc1
	global_store_dwordx2 v115, v[96:97], s[2:3] offset:1024 sc1
	global_store_dwordx2 v115, v[98:99], s[2:3] offset:1536 sc1
	s_add_u32 s2, s2, 0x400000
	s_addc_u32 s3, s3, 0
	s_add_u32 s0, s0, 0x800000
	s_addc_u32 s1, s1, 0
	global_load_dwordx4 v[18:21], v114, s[0:1] offset:0 nt
	global_load_dwordx4 v[22:25], v114, s[0:1] offset:1024 nt
	global_load_dwordx4 v[26:29], v114, s[0:1] offset:2048 nt
	global_load_dwordx4 v[30:33], v114, s[0:1] offset:3072 nt
	s_waitcnt vmcnt(8)
; __device__ __forceinline__ void phase_ln(float* R, const float* __restrict__ g, const float* __restrict__ b, bf16_t* xbf, float samp_scale, const float* __restrict__ part, int nsplit, bool f32_all) {
;     ...
;   for (int r = gw; r < MT; r += nw) {
;     float* row = R + (size_t)r * 1024;
;     f32x4 v[4];
; #pragma unroll
;     for (int i = 0; i < 4; ++i) v[i] = *(const f32x4*)(row + i * 256 + lane * 4);
;     if (r >= MP) {
;       for (int sp = 0; sp < nsplit; ++sp) {
;         const float* prow = part + ((size_t)sp * MS + (r - MP)) * 1024;
; #pragma unroll
;         for (int i = 0; i < 4; ++i) v[i] = v[i] + *(const f32x4*)(prow + i * 256 + lane * 4);
;       }
;     }
;     float s = 0.f;
; #pragma unroll
;     for (int i = 0; i < 4; ++i) s += v[i][0] + v[i][1] + v[i][2] + v[i][3];
; #pragma unroll
;     for (int o = 32; o >= 1; o >>= 1) s += __shfl_xor(s, o);
;     const float mean = s * (1.f / 1024.f);
;     float ss = 0.f;
; #pragma unroll
;     for (int i = 0; i < 4; ++i) { v[i] = v[i] - mean; ss += v[i][0] * v[i][0] + v[i][1] * v[i][1] + v[i][2] * v[i][2] + v[i][3] * v[i][3]; }
; #pragma unroll
;     for (int o = 32; o >= 1; o >>= 1) ss += __shfl_xor(ss, o);
;     const float rstd = rsqrtf(ss * (1.f / 1024.f) + LN_EPS);
; #pragma unroll
;     for (int i = 0; i < 4; ++i) {
;       const f32x4 y = v[i] * rstd * gv[i] + bv[i];
;       if (r >= MP) *(f32x4*)(row + i * 256 + lane * 4) = y * samp_scale;
;       else if (f32_all) *(f32x4*)(row + i * 256 + lane * 4) = y;
;       if (xbf) {
;         u32x2 wv;
;         wv[0] = cvt_pk_bf16(y[0], y[1]); wv[1] = cvt_pk_bf16(y[2], y[3]);
;         *(u32x2*)(xbf + (size_t)r * 1024 + i * 256 + lane * 4) = wv;
;       }
;     }
	v_pk_add_f32 v[66:67], v[0:1], v[2:3]
	v_pk_add_f32 v[68:69], v[4:5], v[6:7]
	v_pk_add_f32 v[70:71], v[8:9], v[10:11]
	v_pk_add_f32 v[72:73], v[12:13], v[14:15]
	v_pk_add_f32 v[66:67], v[66:67], v[68:69]
	v_pk_add_f32 v[70:71], v[70:71], v[72:73]
	v_pk_add_f32 v[66:67], v[66:67], v[70:71]
	v_add_f32_e32 v66, v66, v67
	s_nop 1
	v_add_f32_dpp v66, v66, v66 row_shr:1 row_mask:0xf bank_mask:0xf bound_ctrl:1
	s_nop 1
	v_add_f32_dpp v66, v66, v66 row_shr:2 row_mask:0xf bank_mask:0xf bound_ctrl:1
	s_nop 1
	v_add_f32_dpp v66, v66, v66 row_shr:4 row_mask:0xf bank_mask:0xf bound_ctrl:1
	s_nop 1
	v_add_f32_dpp v66, v66, v66 row_shr:8 row_mask:0xf bank_mask:0xf bound_ctrl:1
	s_nop 0
	v_readlane_b32 s9, v66, 15
	v_readlane_b32 s10, v66, 31
	v_readlane_b32 s11, v66, 47
	v_readlane_b32 vcc_lo, v66, 63
	s_nop 1
	v_mov_b32_e32 v66, s9
	v_add_f32_e32 v66, s10, v66
	v_add_f32_e32 v66, s11, v66
	v_add_f32_e32 v66, vcc_lo, v66
	v_mul_f32_e32 v116, 0x3a800000, v66
	v_mov_b32_e32 v117, v116
	v_pk_add_f32 v[0:1], v[0:1], v[116:117] neg_lo:[0,1] neg_hi:[0,1]
	v_pk_add_f32 v[2:3], v[2:3], v[116:117] neg_lo:[0,1] neg_hi:[0,1]
	v_pk_add_f32 v[4:5], v[4:5], v[116:117] neg_lo:[0,1] neg_hi:[0,1]
	v_pk_add_f32 v[6:7], v[6:7], v[116:117] neg_lo:[0,1] neg_hi:[0,1]
	v_pk_add_f32 v[8:9], v[8:9], v[116:117] neg_lo:[0,1] neg_hi:[0,1]
	v_pk_add_f32 v[10:11], v[10:11], v[116:117] neg_lo:[0,1] neg_hi:[0,1]
	v_pk_add_f32 v[12:13], v[12:13], v[116:117] neg_lo:[0,1] neg_hi:[0,1]
	v_pk_add_f32 v[14:15], v[14:15], v[116:117] neg_lo:[0,1] neg_hi:[0,1]
	v_pk_mul_f32 v[66:67], v[0:1], v[0:1]
	v_pk_mul_f32 v[68:69], v[2:3], v[2:3]
	v_pk_fma_f32 v[66:67], v[4:5], v[4:5], v[66:67]
	v_pk_fma_f32 v[68:69], v[6:7], v[6:7], v[68:69]
	v_pk_fma_f32 v[66:67], v[8:9], v[8:9], v[66:67]
	v_pk_fma_f32 v[68:69], v[10:11], v[10:11], v[68:69]
	v_pk_fma_f32 v[66:67], v[12:13], v[12:13], v[66:67]
	v_pk_fma_f32 v[68:69], v[14:15], v[14:15], v[68:69]
	v_pk_add_f32 v[66:67], v[66:67], v[68:69]
	v_add_f32_e32 v66, v66, v67
	s_nop 1
	v_add_f32_dpp v66, v66, v66 row_shr:1 row_mask:0xf bank_mask:0xf bound_ctrl:1
	s_nop 1
	v_add_f32_dpp v66, v66, v66 row_shr:2 row_mask:0xf bank_mask:0xf bound_ctrl:1
	s_nop 1
	v_add_f32_dpp v66, v66, v66 row_shr:4 row_mask:0xf bank_mask:0xf bound_ctrl:1
	s_nop 1
	v_add_f32_dpp v66, v66, v66 row_shr:8 row_mask:0xf bank_mask:0xf bound_ctrl:1
	s_nop 0
	v_readlane_b32 s9, v66, 15
	v_readlane_b32 s10, v66, 31
	v_readlane_b32 s11, v66, 47
	v_readlane_b32 vcc_lo, v66, 63
	s_nop 1
	v_mov_b32_e32 v66, s9
	v_add_f32_e32 v66, s10, v66
	v_add_f32_e32 v66, s11, v66
	v_add_f32_e32 v66, vcc_lo, v66
	v_mul_f32_e32 v66, 0x3a800000, v66
	v_add_f32_e32 v66, 0x3727c5ac, v66
	v_rsq_f32_e32 v118, v66
	s_nop 0
	v_mov_b32_e32 v119, v118
	v_pk_mul_f32 v[0:1], v[0:1], v[118:119]
	v_pk_mul_f32 v[2:3], v[2:3], v[118:119]
	v_pk_mul_f32 v[4:5], v[4:5], v[118:119]
	v_pk_mul_f32 v[6:7], v[6:7], v[118:119]
	v_pk_mul_f32 v[8:9], v[8:9], v[118:119]
	v_pk_mul_f32 v[10:11], v[10:11], v[118:119]
	v_pk_mul_f32 v[12:13], v[12:13], v[118:119]
	v_pk_mul_f32 v[14:15], v[14:15], v[118:119]
	v_pk_fma_f32 v[76:77], v[0:1], v[34:35], v[50:51]
	v_pk_fma_f32 v[78:79], v[2:3], v[36:37], v[52:53]
	v_pk_fma_f32 v[80:81], v[4:5], v[38:39], v[54:55]
	v_pk_fma_f32 v[82:83], v[6:7], v[40:41], v[56:57]
	v_pk_fma_f32 v[84:85], v[8:9], v[42:43], v[58:59]
	v_pk_fma_f32 v[86:87], v[10:11], v[44:45], v[60:61]
	v_pk_fma_f32 v[88:89], v[12:13], v[46:47], v[62:63]
	v_pk_fma_f32 v[90:91], v[14:15], v[48:49], v[64:65]
	v_cvt_pk_bf16_f32 v92, v76, v77
	v_cvt_pk_bf16_f32 v93, v78, v79
	v_cvt_pk_bf16_f32 v94, v80, v81
	v_cvt_pk_bf16_f32 v95, v82, v83
	v_cvt_pk_bf16_f32 v96, v84, v85
	v_cvt_pk_bf16_f32 v97, v86, v87
	v_cvt_pk_bf16_f32 v98, v88, v89
	v_cvt_pk_bf16_f32 v99, v90, v91
	global_store_dwordx2 v115, v[92:93], s[2:3] offset:0 sc1
	global_store_dwordx2 v115, v[94:95], s[2:3] offset:512 sc1
	global_store_dwordx2 v115, v[96:97], s[2:3] offset:1024 sc1
	global_store_dwordx2 v115, v[98:99], s[2:3] offset:1536 sc1
	s_add_u32 s2, s2, 0x400000
	s_addc_u32 s3, s3, 0
	s_add_u32 s0, s0, 0x800000
	s_addc_u32 s1, s1, 0
	global_load_dwordx4 v[0:3], v114, s[0:1] offset:0 nt
	global_load_dwordx4 v[4:7], v114, s[0:1] offset:1024 nt
	global_load_dwordx4 v[8:11], v114, s[0:1] offset:2048 nt
	global_load_dwordx4 v[12:15], v114, s[0:1] offset:3072 nt
	s_waitcnt vmcnt(8)
; __device__ __forceinline__ void phase_ln(float* R, const float* __restrict__ g, const float* __restrict__ b, bf16_t* xbf, float samp_scale, const float* __restrict__ part, int nsplit, bool f32_all) {
;     ...
;   for (int r = gw; r < MT; r += nw) {
;     float* row = R + (size_t)r * 1024;
;     f32x4 v[4];
; #pragma unroll
;     for (int i = 0; i < 4; ++i) v[i] = *(const f32x4*)(row + i * 256 + lane * 4);
;     if (r >= MP) {
;       for (int sp = 0; sp < nsplit; ++sp) {
;         const float* prow = part + ((size_t)sp * MS + (r - MP)) * 1024;
; #pragma unroll
;         for (int i = 0; i < 4; ++i) v[i] = v[i] + *(const f32x4*)(prow + i * 256 + lane * 4);
;       }
;     }
;     float s = 0.f;
; #pragma unroll
;     for (int i = 0; i < 4; ++i) s += v[i][0] + v[i][1] + v[i][2] + v[i][3];
; #pragma unroll
;     for (int o = 32; o >= 1; o >>= 1) s += __shfl_xor(s, o);
;     const float mean = s * (1.f / 1024.f);
;     float ss = 0.f;
; #pragma unroll
;     for (int i = 0; i < 4; ++i) { v[i] = v[i] - mean; ss += v[i][0] * v[i][0] + v[i][1] * v[i][1] + v[i][2] * v[i][2] + v[i][3] * v[i][3]; }
; #pragma unroll
;     for (int o = 32; o >= 1; o >>= 1) ss += __shfl_xor(ss, o);
;     const float rstd = rsqrtf(ss * (1.f / 1024.f) + LN_EPS);
; #pragma unroll
;     for (int i = 0; i < 4; ++i) {
;       const f32x4 y = v[i] * rstd * gv[i] + bv[i];
;       if (r >= MP) *(f32x4*)(row + i * 256 + lane * 4) = y * samp_scale;
;       else if (f32_all) *(f32x4*)(row + i * 256 + lane * 4) = y;
;       if (xbf) {
;         u32x2 wv;
;         wv[0] = cvt_pk_bf16(y[0], y[1]); wv[1] = cvt_pk_bf16(y[2], y[3]);
;         *(u32x2*)(xbf + (size_t)r * 1024 + i * 256 + lane * 4) = wv;
;       }
;     }
	v_pk_add_f32 v[66:67], v[18:19], v[20:21]
	v_pk_add_f32 v[68:69], v[22:23], v[24:25]
	v_pk_add_f32 v[70:71], v[26:27], v[28:29]
	v_pk_add_f32 v[72:73], v[30:31], v[32:33]
	v_pk_add_f32 v[66:67], v[66:67], v[68:69]
	v_pk_add_f32 v[70:71], v[70:71], v[72:73]
	v_pk_add_f32 v[66:67], v[66:67], v[70:71]
	v_add_f32_e32 v66, v66, v67
	s_nop 1
	v_add_f32_dpp v66, v66, v66 row_shr:1 row_mask:0xf bank_mask:0xf bound_ctrl:1
	s_nop 1
	v_add_f32_dpp v66, v66, v66 row_shr:2 row_mask:0xf bank_mask:0xf bound_ctrl:1
	s_nop 1
	v_add_f32_dpp v66, v66, v66 row_shr:4 row_mask:0xf bank_mask:0xf bound_ctrl:1
	s_nop 1
	v_add_f32_dpp v66, v66, v66 row_shr:8 row_mask:0xf bank_mask:0xf bound_ctrl:1
	s_nop 0
	v_readlane_b32 s9, v66, 15
	v_readlane_b32 s10, v66, 31
	v_readlane_b32 s11, v66, 47
	v_readlane_b32 vcc_lo, v66, 63
	s_nop 1
	v_mov_b32_e32 v66, s9
	v_add_f32_e32 v66, s10, v66
	v_add_f32_e32 v66, s11, v66
	v_add_f32_e32 v66, vcc_lo, v66
	v_mul_f32_e32 v116, 0x3a800000, v66
	v_mov_b32_e32 v117, v116
	v_pk_add_f32 v[18:19], v[18:19], v[116:117] neg_lo:[0,1] neg_hi:[0,1]
	v_pk_add_f32 v[20:21], v[20:21], v[116:117] neg_lo:[0,1] neg_hi:[0,1]
	v_pk_add_f32 v[22:23], v[22:23], v[116:117] neg_lo:[0,1] neg_hi:[0,1]
	v_pk_add_f32 v[24:25], v[24:25], v[116:117] neg_lo:[0,1] neg_hi:[0,1]
	v_pk_add_f32 v[26:27], v[26:27], v[116:117] neg_lo:[0,1] neg_hi:[0,1]
	v_pk_add_f32 v[28:29], v[28:29], v[116:117] neg_lo:[0,1] neg_hi:[0,1]
	v_pk_add_f32 v[30:31], v[30:31], v[116:117] neg_lo:[0,1] neg_hi:[0,1]
	v_pk_add_f32 v[32:33], v[32:33], v[116:117] neg_lo:[0,1] neg_hi:[0,1]
	v_pk_mul_f32 v[66:67], v[18:19], v[18:19]
	v_pk_mul_f32 v[68:69], v[20:21], v[20:21]
	v_pk_fma_f32 v[66:67], v[22:23], v[22:23], v[66:67]
	v_pk_fma_f32 v[68:69], v[24:25], v[24:25], v[68:69]
	v_pk_fma_f32 v[66:67], v[26:27], v[26:27], v[66:67]
	v_pk_fma_f32 v[68:69], v[28:29], v[28:29], v[68:69]
	v_pk_fma_f32 v[66:67], v[30:31], v[30:31], v[66:67]
	v_pk_fma_f32 v[68:69], v[32:33], v[32:33], v[68:69]
	v_pk_add_f32 v[66:67], v[66:67], v[68:69]
	v_add_f32_e32 v66, v66, v67
	s_nop 1
	v_add_f32_dpp v66, v66, v66 row_shr:1 row_mask:0xf bank_mask:0xf bound_ctrl:1
	s_nop 1
	v_add_f32_dpp v66, v66, v66 row_shr:2 row_mask:0xf bank_mask:0xf bound_ctrl:1
	s_nop 1
	v_add_f32_dpp v66, v66, v66 row_shr:4 row_mask:0xf bank_mask:0xf bound_ctrl:1
	s_nop 1
	v_add_f32_dpp v66, v66, v66 row_shr:8 row_mask:0xf bank_mask:0xf bound_ctrl:1
	s_nop 0
	v_readlane_b32 s9, v66, 15
	v_readlane_b32 s10, v66, 31
	v_readlane_b32 s11, v66, 47
	v_readlane_b32 vcc_lo, v66, 63
	s_nop 1
	v_mov_b32_e32 v66, s9
	v_add_f32_e32 v66, s10, v66
	v_add_f32_e32 v66, s11, v66
	v_add_f32_e32 v66, vcc_lo, v66
	v_mul_f32_e32 v66, 0x3a800000, v66
	v_add_f32_e32 v66, 0x3727c5ac, v66
	v_rsq_f32_e32 v118, v66
	s_nop 0
	v_mov_b32_e32 v119, v118
	v_pk_mul_f32 v[18:19], v[18:19], v[118:119]
	v_pk_mul_f32 v[20:21], v[20:21], v[118:119]
	v_pk_mul_f32 v[22:23], v[22:23], v[118:119]
	v_pk_mul_f32 v[24:25], v[24:25], v[118:119]
	v_pk_mul_f32 v[26:27], v[26:27], v[118:119]
	v_pk_mul_f32 v[28:29], v[28:29], v[118:119]
	v_pk_mul_f32 v[30:31], v[30:31], v[118:119]
	v_pk_mul_f32 v[32:33], v[32:33], v[118:119]
	v_pk_fma_f32 v[76:77], v[18:19], v[34:35], v[50:51]
	v_pk_fma_f32 v[78:79], v[20:21], v[36:37], v[52:53]
	v_pk_fma_f32 v[80:81], v[22:23], v[38:39], v[54:55]
	v_pk_fma_f32 v[82:83], v[24:25], v[40:41], v[56:57]
	v_pk_fma_f32 v[84:85], v[26:27], v[42:43], v[58:59]
	v_pk_fma_f32 v[86:87], v[28:29], v[44:45], v[60:61]
	v_pk_fma_f32 v[88:89], v[30:31], v[46:47], v[62:63]
	v_pk_fma_f32 v[90:91], v[32:33], v[48:49], v[64:65]
	v_cvt_pk_bf16_f32 v92, v76, v77
	v_cvt_pk_bf16_f32 v93, v78, v79
	v_cvt_pk_bf16_f32 v94, v80, v81
	v_cvt_pk_bf16_f32 v95, v82, v83
	v_cvt_pk_bf16_f32 v96, v84, v85
	v_cvt_pk_bf16_f32 v97, v86, v87
	v_cvt_pk_bf16_f32 v98, v88, v89
	v_cvt_pk_bf16_f32 v99, v90, v91
	global_store_dwordx2 v115, v[92:93], s[2:3] offset:0 sc1
	global_store_dwordx2 v115, v[94:95], s[2:3] offset:512 sc1
	global_store_dwordx2 v115, v[96:97], s[2:3] offset:1024 sc1
	global_store_dwordx2 v115, v[98:99], s[2:3] offset:1536 sc1
	s_add_u32 s2, s2, 0x400000
	s_addc_u32 s3, s3, 0
	s_add_u32 s0, s0, 0x800000
	s_addc_u32 s1, s1, 0
	global_load_dwordx4 v[18:21], v114, s[0:1] offset:0 nt
	global_load_dwordx4 v[22:25], v114, s[0:1] offset:1024 nt
	global_load_dwordx4 v[26:29], v114, s[0:1] offset:2048 nt
	global_load_dwordx4 v[30:33], v114, s[0:1] offset:3072 nt
	s_waitcnt vmcnt(8)
; __device__ __forceinline__ void phase_ln(float* R, const float* __restrict__ g, const float* __restrict__ b, bf16_t* xbf, float samp_scale, const float* __restrict__ part, int nsplit, bool f32_all) {
;     ...
;   for (int r = gw; r < MT; r += nw) {
;     float* row = R + (size_t)r * 1024;
;     f32x4 v[4];
; #pragma unroll
;     for (int i = 0; i < 4; ++i) v[i] = *(const f32x4*)(row + i * 256 + lane * 4);
;     if (r >= MP) {
;       for (int sp = 0; sp < nsplit; ++sp) {
;         const float* prow = part + ((size_t)sp * MS + (r - MP)) * 1024;
; #pragma unroll
;         for (int i = 0; i < 4; ++i) v[i] = v[i] + *(const f32x4*)(prow + i * 256 + lane * 4);
;       }
;     }
;     float s = 0.f;
; #pragma unroll
;     for (int i = 0; i < 4; ++i) s += v[i][0] + v[i][1] + v[i][2] + v[i][3];
; #pragma unroll
;     for (int o = 32; o >= 1; o >>= 1) s += __shfl_xor(s, o);
;     const float mean = s * (1.f / 1024.f);
;     float ss = 0.f;
; #pragma unroll
;     for (int i = 0; i < 4; ++i) { v[i] = v[i] - mean; ss += v[i][0] * v[i][0] + v[i][1] * v[i][1] + v[i][2] * v[i][2] + v[i][3] * v[i][3]; }
; #pragma unroll
;     for (int o = 32; o >= 1; o >>= 1) ss += __shfl_xor(ss, o);
;     const float rstd = rsqrtf(ss * (1.f / 1024.f) + LN_EPS);
; #pragma unroll
;     for (int i = 0; i < 4; ++i) {
;       const f32x4 y = v[i] * rstd * gv[i] + bv[i];
;       if (r >= MP) *(f32x4*)(row + i * 256 + lane * 4) = y * samp_scale;
;       else if (f32_all) *(f32x4*)(row + i * 256 + lane * 4) = y;
;       if (xbf) {
;         u32x2 wv;
;         wv[0] = cvt_pk_bf16(y[0], y[1]); wv[1] = cvt_pk_bf16(y[2], y[3]);
;         *(u32x2*)(xbf + (size_t)r * 1024 + i * 256 + lane * 4) = wv;
;       }
;     }
	v_pk_add_f32 v[66:67], v[0:1], v[2:3]
	v_pk_add_f32 v[68:69], v[4:5], v[6:7]
	v_pk_add_f32 v[70:71], v[8:9], v[10:11]
	v_pk_add_f32 v[72:73], v[12:13], v[14:15]
	v_pk_add_f32 v[66:67], v[66:67], v[68:69]
	v_pk_add_f32 v[70:71], v[70:71], v[72:73]
	v_pk_add_f32 v[66:67], v[66:67], v[70:71]
	v_add_f32_e32 v66, v66, v67
	s_nop 1
	v_add_f32_dpp v66, v66, v66 row_shr:1 row_mask:0xf bank_mask:0xf bound_ctrl:1
	s_nop 1
	v_add_f32_dpp v66, v66, v66 row_shr:2 row_mask:0xf bank_mask:0xf bound_ctrl:1
	s_nop 1
	v_add_f32_dpp v66, v66, v66 row_shr:4 row_mask:0xf bank_mask:0xf bound_ctrl:1
	s_nop 1
	v_add_f32_dpp v66, v66, v66 row_shr:8 row_mask:0xf bank_mask:0xf bound_ctrl:1
	s_nop 0
	v_readlane_b32 s9, v66, 15
	v_readlane_b32 s10, v66, 31
	v_readlane_b32 s11, v66, 47
	v_readlane_b32 vcc_lo, v66, 63
	s_nop 1
	v_mov_b32_e32 v66, s9
	v_add_f32_e32 v66, s10, v66
	v_add_f32_e32 v66, s11, v66
	v_add_f32_e32 v66, vcc_lo, v66
	v_mul_f32_e32 v116, 0x3a800000, v66
	v_mov_b32_e32 v117, v116
	v_pk_add_f32 v[0:1], v[0:1], v[116:117] neg_lo:[0,1] neg_hi:[0,1]
	v_pk_add_f32 v[2:3], v[2:3], v[116:117] neg_lo:[0,1] neg_hi:[0,1]
	v_pk_add_f32 v[4:5], v[4:5], v[116:117] neg_lo:[0,1] neg_hi:[0,1]
	v_pk_add_f32 v[6:7], v[6:7], v[116:117] neg_lo:[0,1] neg_hi:[0,1]
	v_pk_add_f32 v[8:9], v[8:9], v[116:117] neg_lo:[0,1] neg_hi:[0,1]
	v_pk_add_f32 v[10:11], v[10:11], v[116:117] neg_lo:[0,1] neg_hi:[0,1]
	v_pk_add_f32 v[12:13], v[12:13], v[116:117] neg_lo:[0,1] neg_hi:[0,1]
	v_pk_add_f32 v[14:15], v[14:15], v[116:117] neg_lo:[0,1] neg_hi:[0,1]
	v_pk_mul_f32 v[66:67], v[0:1], v[0:1]
	v_pk_mul_f32 v[68:69], v[2:3], v[2:3]
	v_pk_fma_f32 v[66:67], v[4:5], v[4:5], v[66:67]
	v_pk_fma_f32 v[68:69], v[6:7], v[6:7], v[68:69]
	v_pk_fma_f32 v[66:67], v[8:9], v[8:9], v[66:67]
	v_pk_fma_f32 v[68:69], v[10:11], v[10:11], v[68:69]
	v_pk_fma_f32 v[66:67], v[12:13], v[12:13], v[66:67]
	v_pk_fma_f32 v[68:69], v[14:15], v[14:15], v[68:69]
	v_pk_add_f32 v[66:67], v[66:67], v[68:69]
	v_add_f32_e32 v66, v66, v67
	s_nop 1
	v_add_f32_dpp v66, v66, v66 row_shr:1 row_mask:0xf bank_mask:0xf bound_ctrl:1
	s_nop 1
	v_add_f32_dpp v66, v66, v66 row_shr:2 row_mask:0xf bank_mask:0xf bound_ctrl:1
	s_nop 1
	v_add_f32_dpp v66, v66, v66 row_shr:4 row_mask:0xf bank_mask:0xf bound_ctrl:1
	s_nop 1
	v_add_f32_dpp v66, v66, v66 row_shr:8 row_mask:0xf bank_mask:0xf bound_ctrl:1
	s_nop 0
	v_readlane_b32 s9, v66, 15
	v_readlane_b32 s10, v66, 31
	v_readlane_b32 s11, v66, 47
	v_readlane_b32 vcc_lo, v66, 63
	s_nop 1
	v_mov_b32_e32 v66, s9
	v_add_f32_e32 v66, s10, v66
	v_add_f32_e32 v66, s11, v66
	v_add_f32_e32 v66, vcc_lo, v66
	v_mul_f32_e32 v66, 0x3a800000, v66
	v_add_f32_e32 v66, 0x3727c5ac, v66
	v_rsq_f32_e32 v118, v66
	s_nop 0
	v_mov_b32_e32 v119, v118
	v_pk_mul_f32 v[0:1], v[0:1], v[118:119]
	v_pk_mul_f32 v[2:3], v[2:3], v[118:119]
	v_pk_mul_f32 v[4:5], v[4:5], v[118:119]
	v_pk_mul_f32 v[6:7], v[6:7], v[118:119]
	v_pk_mul_f32 v[8:9], v[8:9], v[118:119]
	v_pk_mul_f32 v[10:11], v[10:11], v[118:119]
	v_pk_mul_f32 v[12:13], v[12:13], v[118:119]
	v_pk_mul_f32 v[14:15], v[14:15], v[118:119]
	v_pk_fma_f32 v[76:77], v[0:1], v[34:35], v[50:51]
	v_pk_fma_f32 v[78:79], v[2:3], v[36:37], v[52:53]
	v_pk_fma_f32 v[80:81], v[4:5], v[38:39], v[54:55]
	v_pk_fma_f32 v[82:83], v[6:7], v[40:41], v[56:57]
	v_pk_fma_f32 v[84:85], v[8:9], v[42:43], v[58:59]
	v_pk_fma_f32 v[86:87], v[10:11], v[44:45], v[60:61]
	v_pk_fma_f32 v[88:89], v[12:13], v[46:47], v[62:63]
	v_pk_fma_f32 v[90:91], v[14:15], v[48:49], v[64:65]
	v_cvt_pk_bf16_f32 v92, v76, v77
	v_cvt_pk_bf16_f32 v93, v78, v79
	v_cvt_pk_bf16_f32 v94, v80, v81
	v_cvt_pk_bf16_f32 v95, v82, v83
	v_cvt_pk_bf16_f32 v96, v84, v85
	v_cvt_pk_bf16_f32 v97, v86, v87
	v_cvt_pk_bf16_f32 v98, v88, v89
	v_cvt_pk_bf16_f32 v99, v90, v91
	global_store_dwordx2 v115, v[92:93], s[2:3] offset:0 sc1
	global_store_dwordx2 v115, v[94:95], s[2:3] offset:512 sc1
	global_store_dwordx2 v115, v[96:97], s[2:3] offset:1024 sc1
	global_store_dwordx2 v115, v[98:99], s[2:3] offset:1536 sc1
	s_add_u32 s2, s2, 0x400000
	s_addc_u32 s3, s3, 0
	s_add_u32 s0, s0, 0x800000
	s_addc_u32 s1, s1, 0
	global_load_dwordx4 v[0:3], v114, s[0:1] offset:0 nt
	global_load_dwordx4 v[4:7], v114, s[0:1] offset:1024 nt
	global_load_dwordx4 v[8:11], v114, s[0:1] offset:2048 nt
	global_load_dwordx4 v[12:15], v114, s[0:1] offset:3072 nt
	s_waitcnt vmcnt(8)
; __device__ __forceinline__ void phase_ln(float* R, const float* __restrict__ g, const float* __restrict__ b, bf16_t* xbf, float samp_scale, const float* __restrict__ part, int nsplit, bool f32_all) {
;     ...
;   for (int r = gw; r < MT; r += nw) {
;     float* row = R + (size_t)r * 1024;
;     f32x4 v[4];
; #pragma unroll
;     for (int i = 0; i < 4; ++i) v[i] = *(const f32x4*)(row + i * 256 + lane * 4);
;     if (r >= MP) {
;       for (int sp = 0; sp < nsplit; ++sp) {
;         const float* prow = part + ((size_t)sp * MS + (r - MP)) * 1024;
; #pragma unroll
;         for (int i = 0; i < 4; ++i) v[i] = v[i] + *(const f32x4*)(prow + i * 256 + lane * 4);
;       }
;     }
;     float s = 0.f;
; #pragma unroll
;     for (int i = 0; i < 4; ++i) s += v[i][0] + v[i][1] + v[i][2] + v[i][3];
; #pragma unroll
;     for (int o = 32; o >= 1; o >>= 1) s += __shfl_xor(s, o);
;     const float mean = s * (1.f / 1024.f);
;     float ss = 0.f;
; #pragma unroll
;     for (int i = 0; i < 4; ++i) { v[i] = v[i] - mean; ss += v[i][0] * v[i][0] + v[i][1] * v[i][1] + v[i][2] * v[i][2] + v[i][3] * v[i][3]; }
; #pragma unroll
;     for (int o = 32; o >= 1; o >>= 1) ss += __shfl_xor(ss, o);
;     const float rstd = rsqrtf(ss * (1.f / 1024.f) + LN_EPS);
; #pragma unroll
;     for (int i = 0; i < 4; ++i) {
;       const f32x4 y = v[i] * rstd * gv[i] + bv[i];
;       if (r >= MP) *(f32x4*)(row + i * 256 + lane * 4) = y * samp_scale;
;       else if (f32_all) *(f32x4*)(row + i * 256 + lane * 4) = y;
;       if (xbf) {
;         u32x2 wv;
;         wv[0] = cvt_pk_bf16(y[0], y[1]); wv[1] = cvt_pk_bf16(y[2], y[3]);
;         *(u32x2*)(xbf + (size_t)r * 1024 + i * 256 + lane * 4) = wv;
;       }
;     }
	v_pk_add_f32 v[66:67], v[18:19], v[20:21]
	v_pk_add_f32 v[68:69], v[22:23], v[24:25]
	v_pk_add_f32 v[70:71], v[26:27], v[28:29]
	v_pk_add_f32 v[72:73], v[30:31], v[32:33]
	v_pk_add_f32 v[66:67], v[66:67], v[68:69]
	v_pk_add_f32 v[70:71], v[70:71], v[72:73]
	v_pk_add_f32 v[66:67], v[66:67], v[70:71]
	v_add_f32_e32 v66, v66, v67
	s_nop 1
	v_add_f32_dpp v66, v66, v66 row_shr:1 row_mask:0xf bank_mask:0xf bound_ctrl:1
	s_nop 1
	v_add_f32_dpp v66, v66, v66 row_shr:2 row_mask:0xf bank_mask:0xf bound_ctrl:1
	s_nop 1
	v_add_f32_dpp v66, v66, v66 row_shr:4 row_mask:0xf bank_mask:0xf bound_ctrl:1
	s_nop 1
	v_add_f32_dpp v66, v66, v66 row_shr:8 row_mask:0xf bank_mask:0xf bound_ctrl:1
	s_nop 0
	v_readlane_b32 s9, v66, 15
	v_readlane_b32 s10, v66, 31
	v_readlane_b32 s11, v66, 47
	v_readlane_b32 vcc_lo, v66, 63
	s_nop 1
	v_mov_b32_e32 v66, s9
	v_add_f32_e32 v66, s10, v66
	v_add_f32_e32 v66, s11, v66
	v_add_f32_e32 v66, vcc_lo, v66
	v_mul_f32_e32 v116, 0x3a800000, v66
	v_mov_b32_e32 v117, v116
	v_pk_add_f32 v[18:19], v[18:19], v[116:117] neg_lo:[0,1] neg_hi:[0,1]
	v_pk_add_f32 v[20:21], v[20:21], v[116:117] neg_lo:[0,1] neg_hi:[0,1]
	v_pk_add_f32 v[22:23], v[22:23], v[116:117] neg_lo:[0,1] neg_hi:[0,1]
	v_pk_add_f32 v[24:25], v[24:25], v[116:117] neg_lo:[0,1] neg_hi:[0,1]
	v_pk_add_f32 v[26:27], v[26:27], v[116:117] neg_lo:[0,1] neg_hi:[0,1]
	v_pk_add_f32 v[28:29], v[28:29], v[116:117] neg_lo:[0,1] neg_hi:[0,1]
	v_pk_add_f32 v[30:31], v[30:31], v[116:117] neg_lo:[0,1] neg_hi:[0,1]
	v_pk_add_f32 v[32:33], v[32:33], v[116:117] neg_lo:[0,1] neg_hi:[0,1]
	v_pk_mul_f32 v[66:67], v[18:19], v[18:19]
	v_pk_mul_f32 v[68:69], v[20:21], v[20:21]
	v_pk_fma_f32 v[66:67], v[22:23], v[22:23], v[66:67]
	v_pk_fma_f32 v[68:69], v[24:25], v[24:25], v[68:69]
	v_pk_fma_f32 v[66:67], v[26:27], v[26:27], v[66:67]
	v_pk_fma_f32 v[68:69], v[28:29], v[28:29], v[68:69]
	v_pk_fma_f32 v[66:67], v[30:31], v[30:31], v[66:67]
	v_pk_fma_f32 v[68:69], v[32:33], v[32:33], v[68:69]
	v_pk_add_f32 v[66:67], v[66:67], v[68:69]
	v_add_f32_e32 v66, v66, v67
	s_nop 1
	v_add_f32_dpp v66, v66, v66 row_shr:1 row_mask:0xf bank_mask:0xf bound_ctrl:1
	s_nop 1
	v_add_f32_dpp v66, v66, v66 row_shr:2 row_mask:0xf bank_mask:0xf bound_ctrl:1
	s_nop 1
	v_add_f32_dpp v66, v66, v66 row_shr:4 row_mask:0xf bank_mask:0xf bound_ctrl:1
	s_nop 1
	v_add_f32_dpp v66, v66, v66 row_shr:8 row_mask:0xf bank_mask:0xf bound_ctrl:1
	s_nop 0
	v_readlane_b32 s9, v66, 15
	v_readlane_b32 s10, v66, 31
	v_readlane_b32 s11, v66, 47
	v_readlane_b32 vcc_lo, v66, 63
	s_nop 1
	v_mov_b32_e32 v66, s9
	v_add_f32_e32 v66, s10, v66
	v_add_f32_e32 v66, s11, v66
	v_add_f32_e32 v66, vcc_lo, v66
	v_mul_f32_e32 v66, 0x3a800000, v66
	v_add_f32_e32 v66, 0x3727c5ac, v66
	v_rsq_f32_e32 v118, v66
	s_nop 0
	v_mov_b32_e32 v119, v118
	v_pk_mul_f32 v[18:19], v[18:19], v[118:119]
	v_pk_mul_f32 v[20:21], v[20:21], v[118:119]
	v_pk_mul_f32 v[22:23], v[22:23], v[118:119]
	v_pk_mul_f32 v[24:25], v[24:25], v[118:119]
	v_pk_mul_f32 v[26:27], v[26:27], v[118:119]
	v_pk_mul_f32 v[28:29], v[28:29], v[118:119]
	v_pk_mul_f32 v[30:31], v[30:31], v[118:119]
	v_pk_mul_f32 v[32:33], v[32:33], v[118:119]
	v_pk_fma_f32 v[76:77], v[18:19], v[34:35], v[50:51]
	v_pk_fma_f32 v[78:79], v[20:21], v[36:37], v[52:53]
	v_pk_fma_f32 v[80:81], v[22:23], v[38:39], v[54:55]
	v_pk_fma_f32 v[82:83], v[24:25], v[40:41], v[56:57]
	v_pk_fma_f32 v[84:85], v[26:27], v[42:43], v[58:59]
	v_pk_fma_f32 v[86:87], v[28:29], v[44:45], v[60:61]
	v_pk_fma_f32 v[88:89], v[30:31], v[46:47], v[62:63]
	v_pk_fma_f32 v[90:91], v[32:33], v[48:49], v[64:65]
	v_cvt_pk_bf16_f32 v92, v76, v77
	v_cvt_pk_bf16_f32 v93, v78, v79
	v_cvt_pk_bf16_f32 v94, v80, v81
	v_cvt_pk_bf16_f32 v95, v82, v83
	v_cvt_pk_bf16_f32 v96, v84, v85
	v_cvt_pk_bf16_f32 v97, v86, v87
	v_cvt_pk_bf16_f32 v98, v88, v89
	v_cvt_pk_bf16_f32 v99, v90, v91
	global_store_dwordx2 v115, v[92:93], s[2:3] offset:0 sc1
	global_store_dwordx2 v115, v[94:95], s[2:3] offset:512 sc1
	global_store_dwordx2 v115, v[96:97], s[2:3] offset:1024 sc1
	global_store_dwordx2 v115, v[98:99], s[2:3] offset:1536 sc1
	s_add_u32 s2, s2, 0x400000
	s_addc_u32 s3, s3, 0
	s_add_u32 s0, s0, 0x800000
	s_addc_u32 s1, s1, 0
	global_load_dwordx4 v[18:21], v114, s[0:1] offset:0 nt
	global_load_dwordx4 v[22:25], v114, s[0:1] offset:1024 nt
	global_load_dwordx4 v[26:29], v114, s[0:1] offset:2048 nt
	global_load_dwordx4 v[30:33], v114, s[0:1] offset:3072 nt
	s_waitcnt vmcnt(8)
; __device__ __forceinline__ void phase_ln(float* R, const float* __restrict__ g, const float* __restrict__ b, bf16_t* xbf, float samp_scale, const float* __restrict__ part, int nsplit, bool f32_all) {
;     ...
;   for (int r = gw; r < MT; r += nw) {
;     float* row = R + (size_t)r * 1024;
;     f32x4 v[4];
; #pragma unroll
;     for (int i = 0; i < 4; ++i) v[i] = *(const f32x4*)(row + i * 256 + lane * 4);
;     if (r >= MP) {
;       for (int sp = 0; sp < nsplit; ++sp) {
;         const float* prow = part + ((size_t)sp * MS + (r - MP)) * 1024;
; #pragma unroll
;         for (int i = 0; i < 4; ++i) v[i] = v[i] + *(const f32x4*)(prow + i * 256 + lane * 4);
;       }
;     }
;     float s = 0.f;
; #pragma unroll
;     for (int i = 0; i < 4; ++i) s += v[i][0] + v[i][1] + v[i][2] + v[i][3];
; #pragma unroll
;     for (int o = 32; o >= 1; o >>= 1) s += __shfl_xor(s, o);
;     const float mean = s * (1.f / 1024.f);
;     float ss = 0.f;
; #pragma unroll
;     for (int i = 0; i < 4; ++i) { v[i] = v[i] - mean; ss += v[i][0] * v[i][0] + v[i][1] * v[i][1] + v[i][2] * v[i][2] + v[i][3] * v[i][3]; }
; #pragma unroll
;     for (int o = 32; o >= 1; o >>= 1) ss += __shfl_xor(ss, o);
;     const float rstd = rsqrtf(ss * (1.f / 1024.f) + LN_EPS);
; #pragma unroll
;     for (int i = 0; i < 4; ++i) {
;       const f32x4 y = v[i] * rstd * gv[i] + bv[i];
;       if (r >= MP) *(f32x4*)(row + i * 256 + lane * 4) = y * samp_scale;
;       else if (f32_all) *(f32x4*)(row + i * 256 + lane * 4) = y;
;       if (xbf) {
;         u32x2 wv;
;         wv[0] = cvt_pk_bf16(y[0], y[1]); wv[1] = cvt_pk_bf16(y[2], y[3]);
;         *(u32x2*)(xbf + (size_t)r * 1024 + i * 256 + lane * 4) = wv;
;       }
;     }
	v_pk_add_f32 v[66:67], v[0:1], v[2:3]
	v_pk_add_f32 v[68:69], v[4:5], v[6:7]
	v_pk_add_f32 v[70:71], v[8:9], v[10:11]
	v_pk_add_f32 v[72:73], v[12:13], v[14:15]
	v_pk_add_f32 v[66:67], v[66:67], v[68:69]
	v_pk_add_f32 v[70:71], v[70:71], v[72:73]
	v_pk_add_f32 v[66:67], v[66:67], v[70:71]
	v_add_f32_e32 v66, v66, v67
	s_nop 1
	v_add_f32_dpp v66, v66, v66 row_shr:1 row_mask:0xf bank_mask:0xf bound_ctrl:1
	s_nop 1
	v_add_f32_dpp v66, v66, v66 row_shr:2 row_mask:0xf bank_mask:0xf bound_ctrl:1
	s_nop 1
	v_add_f32_dpp v66, v66, v66 row_shr:4 row_mask:0xf bank_mask:0xf bound_ctrl:1
	s_nop 1
	v_add_f32_dpp v66, v66, v66 row_shr:8 row_mask:0xf bank_mask:0xf bound_ctrl:1
	s_nop 0
	v_readlane_b32 s9, v66, 15
	v_readlane_b32 s10, v66, 31
	v_readlane_b32 s11, v66, 47
	v_readlane_b32 vcc_lo, v66, 63
	s_nop 1
	v_mov_b32_e32 v66, s9
	v_add_f32_e32 v66, s10, v66
	v_add_f32_e32 v66, s11, v66
	v_add_f32_e32 v66, vcc_lo, v66
	v_mul_f32_e32 v116, 0x3a800000, v66
	v_mov_b32_e32 v117, v116
	v_pk_add_f32 v[0:1], v[0:1], v[116:117] neg_lo:[0,1] neg_hi:[0,1]
	v_pk_add_f32 v[2:3], v[2:3], v[116:117] neg_lo:[0,1] neg_hi:[0,1]
	v_pk_add_f32 v[4:5], v[4:5], v[116:117] neg_lo:[0,1] neg_hi:[0,1]
	v_pk_add_f32 v[6:7], v[6:7], v[116:117] neg_lo:[0,1] neg_hi:[0,1]
	v_pk_add_f32 v[8:9], v[8:9], v[116:117] neg_lo:[0,1] neg_hi:[0,1]
	v_pk_add_f32 v[10:11], v[10:11], v[116:117] neg_lo:[0,1] neg_hi:[0,1]
	v_pk_add_f32 v[12:13], v[12:13], v[116:117] neg_lo:[0,1] neg_hi:[0,1]
	v_pk_add_f32 v[14:15], v[14:15], v[116:117] neg_lo:[0,1] neg_hi:[0,1]
	v_pk_mul_f32 v[66:67], v[0:1], v[0:1]
	v_pk_mul_f32 v[68:69], v[2:3], v[2:3]
	v_pk_fma_f32 v[66:67], v[4:5], v[4:5], v[66:67]
	v_pk_fma_f32 v[68:69], v[6:7], v[6:7], v[68:69]
	v_pk_fma_f32 v[66:67], v[8:9], v[8:9], v[66:67]
	v_pk_fma_f32 v[68:69], v[10:11], v[10:11], v[68:69]
	v_pk_fma_f32 v[66:67], v[12:13], v[12:13], v[66:67]
	v_pk_fma_f32 v[68:69], v[14:15], v[14:15], v[68:69]
	v_pk_add_f32 v[66:67], v[66:67], v[68:69]
	v_add_f32_e32 v66, v66, v67
	s_nop 1
	v_add_f32_dpp v66, v66, v66 row_shr:1 row_mask:0xf bank_mask:0xf bound_ctrl:1
	s_nop 1
	v_add_f32_dpp v66, v66, v66 row_shr:2 row_mask:0xf bank_mask:0xf bound_ctrl:1
	s_nop 1
	v_add_f32_dpp v66, v66, v66 row_shr:4 row_mask:0xf bank_mask:0xf bound_ctrl:1
	s_nop 1
	v_add_f32_dpp v66, v66, v66 row_shr:8 row_mask:0xf bank_mask:0xf bound_ctrl:1
	s_nop 0
	v_readlane_b32 s9, v66, 15
	v_readlane_b32 s10, v66, 31
	v_readlane_b32 s11, v66, 47
	v_readlane_b32 vcc_lo, v66, 63
	s_nop 1
	v_mov_b32_e32 v66, s9
	v_add_f32_e32 v66, s10, v66
	v_add_f32_e32 v66, s11, v66
	v_add_f32_e32 v66, vcc_lo, v66
	v_mul_f32_e32 v66, 0x3a800000, v66
	v_add_f32_e32 v66, 0x3727c5ac, v66
	v_rsq_f32_e32 v118, v66
	s_nop 0
	v_mov_b32_e32 v119, v118
	v_pk_mul_f32 v[0:1], v[0:1], v[118:119]
	v_pk_mul_f32 v[2:3], v[2:3], v[118:119]
	v_pk_mul_f32 v[4:5], v[4:5], v[118:119]
	v_pk_mul_f32 v[6:7], v[6:7], v[118:119]
	v_pk_mul_f32 v[8:9], v[8:9], v[118:119]
	v_pk_mul_f32 v[10:11], v[10:11], v[118:119]
	v_pk_mul_f32 v[12:13], v[12:13], v[118:119]
	v_pk_mul_f32 v[14:15], v[14:15], v[118:119]
	v_pk_fma_f32 v[76:77], v[0:1], v[34:35], v[50:51]
	v_pk_fma_f32 v[78:79], v[2:3], v[36:37], v[52:53]
	v_pk_fma_f32 v[80:81], v[4:5], v[38:39], v[54:55]
	v_pk_fma_f32 v[82:83], v[6:7], v[40:41], v[56:57]
	v_pk_fma_f32 v[84:85], v[8:9], v[42:43], v[58:59]
	v_pk_fma_f32 v[86:87], v[10:11], v[44:45], v[60:61]
	v_pk_fma_f32 v[88:89], v[12:13], v[46:47], v[62:63]
	v_pk_fma_f32 v[90:91], v[14:15], v[48:49], v[64:65]
	v_cvt_pk_bf16_f32 v92, v76, v77
	v_cvt_pk_bf16_f32 v93, v78, v79
	v_cvt_pk_bf16_f32 v94, v80, v81
	v_cvt_pk_bf16_f32 v95, v82, v83
	v_cvt_pk_bf16_f32 v96, v84, v85
	v_cvt_pk_bf16_f32 v97, v86, v87
	v_cvt_pk_bf16_f32 v98, v88, v89
	v_cvt_pk_bf16_f32 v99, v90, v91
	global_store_dwordx2 v115, v[92:93], s[2:3] offset:0 sc1
	global_store_dwordx2 v115, v[94:95], s[2:3] offset:512 sc1
	global_store_dwordx2 v115, v[96:97], s[2:3] offset:1024 sc1
	global_store_dwordx2 v115, v[98:99], s[2:3] offset:1536 sc1
	s_add_u32 s2, s2, 0x400000
	s_addc_u32 s3, s3, 0
	s_add_u32 s0, s0, 0x800000
	s_addc_u32 s1, s1, 0
	global_load_dwordx4 v[0:3], v114, s[0:1] offset:0 nt
	global_load_dwordx4 v[4:7], v114, s[0:1] offset:1024 nt
	global_load_dwordx4 v[8:11], v114, s[0:1] offset:2048 nt
	global_load_dwordx4 v[12:15], v114, s[0:1] offset:3072 nt
	s_waitcnt vmcnt(8)
; __device__ __forceinline__ void phase_ln(float* R, const float* __restrict__ g, const float* __restrict__ b, bf16_t* xbf, float samp_scale, const float* __restrict__ part, int nsplit, bool f32_all) {
;     ...
;   for (int r = gw; r < MT; r += nw) {
;     float* row = R + (size_t)r * 1024;
;     f32x4 v[4];
; #pragma unroll
;     for (int i = 0; i < 4; ++i) v[i] = *(const f32x4*)(row + i * 256 + lane * 4);
;     if (r >= MP) {
;       for (int sp = 0; sp < nsplit; ++sp) {
;         const float* prow = part + ((size_t)sp * MS + (r - MP)) * 1024;
; #pragma unroll
;         for (int i = 0; i < 4; ++i) v[i] = v[i] + *(const f32x4*)(prow + i * 256 + lane * 4);
;       }
;     }
;     float s = 0.f;
; #pragma unroll
;     for (int i = 0; i < 4; ++i) s += v[i][0] + v[i][1] + v[i][2] + v[i][3];
; #pragma unroll
;     for (int o = 32; o >= 1; o >>= 1) s += __shfl_xor(s, o);
;     const float mean = s * (1.f / 1024.f);
;     float ss = 0.f;
; #pragma unroll
;     for (int i = 0; i < 4; ++i) { v[i] = v[i] - mean; ss += v[i][0] * v[i][0] + v[i][1] * v[i][1] + v[i][2] * v[i][2] + v[i][3] * v[i][3]; }
; #pragma unroll
;     for (int o = 32; o >= 1; o >>= 1) ss += __shfl_xor(ss, o);
;     const float rstd = rsqrtf(ss * (1.f / 1024.f) + LN_EPS);
; #pragma unroll
;     for (int i = 0; i < 4; ++i) {
;       const f32x4 y = v[i] * rstd * gv[i] + bv[i];
;       if (r >= MP) *(f32x4*)(row + i * 256 + lane * 4) = y * samp_scale;
;       else if (f32_all) *(f32x4*)(row + i * 256 + lane * 4) = y;
;       if (xbf) {
;         u32x2 wv;
;         wv[0] = cvt_pk_bf16(y[0], y[1]); wv[1] = cvt_pk_bf16(y[2], y[3]);
;         *(u32x2*)(xbf + (size_t)r * 1024 + i * 256 + lane * 4) = wv;
;       }
;     }
	v_pk_add_f32 v[66:67], v[18:19], v[20:21]
	v_pk_add_f32 v[68:69], v[22:23], v[24:25]
	v_pk_add_f32 v[70:71], v[26:27], v[28:29]
	v_pk_add_f32 v[72:73], v[30:31], v[32:33]
	v_pk_add_f32 v[66:67], v[66:67], v[68:69]
	v_pk_add_f32 v[70:71], v[70:71], v[72:73]
	v_pk_add_f32 v[66:67], v[66:67], v[70:71]
	v_add_f32_e32 v66, v66, v67
	s_nop 1
	v_add_f32_dpp v66, v66, v66 row_shr:1 row_mask:0xf bank_mask:0xf bound_ctrl:1
	s_nop 1
	v_add_f32_dpp v66, v66, v66 row_shr:2 row_mask:0xf bank_mask:0xf bound_ctrl:1
	s_nop 1
	v_add_f32_dpp v66, v66, v66 row_shr:4 row_mask:0xf bank_mask:0xf bound_ctrl:1
	s_nop 1
	v_add_f32_dpp v66, v66, v66 row_shr:8 row_mask:0xf bank_mask:0xf bound_ctrl:1
	s_nop 0
	v_readlane_b32 s9, v66, 15
	v_readlane_b32 s10, v66, 31
	v_readlane_b32 s11, v66, 47
	v_readlane_b32 vcc_lo, v66, 63
	s_nop 1
	v_mov_b32_e32 v66, s9
	v_add_f32_e32 v66, s10, v66
	v_add_f32_e32 v66, s11, v66
	v_add_f32_e32 v66, vcc_lo, v66
	v_mul_f32_e32 v116, 0x3a800000, v66
	v_mov_b32_e32 v117, v116
	v_pk_add_f32 v[18:19], v[18:19], v[116:117] neg_lo:[0,1] neg_hi:[0,1]
	v_pk_add_f32 v[20:21], v[20:21], v[116:117] neg_lo:[0,1] neg_hi:[0,1]
	v_pk_add_f32 v[22:23], v[22:23], v[116:117] neg_lo:[0,1] neg_hi:[0,1]
	v_pk_add_f32 v[24:25], v[24:25], v[116:117] neg_lo:[0,1] neg_hi:[0,1]
	v_pk_add_f32 v[26:27], v[26:27], v[116:117] neg_lo:[0,1] neg_hi:[0,1]
	v_pk_add_f32 v[28:29], v[28:29], v[116:117] neg_lo:[0,1] neg_hi:[0,1]
	v_pk_add_f32 v[30:31], v[30:31], v[116:117] neg_lo:[0,1] neg_hi:[0,1]
	v_pk_add_f32 v[32:33], v[32:33], v[116:117] neg_lo:[0,1] neg_hi:[0,1]
	v_pk_mul_f32 v[66:67], v[18:19], v[18:19]
	v_pk_mul_f32 v[68:69], v[20:21], v[20:21]
	v_pk_fma_f32 v[66:67], v[22:23], v[22:23], v[66:67]
	v_pk_fma_f32 v[68:69], v[24:25], v[24:25], v[68:69]
	v_pk_fma_f32 v[66:67], v[26:27], v[26:27], v[66:67]
	v_pk_fma_f32 v[68:69], v[28:29], v[28:29], v[68:69]
	v_pk_fma_f32 v[66:67], v[30:31], v[30:31], v[66:67]
	v_pk_fma_f32 v[68:69], v[32:33], v[32:33], v[68:69]
	v_pk_add_f32 v[66:67], v[66:67], v[68:69]
	v_add_f32_e32 v66, v66, v67
	s_nop 1
	v_add_f32_dpp v66, v66, v66 row_shr:1 row_mask:0xf bank_mask:0xf bound_ctrl:1
	s_nop 1
	v_add_f32_dpp v66, v66, v66 row_shr:2 row_mask:0xf bank_mask:0xf bound_ctrl:1
	s_nop 1
	v_add_f32_dpp v66, v66, v66 row_shr:4 row_mask:0xf bank_mask:0xf bound_ctrl:1
	s_nop 1
	v_add_f32_dpp v66, v66, v66 row_shr:8 row_mask:0xf bank_mask:0xf bound_ctrl:1
	s_nop 0
	v_readlane_b32 s9, v66, 15
	v_readlane_b32 s10, v66, 31
	v_readlane_b32 s11, v66, 47
	v_readlane_b32 vcc_lo, v66, 63
	s_nop 1
	v_mov_b32_e32 v66, s9
	v_add_f32_e32 v66, s10, v66
	v_add_f32_e32 v66, s11, v66
	v_add_f32_e32 v66, vcc_lo, v66
	v_mul_f32_e32 v66, 0x3a800000, v66
	v_add_f32_e32 v66, 0x3727c5ac, v66
	v_rsq_f32_e32 v118, v66
	s_nop 0
	v_mov_b32_e32 v119, v118
	v_pk_mul_f32 v[18:19], v[18:19], v[118:119]
	v_pk_mul_f32 v[20:21], v[20:21], v[118:119]
	v_pk_mul_f32 v[22:23], v[22:23], v[118:119]
	v_pk_mul_f32 v[24:25], v[24:25], v[118:119]
	v_pk_mul_f32 v[26:27], v[26:27], v[118:119]
	v_pk_mul_f32 v[28:29], v[28:29], v[118:119]
	v_pk_mul_f32 v[30:31], v[30:31], v[118:119]
	v_pk_mul_f32 v[32:33], v[32:33], v[118:119]
	v_pk_fma_f32 v[76:77], v[18:19], v[34:35], v[50:51]
	v_pk_fma_f32 v[78:79], v[20:21], v[36:37], v[52:53]
	v_pk_fma_f32 v[80:81], v[22:23], v[38:39], v[54:55]
	v_pk_fma_f32 v[82:83], v[24:25], v[40:41], v[56:57]
	v_pk_fma_f32 v[84:85], v[26:27], v[42:43], v[58:59]
	v_pk_fma_f32 v[86:87], v[28:29], v[44:45], v[60:61]
	v_pk_fma_f32 v[88:89], v[30:31], v[46:47], v[62:63]
	v_pk_fma_f32 v[90:91], v[32:33], v[48:49], v[64:65]
	v_cvt_pk_bf16_f32 v92, v76, v77
	v_cvt_pk_bf16_f32 v93, v78, v79
	v_cvt_pk_bf16_f32 v94, v80, v81
	v_cvt_pk_bf16_f32 v95, v82, v83
	v_cvt_pk_bf16_f32 v96, v84, v85
	v_cvt_pk_bf16_f32 v97, v86, v87
	v_cvt_pk_bf16_f32 v98, v88, v89
	v_cvt_pk_bf16_f32 v99, v90, v91
	global_store_dwordx2 v115, v[92:93], s[2:3] offset:0 sc1
	global_store_dwordx2 v115, v[94:95], s[2:3] offset:512 sc1
	global_store_dwordx2 v115, v[96:97], s[2:3] offset:1024 sc1
	global_store_dwordx2 v115, v[98:99], s[2:3] offset:1536 sc1
	s_add_u32 s2, s2, 0x400000
	s_addc_u32 s3, s3, 0
	s_add_u32 s0, s0, 0x800000
	s_addc_u32 s1, s1, 0
	global_load_dwordx4 v[18:21], v114, s[0:1] offset:0 nt
	global_load_dwordx4 v[22:25], v114, s[0:1] offset:1024 nt
	global_load_dwordx4 v[26:29], v114, s[0:1] offset:2048 nt
	global_load_dwordx4 v[30:33], v114, s[0:1] offset:3072 nt
	s_waitcnt vmcnt(8)
; __device__ __forceinline__ void phase_ln(float* R, const float* __restrict__ g, const float* __restrict__ b, bf16_t* xbf, float samp_scale, const float* __restrict__ part, int nsplit, bool f32_all) {
;     ...
;   for (int r = gw; r < MT; r += nw) {
;     float* row = R + (size_t)r * 1024;
;     f32x4 v[4];
; #pragma unroll
;     for (int i = 0; i < 4; ++i) v[i] = *(const f32x4*)(row + i * 256 + lane * 4);
;     if (r >= MP) {
;       for (int sp = 0; sp < nsplit; ++sp) {
;         const float* prow = part + ((size_t)sp * MS + (r - MP)) * 1024;
; #pragma unroll
;         for (int i = 0; i < 4; ++i) v[i] = v[i] + *(const f32x4*)(prow + i * 256 + lane * 4);
;       }
;     }
;     float s = 0.f;
; #pragma unroll
;     for (int i = 0; i < 4; ++i) s += v[i][0] + v[i][1] + v[i][2] + v[i][3];
; #pragma unroll
;     for (int o = 32; o >= 1; o >>= 1) s += __shfl_xor(s, o);
;     const float mean = s * (1.f / 1024.f);
;     float ss = 0.f;
; #pragma unroll
;     for (int i = 0; i < 4; ++i) { v[i] = v[i] - mean; ss += v[i][0] * v[i][0] + v[i][1] * v[i][1] + v[i][2] * v[i][2] + v[i][3] * v[i][3]; }
; #pragma unroll
;     for (int o = 32; o >= 1; o >>= 1) ss += __shfl_xor(ss, o);
;     const float rstd = rsqrtf(ss * (1.f / 1024.f) + LN_EPS);
; #pragma unroll
;     for (int i = 0; i < 4; ++i) {
;       const f32x4 y = v[i] * rstd * gv[i] + bv[i];
;       if (r >= MP) *(f32x4*)(row + i * 256 + lane * 4) = y * samp_scale;
;       else if (f32_all) *(f32x4*)(row + i * 256 + lane * 4) = y;
;       if (xbf) {
;         u32x2 wv;
;         wv[0] = cvt_pk_bf16(y[0], y[1]); wv[1] = cvt_pk_bf16(y[2], y[3]);
;         *(u32x2*)(xbf + (size_t)r * 1024 + i * 256 + lane * 4) = wv;
;       }
;     }
	v_pk_add_f32 v[66:67], v[0:1], v[2:3]
	v_pk_add_f32 v[68:69], v[4:5], v[6:7]
	v_pk_add_f32 v[70:71], v[8:9], v[10:11]
	v_pk_add_f32 v[72:73], v[12:13], v[14:15]
	v_pk_add_f32 v[66:67], v[66:67], v[68:69]
	v_pk_add_f32 v[70:71], v[70:71], v[72:73]
	v_pk_add_f32 v[66:67], v[66:67], v[70:71]
	v_add_f32_e32 v66, v66, v67
	s_nop 1
	v_add_f32_dpp v66, v66, v66 row_shr:1 row_mask:0xf bank_mask:0xf bound_ctrl:1
	s_nop 1
	v_add_f32_dpp v66, v66, v66 row_shr:2 row_mask:0xf bank_mask:0xf bound_ctrl:1
	s_nop 1
	v_add_f32_dpp v66, v66, v66 row_shr:4 row_mask:0xf bank_mask:0xf bound_ctrl:1
	s_nop 1
	v_add_f32_dpp v66, v66, v66 row_shr:8 row_mask:0xf bank_mask:0xf bound_ctrl:1
	s_nop 0
	v_readlane_b32 s9, v66, 15
	v_readlane_b32 s10, v66, 31
	v_readlane_b32 s11, v66, 47
	v_readlane_b32 vcc_lo, v66, 63
	s_nop 1
	v_mov_b32_e32 v66, s9
	v_add_f32_e32 v66, s10, v66
	v_add_f32_e32 v66, s11, v66
	v_add_f32_e32 v66, vcc_lo, v66
	v_mul_f32_e32 v116, 0x3a800000, v66
	v_mov_b32_e32 v117, v116
	v_pk_add_f32 v[0:1], v[0:1], v[116:117] neg_lo:[0,1] neg_hi:[0,1]
	v_pk_add_f32 v[2:3], v[2:3], v[116:117] neg_lo:[0,1] neg_hi:[0,1]
	v_pk_add_f32 v[4:5], v[4:5], v[116:117] neg_lo:[0,1] neg_hi:[0,1]
	v_pk_add_f32 v[6:7], v[6:7], v[116:117] neg_lo:[0,1] neg_hi:[0,1]
	v_pk_add_f32 v[8:9], v[8:9], v[116:117] neg_lo:[0,1] neg_hi:[0,1]
	v_pk_add_f32 v[10:11], v[10:11], v[116:117] neg_lo:[0,1] neg_hi:[0,1]
	v_pk_add_f32 v[12:13], v[12:13], v[116:117] neg_lo:[0,1] neg_hi:[0,1]
	v_pk_add_f32 v[14:15], v[14:15], v[116:117] neg_lo:[0,1] neg_hi:[0,1]
	v_pk_mul_f32 v[66:67], v[0:1], v[0:1]
	v_pk_mul_f32 v[68:69], v[2:3], v[2:3]
	v_pk_fma_f32 v[66:67], v[4:5], v[4:5], v[66:67]
	v_pk_fma_f32 v[68:69], v[6:7], v[6:7], v[68:69]
	v_pk_fma_f32 v[66:67], v[8:9], v[8:9], v[66:67]
	v_pk_fma_f32 v[68:69], v[10:11], v[10:11], v[68:69]
	v_pk_fma_f32 v[66:67], v[12:13], v[12:13], v[66:67]
	v_pk_fma_f32 v[68:69], v[14:15], v[14:15], v[68:69]
	v_pk_add_f32 v[66:67], v[66:67], v[68:69]
	v_add_f32_e32 v66, v66, v67
	s_nop 1
	v_add_f32_dpp v66, v66, v66 row_shr:1 row_mask:0xf bank_mask:0xf bound_ctrl:1
	s_nop 1
	v_add_f32_dpp v66, v66, v66 row_shr:2 row_mask:0xf bank_mask:0xf bound_ctrl:1
	s_nop 1
	v_add_f32_dpp v66, v66, v66 row_shr:4 row_mask:0xf bank_mask:0xf bound_ctrl:1
	s_nop 1
	v_add_f32_dpp v66, v66, v66 row_shr:8 row_mask:0xf bank_mask:0xf bound_ctrl:1
	s_nop 0
	v_readlane_b32 s9, v66, 15
	v_readlane_b32 s10, v66, 31
	v_readlane_b32 s11, v66, 47
	v_readlane_b32 vcc_lo, v66, 63
	s_nop 1
	v_mov_b32_e32 v66, s9
	v_add_f32_e32 v66, s10, v66
	v_add_f32_e32 v66, s11, v66
	v_add_f32_e32 v66, vcc_lo, v66
	v_mul_f32_e32 v66, 0x3a800000, v66
	v_add_f32_e32 v66, 0x3727c5ac, v66
	v_rsq_f32_e32 v118, v66
	s_nop 0
	v_mov_b32_e32 v119, v118
	v_pk_mul_f32 v[0:1], v[0:1], v[118:119]
	v_pk_mul_f32 v[2:3], v[2:3], v[118:119]
	v_pk_mul_f32 v[4:5], v[4:5], v[118:119]
	v_pk_mul_f32 v[6:7], v[6:7], v[118:119]
	v_pk_mul_f32 v[8:9], v[8:9], v[118:119]
	v_pk_mul_f32 v[10:11], v[10:11], v[118:119]
	v_pk_mul_f32 v[12:13], v[12:13], v[118:119]
	v_pk_mul_f32 v[14:15], v[14:15], v[118:119]
	v_pk_fma_f32 v[76:77], v[0:1], v[34:35], v[50:51]
	v_pk_fma_f32 v[78:79], v[2:3], v[36:37], v[52:53]
	v_pk_fma_f32 v[80:81], v[4:5], v[38:39], v[54:55]
	v_pk_fma_f32 v[82:83], v[6:7], v[40:41], v[56:57]
	v_pk_fma_f32 v[84:85], v[8:9], v[42:43], v[58:59]
	v_pk_fma_f32 v[86:87], v[10:11], v[44:45], v[60:61]
	v_pk_fma_f32 v[88:89], v[12:13], v[46:47], v[62:63]
	v_pk_fma_f32 v[90:91], v[14:15], v[48:49], v[64:65]
	v_cvt_pk_bf16_f32 v92, v76, v77
	v_cvt_pk_bf16_f32 v93, v78, v79
	v_cvt_pk_bf16_f32 v94, v80, v81
	v_cvt_pk_bf16_f32 v95, v82, v83
	v_cvt_pk_bf16_f32 v96, v84, v85
	v_cvt_pk_bf16_f32 v97, v86, v87
	v_cvt_pk_bf16_f32 v98, v88, v89
	v_cvt_pk_bf16_f32 v99, v90, v91
	global_store_dwordx2 v115, v[92:93], s[2:3] offset:0 sc1
	global_store_dwordx2 v115, v[94:95], s[2:3] offset:512 sc1
	global_store_dwordx2 v115, v[96:97], s[2:3] offset:1024 sc1
	global_store_dwordx2 v115, v[98:99], s[2:3] offset:1536 sc1
	s_add_u32 s2, s2, 0x400000
	s_addc_u32 s3, s3, 0
	s_add_u32 s0, s0, 0x800000
	s_addc_u32 s1, s1, 0
	global_load_dwordx4 v[0:3], v114, s[0:1] offset:0 nt
	global_load_dwordx4 v[4:7], v114, s[0:1] offset:1024 nt
	global_load_dwordx4 v[8:11], v114, s[0:1] offset:2048 nt
	global_load_dwordx4 v[12:15], v114, s[0:1] offset:3072 nt
	s_waitcnt vmcnt(8)
; __device__ __forceinline__ void phase_ln(float* R, const float* __restrict__ g, const float* __restrict__ b, bf16_t* xbf, float samp_scale, const float* __restrict__ part, int nsplit, bool f32_all) {
;     ...
;   for (int r = gw; r < MT; r += nw) {
;     float* row = R + (size_t)r * 1024;
;     f32x4 v[4];
; #pragma unroll
;     for (int i = 0; i < 4; ++i) v[i] = *(const f32x4*)(row + i * 256 + lane * 4);
;     if (r >= MP) {
;       for (int sp = 0; sp < nsplit; ++sp) {
;         const float* prow = part + ((size_t)sp * MS + (r - MP)) * 1024;
; #pragma unroll
;         for (int i = 0; i < 4; ++i) v[i] = v[i] + *(const f32x4*)(prow + i * 256 + lane * 4);
;       }
;     }
;     float s = 0.f;
; #pragma unroll
;     for (int i = 0; i < 4; ++i) s += v[i][0] + v[i][1] + v[i][2] + v[i][3];
; #pragma unroll
;     for (int o = 32; o >= 1; o >>= 1) s += __shfl_xor(s, o);
;     const float mean = s * (1.f / 1024.f);
;     float ss = 0.f;
; #pragma unroll
;     for (int i = 0; i < 4; ++i) { v[i] = v[i] - mean; ss += v[i][0] * v[i][0] + v[i][1] * v[i][1] + v[i][2] * v[i][2] + v[i][3] * v[i][3]; }
; #pragma unroll
;     for (int o = 32; o >= 1; o >>= 1) ss += __shfl_xor(ss, o);
;     const float rstd = rsqrtf(ss * (1.f / 1024.f) + LN_EPS);
; #pragma unroll
;     for (int i = 0; i < 4; ++i) {
;       const f32x4 y = v[i] * rstd * gv[i] + bv[i];
;       if (r >= MP) *(f32x4*)(row + i * 256 + lane * 4) = y * samp_scale;
;       else if (f32_all) *(f32x4*)(row + i * 256 + lane * 4) = y;
;       if (xbf) {
;         u32x2 wv;
;         wv[0] = cvt_pk_bf16(y[0], y[1]); wv[1] = cvt_pk_bf16(y[2], y[3]);
;         *(u32x2*)(xbf + (size_t)r * 1024 + i * 256 + lane * 4) = wv;
;       }
;     }
	v_pk_add_f32 v[66:67], v[18:19], v[20:21]
	v_pk_add_f32 v[68:69], v[22:23], v[24:25]
	v_pk_add_f32 v[70:71], v[26:27], v[28:29]
	v_pk_add_f32 v[72:73], v[30:31], v[32:33]
	v_pk_add_f32 v[66:67], v[66:67], v[68:69]
	v_pk_add_f32 v[70:71], v[70:71], v[72:73]
	v_pk_add_f32 v[66:67], v[66:67], v[70:71]
	v_add_f32_e32 v66, v66, v67
	s_nop 1
	v_add_f32_dpp v66, v66, v66 row_shr:1 row_mask:0xf bank_mask:0xf bound_ctrl:1
	s_nop 1
	v_add_f32_dpp v66, v66, v66 row_shr:2 row_mask:0xf bank_mask:0xf bound_ctrl:1
	s_nop 1
	v_add_f32_dpp v66, v66, v66 row_shr:4 row_mask:0xf bank_mask:0xf bound_ctrl:1
	s_nop 1
	v_add_f32_dpp v66, v66, v66 row_shr:8 row_mask:0xf bank_mask:0xf bound_ctrl:1
	s_nop 0
	v_readlane_b32 s9, v66, 15
	v_readlane_b32 s10, v66, 31
	v_readlane_b32 s11, v66, 47
	v_readlane_b32 vcc_lo, v66, 63
	s_nop 1
	v_mov_b32_e32 v66, s9
	v_add_f32_e32 v66, s10, v66
	v_add_f32_e32 v66, s11, v66
	v_add_f32_e32 v66, vcc_lo, v66
	v_mul_f32_e32 v116, 0x3a800000, v66
	v_mov_b32_e32 v117, v116
	v_pk_add_f32 v[18:19], v[18:19], v[116:117] neg_lo:[0,1] neg_hi:[0,1]
	v_pk_add_f32 v[20:21], v[20:21], v[116:117] neg_lo:[0,1] neg_hi:[0,1]
	v_pk_add_f32 v[22:23], v[22:23], v[116:117] neg_lo:[0,1] neg_hi:[0,1]
	v_pk_add_f32 v[24:25], v[24:25], v[116:117] neg_lo:[0,1] neg_hi:[0,1]
	v_pk_add_f32 v[26:27], v[26:27], v[116:117] neg_lo:[0,1] neg_hi:[0,1]
	v_pk_add_f32 v[28:29], v[28:29], v[116:117] neg_lo:[0,1] neg_hi:[0,1]
	v_pk_add_f32 v[30:31], v[30:31], v[116:117] neg_lo:[0,1] neg_hi:[0,1]
	v_pk_add_f32 v[32:33], v[32:33], v[116:117] neg_lo:[0,1] neg_hi:[0,1]
	v_pk_mul_f32 v[66:67], v[18:19], v[18:19]
	v_pk_mul_f32 v[68:69], v[20:21], v[20:21]
	v_pk_fma_f32 v[66:67], v[22:23], v[22:23], v[66:67]
	v_pk_fma_f32 v[68:69], v[24:25], v[24:25], v[68:69]
	v_pk_fma_f32 v[66:67], v[26:27], v[26:27], v[66:67]
	v_pk_fma_f32 v[68:69], v[28:29], v[28:29], v[68:69]
	v_pk_fma_f32 v[66:67], v[30:31], v[30:31], v[66:67]
	v_pk_fma_f32 v[68:69], v[32:33], v[32:33], v[68:69]
	v_pk_add_f32 v[66:67], v[66:67], v[68:69]
	v_add_f32_e32 v66, v66, v67
	s_nop 1
	v_add_f32_dpp v66, v66, v66 row_shr:1 row_mask:0xf bank_mask:0xf bound_ctrl:1
	s_nop 1
	v_add_f32_dpp v66, v66, v66 row_shr:2 row_mask:0xf bank_mask:0xf bound_ctrl:1
	s_nop 1
	v_add_f32_dpp v66, v66, v66 row_shr:4 row_mask:0xf bank_mask:0xf bound_ctrl:1
	s_nop 1
	v_add_f32_dpp v66, v66, v66 row_shr:8 row_mask:0xf bank_mask:0xf bound_ctrl:1
	s_nop 0
	v_readlane_b32 s9, v66, 15
	v_readlane_b32 s10, v66, 31
	v_readlane_b32 s11, v66, 47
	v_readlane_b32 vcc_lo, v66, 63
	s_nop 1
	v_mov_b32_e32 v66, s9
	v_add_f32_e32 v66, s10, v66
	v_add_f32_e32 v66, s11, v66
	v_add_f32_e32 v66, vcc_lo, v66
	v_mul_f32_e32 v66, 0x3a800000, v66
	v_add_f32_e32 v66, 0x3727c5ac, v66
	v_rsq_f32_e32 v118, v66
	s_nop 0
	v_mov_b32_e32 v119, v118
	v_pk_mul_f32 v[18:19], v[18:19], v[118:119]
	v_pk_mul_f32 v[20:21], v[20:21], v[118:119]
	v_pk_mul_f32 v[22:23], v[22:23], v[118:119]
	v_pk_mul_f32 v[24:25], v[24:25], v[118:119]
	v_pk_mul_f32 v[26:27], v[26:27], v[118:119]
	v_pk_mul_f32 v[28:29], v[28:29], v[118:119]
	v_pk_mul_f32 v[30:31], v[30:31], v[118:119]
	v_pk_mul_f32 v[32:33], v[32:33], v[118:119]
	v_pk_fma_f32 v[76:77], v[18:19], v[34:35], v[50:51]
	v_pk_fma_f32 v[78:79], v[20:21], v[36:37], v[52:53]
	v_pk_fma_f32 v[80:81], v[22:23], v[38:39], v[54:55]
	v_pk_fma_f32 v[82:83], v[24:25], v[40:41], v[56:57]
	v_pk_fma_f32 v[84:85], v[26:27], v[42:43], v[58:59]
	v_pk_fma_f32 v[86:87], v[28:29], v[44:45], v[60:61]
	v_pk_fma_f32 v[88:89], v[30:31], v[46:47], v[62:63]
	v_pk_fma_f32 v[90:91], v[32:33], v[48:49], v[64:65]
	v_cvt_pk_bf16_f32 v92, v76, v77
	v_cvt_pk_bf16_f32 v93, v78, v79
	v_cvt_pk_bf16_f32 v94, v80, v81
	v_cvt_pk_bf16_f32 v95, v82, v83
	v_cvt_pk_bf16_f32 v96, v84, v85
	v_cvt_pk_bf16_f32 v97, v86, v87
	v_cvt_pk_bf16_f32 v98, v88, v89
	v_cvt_pk_bf16_f32 v99, v90, v91
	global_store_dwordx2 v115, v[92:93], s[2:3] offset:0 sc1
	global_store_dwordx2 v115, v[94:95], s[2:3] offset:512 sc1
	global_store_dwordx2 v115, v[96:97], s[2:3] offset:1024 sc1
	global_store_dwordx2 v115, v[98:99], s[2:3] offset:1536 sc1
	s_add_u32 s2, s2, 0x400000
	s_addc_u32 s3, s3, 0
	s_add_u32 s0, s0, 0x800000
	s_addc_u32 s1, s1, 0
	global_load_dwordx4 v[18:21], v114, s[0:1] offset:0 nt
	global_load_dwordx4 v[22:25], v114, s[0:1] offset:1024 nt
	global_load_dwordx4 v[26:29], v114, s[0:1] offset:2048 nt
	global_load_dwordx4 v[30:33], v114, s[0:1] offset:3072 nt
	s_waitcnt vmcnt(8)
; __device__ __forceinline__ void phase_ln(float* R, const float* __restrict__ g, const float* __restrict__ b, bf16_t* xbf, float samp_scale, const float* __restrict__ part, int nsplit, bool f32_all) {
;     ...
;   for (int r = gw; r < MT; r += nw) {
;     float* row = R + (size_t)r * 1024;
;     f32x4 v[4];
; #pragma unroll
;     for (int i = 0; i < 4; ++i) v[i] = *(const f32x4*)(row + i * 256 + lane * 4);
;     if (r >= MP) {
;       for (int sp = 0; sp < nsplit; ++sp) {
;         const float* prow = part + ((size_t)sp * MS + (r - MP)) * 1024;
; #pragma unroll
;         for (int i = 0; i < 4; ++i) v[i] = v[i] + *(const f32x4*)(prow + i * 256 + lane * 4);
;       }
;     }
;     float s = 0.f;
; #pragma unroll
;     for (int i = 0; i < 4; ++i) s += v[i][0] + v[i][1] + v[i][2] + v[i][3];
; #pragma unroll
;     for (int o = 32; o >= 1; o >>= 1) s += __shfl_xor(s, o);
;     const float mean = s * (1.f / 1024.f);
;     float ss = 0.f;
; #pragma unroll
;     for (int i = 0; i < 4; ++i) { v[i] = v[i] - mean; ss += v[i][0] * v[i][0] + v[i][1] * v[i][1] + v[i][2] * v[i][2] + v[i][3] * v[i][3]; }
; #pragma unroll
;     for (int o = 32; o >= 1; o >>= 1) ss += __shfl_xor(ss, o);
;     const float rstd = rsqrtf(ss * (1.f / 1024.f) + LN_EPS);
; #pragma unroll
;     for (int i = 0; i < 4; ++i) {
;       const f32x4 y = v[i] * rstd * gv[i] + bv[i];
;       if (r >= MP) *(f32x4*)(row + i * 256 + lane * 4) = y * samp_scale;
;       else if (f32_all) *(f32x4*)(row + i * 256 + lane * 4) = y;
;       if (xbf) {
;         u32x2 wv;
;         wv[0] = cvt_pk_bf16(y[0], y[1]); wv[1] = cvt_pk_bf16(y[2], y[3]);
;         *(u32x2*)(xbf + (size_t)r * 1024 + i * 256 + lane * 4) = wv;
;       }
;     }
	v_pk_add_f32 v[66:67], v[0:1], v[2:3]
	v_pk_add_f32 v[68:69], v[4:5], v[6:7]
	v_pk_add_f32 v[70:71], v[8:9], v[10:11]
	v_pk_add_f32 v[72:73], v[12:13], v[14:15]
	v_pk_add_f32 v[66:67], v[66:67], v[68:69]
	v_pk_add_f32 v[70:71], v[70:71], v[72:73]
	v_pk_add_f32 v[66:67], v[66:67], v[70:71]
	v_add_f32_e32 v66, v66, v67
	s_nop 1
	v_add_f32_dpp v66, v66, v66 row_shr:1 row_mask:0xf bank_mask:0xf bound_ctrl:1
	s_nop 1
	v_add_f32_dpp v66, v66, v66 row_shr:2 row_mask:0xf bank_mask:0xf bound_ctrl:1
	s_nop 1
	v_add_f32_dpp v66, v66, v66 row_shr:4 row_mask:0xf bank_mask:0xf bound_ctrl:1
	s_nop 1
	v_add_f32_dpp v66, v66, v66 row_shr:8 row_mask:0xf bank_mask:0xf bound_ctrl:1
	s_nop 0
	v_readlane_b32 s9, v66, 15
	v_readlane_b32 s10, v66, 31
	v_readlane_b32 s11, v66, 47
	v_readlane_b32 vcc_lo, v66, 63
	s_nop 1
	v_mov_b32_e32 v66, s9
	v_add_f32_e32 v66, s10, v66
	v_add_f32_e32 v66, s11, v66
	v_add_f32_e32 v66, vcc_lo, v66
	v_mul_f32_e32 v116, 0x3a800000, v66
	v_mov_b32_e32 v117, v116
	v_pk_add_f32 v[0:1], v[0:1], v[116:117] neg_lo:[0,1] neg_hi:[0,1]
	v_pk_add_f32 v[2:3], v[2:3], v[116:117] neg_lo:[0,1] neg_hi:[0,1]
	v_pk_add_f32 v[4:5], v[4:5], v[116:117] neg_lo:[0,1] neg_hi:[0,1]
	v_pk_add_f32 v[6:7], v[6:7], v[116:117] neg_lo:[0,1] neg_hi:[0,1]
	v_pk_add_f32 v[8:9], v[8:9], v[116:117] neg_lo:[0,1] neg_hi:[0,1]
	v_pk_add_f32 v[10:11], v[10:11], v[116:117] neg_lo:[0,1] neg_hi:[0,1]
	v_pk_add_f32 v[12:13], v[12:13], v[116:117] neg_lo:[0,1] neg_hi:[0,1]
	v_pk_add_f32 v[14:15], v[14:15], v[116:117] neg_lo:[0,1] neg_hi:[0,1]
	v_pk_mul_f32 v[66:67], v[0:1], v[0:1]
	v_pk_mul_f32 v[68:69], v[2:3], v[2:3]
	v_pk_fma_f32 v[66:67], v[4:5], v[4:5], v[66:67]
	v_pk_fma_f32 v[68:69], v[6:7], v[6:7], v[68:69]
	v_pk_fma_f32 v[66:67], v[8:9], v[8:9], v[66:67]
	v_pk_fma_f32 v[68:69], v[10:11], v[10:11], v[68:69]
	v_pk_fma_f32 v[66:67], v[12:13], v[12:13], v[66:67]
	v_pk_fma_f32 v[68:69], v[14:15], v[14:15], v[68:69]
	v_pk_add_f32 v[66:67], v[66:67], v[68:69]
	v_add_f32_e32 v66, v66, v67
	s_nop 1
	v_add_f32_dpp v66, v66, v66 row_shr:1 row_mask:0xf bank_mask:0xf bound_ctrl:1
	s_nop 1
	v_add_f32_dpp v66, v66, v66 row_shr:2 row_mask:0xf bank_mask:0xf bound_ctrl:1
	s_nop 1
	v_add_f32_dpp v66, v66, v66 row_shr:4 row_mask:0xf bank_mask:0xf bound_ctrl:1
	s_nop 1
	v_add_f32_dpp v66, v66, v66 row_shr:8 row_mask:0xf bank_mask:0xf bound_ctrl:1
	s_nop 0
	v_readlane_b32 s9, v66, 15
	v_readlane_b32 s10, v66, 31
	v_readlane_b32 s11, v66, 47
	v_readlane_b32 vcc_lo, v66, 63
	s_nop 1
	v_mov_b32_e32 v66, s9
	v_add_f32_e32 v66, s10, v66
	v_add_f32_e32 v66, s11, v66
	v_add_f32_e32 v66, vcc_lo, v66
	v_mul_f32_e32 v66, 0x3a800000, v66
	v_add_f32_e32 v66, 0x3727c5ac, v66
	v_rsq_f32_e32 v118, v66
	s_nop 0
	v_mov_b32_e32 v119, v118
	v_pk_mul_f32 v[0:1], v[0:1], v[118:119]
	v_pk_mul_f32 v[2:3], v[2:3], v[118:119]
	v_pk_mul_f32 v[4:5], v[4:5], v[118:119]
	v_pk_mul_f32 v[6:7], v[6:7], v[118:119]
	v_pk_mul_f32 v[8:9], v[8:9], v[118:119]
	v_pk_mul_f32 v[10:11], v[10:11], v[118:119]
	v_pk_mul_f32 v[12:13], v[12:13], v[118:119]
	v_pk_mul_f32 v[14:15], v[14:15], v[118:119]
	v_pk_fma_f32 v[76:77], v[0:1], v[34:35], v[50:51]
	v_pk_fma_f32 v[78:79], v[2:3], v[36:37], v[52:53]
	v_pk_fma_f32 v[80:81], v[4:5], v[38:39], v[54:55]
	v_pk_fma_f32 v[82:83], v[6:7], v[40:41], v[56:57]
	v_pk_fma_f32 v[84:85], v[8:9], v[42:43], v[58:59]
	v_pk_fma_f32 v[86:87], v[10:11], v[44:45], v[60:61]
	v_pk_fma_f32 v[88:89], v[12:13], v[46:47], v[62:63]
	v_pk_fma_f32 v[90:91], v[14:15], v[48:49], v[64:65]
	v_cvt_pk_bf16_f32 v92, v76, v77
	v_cvt_pk_bf16_f32 v93, v78, v79
	v_cvt_pk_bf16_f32 v94, v80, v81
	v_cvt_pk_bf16_f32 v95, v82, v83
	v_cvt_pk_bf16_f32 v96, v84, v85
	v_cvt_pk_bf16_f32 v97, v86, v87
	v_cvt_pk_bf16_f32 v98, v88, v89
	v_cvt_pk_bf16_f32 v99, v90, v91
	global_store_dwordx2 v115, v[92:93], s[2:3] offset:0 sc1
	global_store_dwordx2 v115, v[94:95], s[2:3] offset:512 sc1
	global_store_dwordx2 v115, v[96:97], s[2:3] offset:1024 sc1
	global_store_dwordx2 v115, v[98:99], s[2:3] offset:1536 sc1
	s_add_u32 s2, s2, 0x400000
	s_addc_u32 s3, s3, 0
	s_add_u32 s0, s0, 0x800000
	s_addc_u32 s1, s1, 0
	global_load_dwordx4 v[0:3], v114, s[0:1] offset:0 nt
	global_load_dwordx4 v[4:7], v114, s[0:1] offset:1024 nt
	global_load_dwordx4 v[8:11], v114, s[0:1] offset:2048 nt
	global_load_dwordx4 v[12:15], v114, s[0:1] offset:3072 nt
	s_waitcnt vmcnt(8)
; __device__ __forceinline__ void phase_ln(float* R, const float* __restrict__ g, const float* __restrict__ b, bf16_t* xbf, float samp_scale, const float* __restrict__ part, int nsplit, bool f32_all) {
;     ...
;   for (int r = gw; r < MT; r += nw) {
;     float* row = R + (size_t)r * 1024;
;     f32x4 v[4];
; #pragma unroll
;     for (int i = 0; i < 4; ++i) v[i] = *(const f32x4*)(row + i * 256 + lane * 4);
;     if (r >= MP) {
;       for (int sp = 0; sp < nsplit; ++sp) {
;         const float* prow = part + ((size_t)sp * MS + (r - MP)) * 1024;
; #pragma unroll
;         for (int i = 0; i < 4; ++i) v[i] = v[i] + *(const f32x4*)(prow + i * 256 + lane * 4);
;       }
;     }
;     float s = 0.f;
; #pragma unroll
;     for (int i = 0; i < 4; ++i) s += v[i][0] + v[i][1] + v[i][2] + v[i][3];
; #pragma unroll
;     for (int o = 32; o >= 1; o >>= 1) s += __shfl_xor(s, o);
;     const float mean = s * (1.f / 1024.f);
;     float ss = 0.f;
; #pragma unroll
;     for (int i = 0; i < 4; ++i) { v[i] = v[i] - mean; ss += v[i][0] * v[i][0] + v[i][1] * v[i][1] + v[i][2] * v[i][2] + v[i][3] * v[i][3]; }
; #pragma unroll
;     for (int o = 32; o >= 1; o >>= 1) ss += __shfl_xor(ss, o);
;     const float rstd = rsqrtf(ss * (1.f / 1024.f) + LN_EPS);
; #pragma unroll
;     for (int i = 0; i < 4; ++i) {
;       const f32x4 y = v[i] * rstd * gv[i] + bv[i];
;       if (r >= MP) *(f32x4*)(row + i * 256 + lane * 4) = y * samp_scale;
;       else if (f32_all) *(f32x4*)(row + i * 256 + lane * 4) = y;
;       if (xbf) {
;         u32x2 wv;
;         wv[0] = cvt_pk_bf16(y[0], y[1]); wv[1] = cvt_pk_bf16(y[2], y[3]);
;         *(u32x2*)(xbf + (size_t)r * 1024 + i * 256 + lane * 4) = wv;
;       }
;     }
	v_pk_add_f32 v[66:67], v[18:19], v[20:21]
	v_pk_add_f32 v[68:69], v[22:23], v[24:25]
	v_pk_add_f32 v[70:71], v[26:27], v[28:29]
	v_pk_add_f32 v[72:73], v[30:31], v[32:33]
	v_pk_add_f32 v[66:67], v[66:67], v[68:69]
	v_pk_add_f32 v[70:71], v[70:71], v[72:73]
	v_pk_add_f32 v[66:67], v[66:67], v[70:71]
	v_add_f32_e32 v66, v66, v67
	s_nop 1
	v_add_f32_dpp v66, v66, v66 row_shr:1 row_mask:0xf bank_mask:0xf bound_ctrl:1
	s_nop 1
	v_add_f32_dpp v66, v66, v66 row_shr:2 row_mask:0xf bank_mask:0xf bound_ctrl:1
	s_nop 1
	v_add_f32_dpp v66, v66, v66 row_shr:4 row_mask:0xf bank_mask:0xf bound_ctrl:1
	s_nop 1
	v_add_f32_dpp v66, v66, v66 row_shr:8 row_mask:0xf bank_mask:0xf bound_ctrl:1
	s_nop 0
	v_readlane_b32 s9, v66, 15
	v_readlane_b32 s10, v66, 31
	v_readlane_b32 s11, v66, 47
	v_readlane_b32 vcc_lo, v66, 63
	s_nop 1
	v_mov_b32_e32 v66, s9
	v_add_f32_e32 v66, s10, v66
	v_add_f32_e32 v66, s11, v66
	v_add_f32_e32 v66, vcc_lo, v66
	v_mul_f32_e32 v116, 0x3a800000, v66
	v_mov_b32_e32 v117, v116
	v_pk_add_f32 v[18:19], v[18:19], v[116:117] neg_lo:[0,1] neg_hi:[0,1]
	v_pk_add_f32 v[20:21], v[20:21], v[116:117] neg_lo:[0,1] neg_hi:[0,1]
	v_pk_add_f32 v[22:23], v[22:23], v[116:117] neg_lo:[0,1] neg_hi:[0,1]
	v_pk_add_f32 v[24:25], v[24:25], v[116:117] neg_lo:[0,1] neg_hi:[0,1]
	v_pk_add_f32 v[26:27], v[26:27], v[116:117] neg_lo:[0,1] neg_hi:[0,1]
	v_pk_add_f32 v[28:29], v[28:29], v[116:117] neg_lo:[0,1] neg_hi:[0,1]
	v_pk_add_f32 v[30:31], v[30:31], v[116:117] neg_lo:[0,1] neg_hi:[0,1]
	v_pk_add_f32 v[32:33], v[32:33], v[116:117] neg_lo:[0,1] neg_hi:[0,1]
	v_pk_mul_f32 v[66:67], v[18:19], v[18:19]
	v_pk_mul_f32 v[68:69], v[20:21], v[20:21]
	v_pk_fma_f32 v[66:67], v[22:23], v[22:23], v[66:67]
	v_pk_fma_f32 v[68:69], v[24:25], v[24:25], v[68:69]
	v_pk_fma_f32 v[66:67], v[26:27], v[26:27], v[66:67]
	v_pk_fma_f32 v[68:69], v[28:29], v[28:29], v[68:69]
	v_pk_fma_f32 v[66:67], v[30:31], v[30:31], v[66:67]
	v_pk_fma_f32 v[68:69], v[32:33], v[32:33], v[68:69]
	v_pk_add_f32 v[66:67], v[66:67], v[68:69]
	v_add_f32_e32 v66, v66, v67
	s_nop 1
	v_add_f32_dpp v66, v66, v66 row_shr:1 row_mask:0xf bank_mask:0xf bound_ctrl:1
	s_nop 1
	v_add_f32_dpp v66, v66, v66 row_shr:2 row_mask:0xf bank_mask:0xf bound_ctrl:1
	s_nop 1
	v_add_f32_dpp v66, v66, v66 row_shr:4 row_mask:0xf bank_mask:0xf bound_ctrl:1
	s_nop 1
	v_add_f32_dpp v66, v66, v66 row_shr:8 row_mask:0xf bank_mask:0xf bound_ctrl:1
	s_nop 0
	v_readlane_b32 s9, v66, 15
	v_readlane_b32 s10, v66, 31
	v_readlane_b32 s11, v66, 47
	v_readlane_b32 vcc_lo, v66, 63
	s_nop 1
	v_mov_b32_e32 v66, s9
	v_add_f32_e32 v66, s10, v66
	v_add_f32_e32 v66, s11, v66
	v_add_f32_e32 v66, vcc_lo, v66
	v_mul_f32_e32 v66, 0x3a800000, v66
	v_add_f32_e32 v66, 0x3727c5ac, v66
	v_rsq_f32_e32 v118, v66
	s_nop 0
	v_mov_b32_e32 v119, v118
	v_pk_mul_f32 v[18:19], v[18:19], v[118:119]
	v_pk_mul_f32 v[20:21], v[20:21], v[118:119]
	v_pk_mul_f32 v[22:23], v[22:23], v[118:119]
	v_pk_mul_f32 v[24:25], v[24:25], v[118:119]
	v_pk_mul_f32 v[26:27], v[26:27], v[118:119]
	v_pk_mul_f32 v[28:29], v[28:29], v[118:119]
	v_pk_mul_f32 v[30:31], v[30:31], v[118:119]
	v_pk_mul_f32 v[32:33], v[32:33], v[118:119]
	v_pk_fma_f32 v[76:77], v[18:19], v[34:35], v[50:51]
	v_pk_fma_f32 v[78:79], v[20:21], v[36:37], v[52:53]
	v_pk_fma_f32 v[80:81], v[22:23], v[38:39], v[54:55]
	v_pk_fma_f32 v[82:83], v[24:25], v[40:41], v[56:57]
	v_pk_fma_f32 v[84:85], v[26:27], v[42:43], v[58:59]
	v_pk_fma_f32 v[86:87], v[28:29], v[44:45], v[60:61]
	v_pk_fma_f32 v[88:89], v[30:31], v[46:47], v[62:63]
	v_pk_fma_f32 v[90:91], v[32:33], v[48:49], v[64:65]
	v_cvt_pk_bf16_f32 v92, v76, v77
	v_cvt_pk_bf16_f32 v93, v78, v79
	v_cvt_pk_bf16_f32 v94, v80, v81
	v_cvt_pk_bf16_f32 v95, v82, v83
	v_cvt_pk_bf16_f32 v96, v84, v85
	v_cvt_pk_bf16_f32 v97, v86, v87
	v_cvt_pk_bf16_f32 v98, v88, v89
	v_cvt_pk_bf16_f32 v99, v90, v91
	global_store_dwordx2 v115, v[92:93], s[2:3] offset:0 sc1
	global_store_dwordx2 v115, v[94:95], s[2:3] offset:512 sc1
	global_store_dwordx2 v115, v[96:97], s[2:3] offset:1024 sc1
	global_store_dwordx2 v115, v[98:99], s[2:3] offset:1536 sc1
	s_add_u32 s2, s2, 0x400000
	s_addc_u32 s3, s3, 0
	s_add_u32 s0, s0, 0x800000
	s_addc_u32 s1, s1, 0
	global_load_dwordx4 v[18:21], v114, s[0:1] offset:0 nt
	global_load_dwordx4 v[22:25], v114, s[0:1] offset:1024 nt
	global_load_dwordx4 v[26:29], v114, s[0:1] offset:2048 nt
	global_load_dwordx4 v[30:33], v114, s[0:1] offset:3072 nt
	s_waitcnt vmcnt(8)
; __device__ __forceinline__ void phase_ln(float* R, const float* __restrict__ g, const float* __restrict__ b, bf16_t* xbf, float samp_scale, const float* __restrict__ part, int nsplit, bool f32_all) {
;     ...
;   for (int r = gw; r < MT; r += nw) {
;     float* row = R + (size_t)r * 1024;
;     f32x4 v[4];
; #pragma unroll
;     for (int i = 0; i < 4; ++i) v[i] = *(const f32x4*)(row + i * 256 + lane * 4);
;     if (r >= MP) {
;       for (int sp = 0; sp < nsplit; ++sp) {
;         const float* prow = part + ((size_t)sp * MS + (r - MP)) * 1024;
; #pragma unroll
;         for (int i = 0; i < 4; ++i) v[i] = v[i] + *(const f32x4*)(prow + i * 256 + lane * 4);
;       }
;     }
;     float s = 0.f;
; #pragma unroll
;     for (int i = 0; i < 4; ++i) s += v[i][0] + v[i][1] + v[i][2] + v[i][3];
; #pragma unroll
;     for (int o = 32; o >= 1; o >>= 1) s += __shfl_xor(s, o);
;     const float mean = s * (1.f / 1024.f);
;     float ss = 0.f;
; #pragma unroll
;     for (int i = 0; i < 4; ++i) { v[i] = v[i] - mean; ss += v[i][0] * v[i][0] + v[i][1] * v[i][1] + v[i][2] * v[i][2] + v[i][3] * v[i][3]; }
; #pragma unroll
;     for (int o = 32; o >= 1; o >>= 1) ss += __shfl_xor(ss, o);
;     const float rstd = rsqrtf(ss * (1.f / 1024.f) + LN_EPS);
; #pragma unroll
;     for (int i = 0; i < 4; ++i) {
;       const f32x4 y = v[i] * rstd * gv[i] + bv[i];
;       if (r >= MP) *(f32x4*)(row + i * 256 + lane * 4) = y * samp_scale;
;       else if (f32_all) *(f32x4*)(row + i * 256 + lane * 4) = y;
;       if (xbf) {
;         u32x2 wv;
;         wv[0] = cvt_pk_bf16(y[0], y[1]); wv[1] = cvt_pk_bf16(y[2], y[3]);
;         *(u32x2*)(xbf + (size_t)r * 1024 + i * 256 + lane * 4) = wv;
;       }
;     }
	v_pk_add_f32 v[66:67], v[0:1], v[2:3]
	v_pk_add_f32 v[68:69], v[4:5], v[6:7]
	v_pk_add_f32 v[70:71], v[8:9], v[10:11]
	v_pk_add_f32 v[72:73], v[12:13], v[14:15]
	v_pk_add_f32 v[66:67], v[66:67], v[68:69]
	v_pk_add_f32 v[70:71], v[70:71], v[72:73]
	v_pk_add_f32 v[66:67], v[66:67], v[70:71]
	v_add_f32_e32 v66, v66, v67
	s_nop 1
	v_add_f32_dpp v66, v66, v66 row_shr:1 row_mask:0xf bank_mask:0xf bound_ctrl:1
	s_nop 1
	v_add_f32_dpp v66, v66, v66 row_shr:2 row_mask:0xf bank_mask:0xf bound_ctrl:1
	s_nop 1
	v_add_f32_dpp v66, v66, v66 row_shr:4 row_mask:0xf bank_mask:0xf bound_ctrl:1
	s_nop 1
	v_add_f32_dpp v66, v66, v66 row_shr:8 row_mask:0xf bank_mask:0xf bound_ctrl:1
	s_nop 0
	v_readlane_b32 s9, v66, 15
	v_readlane_b32 s10, v66, 31
	v_readlane_b32 s11, v66, 47
	v_readlane_b32 vcc_lo, v66, 63
	s_nop 1
	v_mov_b32_e32 v66, s9
	v_add_f32_e32 v66, s10, v66
	v_add_f32_e32 v66, s11, v66
	v_add_f32_e32 v66, vcc_lo, v66
	v_mul_f32_e32 v116, 0x3a800000, v66
	v_mov_b32_e32 v117, v116
	v_pk_add_f32 v[0:1], v[0:1], v[116:117] neg_lo:[0,1] neg_hi:[0,1]
	v_pk_add_f32 v[2:3], v[2:3], v[116:117] neg_lo:[0,1] neg_hi:[0,1]
	v_pk_add_f32 v[4:5], v[4:5], v[116:117] neg_lo:[0,1] neg_hi:[0,1]
	v_pk_add_f32 v[6:7], v[6:7], v[116:117] neg_lo:[0,1] neg_hi:[0,1]
	v_pk_add_f32 v[8:9], v[8:9], v[116:117] neg_lo:[0,1] neg_hi:[0,1]
	v_pk_add_f32 v[10:11], v[10:11], v[116:117] neg_lo:[0,1] neg_hi:[0,1]
	v_pk_add_f32 v[12:13], v[12:13], v[116:117] neg_lo:[0,1] neg_hi:[0,1]
	v_pk_add_f32 v[14:15], v[14:15], v[116:117] neg_lo:[0,1] neg_hi:[0,1]
	v_pk_mul_f32 v[66:67], v[0:1], v[0:1]
	v_pk_mul_f32 v[68:69], v[2:3], v[2:3]
	v_pk_fma_f32 v[66:67], v[4:5], v[4:5], v[66:67]
	v_pk_fma_f32 v[68:69], v[6:7], v[6:7], v[68:69]
	v_pk_fma_f32 v[66:67], v[8:9], v[8:9], v[66:67]
	v_pk_fma_f32 v[68:69], v[10:11], v[10:11], v[68:69]
	v_pk_fma_f32 v[66:67], v[12:13], v[12:13], v[66:67]
	v_pk_fma_f32 v[68:69], v[14:15], v[14:15], v[68:69]
	v_pk_add_f32 v[66:67], v[66:67], v[68:69]
	v_add_f32_e32 v66, v66, v67
	s_nop 1
	v_add_f32_dpp v66, v66, v66 row_shr:1 row_mask:0xf bank_mask:0xf bound_ctrl:1
	s_nop 1
	v_add_f32_dpp v66, v66, v66 row_shr:2 row_mask:0xf bank_mask:0xf bound_ctrl:1
	s_nop 1
	v_add_f32_dpp v66, v66, v66 row_shr:4 row_mask:0xf bank_mask:0xf bound_ctrl:1
	s_nop 1
	v_add_f32_dpp v66, v66, v66 row_shr:8 row_mask:0xf bank_mask:0xf bound_ctrl:1
	s_nop 0
	v_readlane_b32 s9, v66, 15
	v_readlane_b32 s10, v66, 31
	v_readlane_b32 s11, v66, 47
	v_readlane_b32 vcc_lo, v66, 63
	s_nop 1
	v_mov_b32_e32 v66, s9
	v_add_f32_e32 v66, s10, v66
	v_add_f32_e32 v66, s11, v66
	v_add_f32_e32 v66, vcc_lo, v66
	v_mul_f32_e32 v66, 0x3a800000, v66
	v_add_f32_e32 v66, 0x3727c5ac, v66
	v_rsq_f32_e32 v118, v66
	s_nop 0
	v_mov_b32_e32 v119, v118
	v_pk_mul_f32 v[0:1], v[0:1], v[118:119]
	v_pk_mul_f32 v[2:3], v[2:3], v[118:119]
	v_pk_mul_f32 v[4:5], v[4:5], v[118:119]
	v_pk_mul_f32 v[6:7], v[6:7], v[118:119]
	v_pk_mul_f32 v[8:9], v[8:9], v[118:119]
	v_pk_mul_f32 v[10:11], v[10:11], v[118:119]
	v_pk_mul_f32 v[12:13], v[12:13], v[118:119]
	v_pk_mul_f32 v[14:15], v[14:15], v[118:119]
	v_pk_fma_f32 v[76:77], v[0:1], v[34:35], v[50:51]
	v_pk_fma_f32 v[78:79], v[2:3], v[36:37], v[52:53]
	v_pk_fma_f32 v[80:81], v[4:5], v[38:39], v[54:55]
	v_pk_fma_f32 v[82:83], v[6:7], v[40:41], v[56:57]
	v_pk_fma_f32 v[84:85], v[8:9], v[42:43], v[58:59]
	v_pk_fma_f32 v[86:87], v[10:11], v[44:45], v[60:61]
	v_pk_fma_f32 v[88:89], v[12:13], v[46:47], v[62:63]
	v_pk_fma_f32 v[90:91], v[14:15], v[48:49], v[64:65]
	v_cvt_pk_bf16_f32 v92, v76, v77
	v_cvt_pk_bf16_f32 v93, v78, v79
	v_cvt_pk_bf16_f32 v94, v80, v81
	v_cvt_pk_bf16_f32 v95, v82, v83
	v_cvt_pk_bf16_f32 v96, v84, v85
	v_cvt_pk_bf16_f32 v97, v86, v87
	v_cvt_pk_bf16_f32 v98, v88, v89
	v_cvt_pk_bf16_f32 v99, v90, v91
	global_store_dwordx2 v115, v[92:93], s[2:3] offset:0 sc1
	global_store_dwordx2 v115, v[94:95], s[2:3] offset:512 sc1
	global_store_dwordx2 v115, v[96:97], s[2:3] offset:1024 sc1
	global_store_dwordx2 v115, v[98:99], s[2:3] offset:1536 sc1
	s_add_u32 s2, s2, 0x400000
	s_addc_u32 s3, s3, 0
	s_waitcnt vmcnt(4)
	v_pk_add_f32 v[66:67], v[18:19], v[20:21]
	v_pk_add_f32 v[68:69], v[22:23], v[24:25]
	v_pk_add_f32 v[70:71], v[26:27], v[28:29]
	v_pk_add_f32 v[72:73], v[30:31], v[32:33]
	v_pk_add_f32 v[66:67], v[66:67], v[68:69]
	v_pk_add_f32 v[70:71], v[70:71], v[72:73]
	v_pk_add_f32 v[66:67], v[66:67], v[70:71]
	v_add_f32_e32 v66, v66, v67
	s_nop 1
	v_add_f32_dpp v66, v66, v66 row_shr:1 row_mask:0xf bank_mask:0xf bound_ctrl:1
	s_nop 1
	v_add_f32_dpp v66, v66, v66 row_shr:2 row_mask:0xf bank_mask:0xf bound_ctrl:1
	s_nop 1
	v_add_f32_dpp v66, v66, v66 row_shr:4 row_mask:0xf bank_mask:0xf bound_ctrl:1
	s_nop 1
	v_add_f32_dpp v66, v66, v66 row_shr:8 row_mask:0xf bank_mask:0xf bound_ctrl:1
	s_nop 0
	v_readlane_b32 s9, v66, 15
	v_readlane_b32 s10, v66, 31
	v_readlane_b32 s11, v66, 47
	v_readlane_b32 vcc_lo, v66, 63
	s_nop 1
	v_mov_b32_e32 v66, s9
	v_add_f32_e32 v66, s10, v66
	v_add_f32_e32 v66, s11, v66
	v_add_f32_e32 v66, vcc_lo, v66
	v_mul_f32_e32 v116, 0x3a800000, v66
	v_mov_b32_e32 v117, v116
	v_pk_add_f32 v[18:19], v[18:19], v[116:117] neg_lo:[0,1] neg_hi:[0,1]
	v_pk_add_f32 v[20:21], v[20:21], v[116:117] neg_lo:[0,1] neg_hi:[0,1]
	v_pk_add_f32 v[22:23], v[22:23], v[116:117] neg_lo:[0,1] neg_hi:[0,1]
	v_pk_add_f32 v[24:25], v[24:25], v[116:117] neg_lo:[0,1] neg_hi:[0,1]
	v_pk_add_f32 v[26:27], v[26:27], v[116:117] neg_lo:[0,1] neg_hi:[0,1]
	v_pk_add_f32 v[28:29], v[28:29], v[116:117] neg_lo:[0,1] neg_hi:[0,1]
	v_pk_add_f32 v[30:31], v[30:31], v[116:117] neg_lo:[0,1] neg_hi:[0,1]
	v_pk_add_f32 v[32:33], v[32:33], v[116:117] neg_lo:[0,1] neg_hi:[0,1]
	v_pk_mul_f32 v[66:67], v[18:19], v[18:19]
; __device__ __forceinline__ void phase_ln(float* R, const float* __restrict__ g, const float* __restrict__ b, bf16_t* xbf, float samp_scale, const float* __restrict__ part, int nsplit, bool f32_all) {
;     ...
;   for (int r = gw; r < MT; r += nw) {
;     float* row = R + (size_t)r * 1024;
;     f32x4 v[4];
; #pragma unroll
;     for (int i = 0; i < 4; ++i) v[i] = *(const f32x4*)(row + i * 256 + lane * 4);
;     if (r >= MP) {
;       for (int sp = 0; sp < nsplit; ++sp) {
;         const float* prow = part + ((size_t)sp * MS + (r - MP)) * 1024;
; #pragma unroll
;         for (int i = 0; i < 4; ++i) v[i] = v[i] + *(const f32x4*)(prow + i * 256 + lane * 4);
;       }
;     }
;     float s = 0.f;
; #pragma unroll
;     for (int i = 0; i < 4; ++i) s += v[i][0] + v[i][1] + v[i][2] + v[i][3];
; #pragma unroll
;     for (int o = 32; o >= 1; o >>= 1) s += __shfl_xor(s, o);
;     const float mean = s * (1.f / 1024.f);
;     float ss = 0.f;
; #pragma unroll
;     for (int i = 0; i < 4; ++i) { v[i] = v[i] - mean; ss += v[i][0] * v[i][0] + v[i][1] * v[i][1] + v[i][2] * v[i][2] + v[i][3] * v[i][3]; }
; #pragma unroll
;     for (int o = 32; o >= 1; o >>= 1) ss += __shfl_xor(ss, o);
;     const float rstd = rsqrtf(ss * (1.f / 1024.f) + LN_EPS);
; #pragma unroll
;     for (int i = 0; i < 4; ++i) {
;       const f32x4 y = v[i] * rstd * gv[i] + bv[i];
;       if (r >= MP) *(f32x4*)(row + i * 256 + lane * 4) = y * samp_scale;
;       else if (f32_all) *(f32x4*)(row + i * 256 + lane * 4) = y;
;       if (xbf) {
;         u32x2 wv;
;         wv[0] = cvt_pk_bf16(y[0], y[1]); wv[1] = cvt_pk_bf16(y[2], y[3]);
;         *(u32x2*)(xbf + (size_t)r * 1024 + i * 256 + lane * 4) = wv;
;       }
;     }
	v_pk_mul_f32 v[68:69], v[20:21], v[20:21]
	v_pk_fma_f32 v[66:67], v[22:23], v[22:23], v[66:67]
	v_pk_fma_f32 v[68:69], v[24:25], v[24:25], v[68:69]
	v_pk_fma_f32 v[66:67], v[26:27], v[26:27], v[66:67]
	v_pk_fma_f32 v[68:69], v[28:29], v[28:29], v[68:69]
	v_pk_fma_f32 v[66:67], v[30:31], v[30:31], v[66:67]
	v_pk_fma_f32 v[68:69], v[32:33], v[32:33], v[68:69]
	v_pk_add_f32 v[66:67], v[66:67], v[68:69]
	v_add_f32_e32 v66, v66, v67
	s_nop 1
	v_add_f32_dpp v66, v66, v66 row_shr:1 row_mask:0xf bank_mask:0xf bound_ctrl:1
	s_nop 1
	v_add_f32_dpp v66, v66, v66 row_shr:2 row_mask:0xf bank_mask:0xf bound_ctrl:1
	s_nop 1
	v_add_f32_dpp v66, v66, v66 row_shr:4 row_mask:0xf bank_mask:0xf bound_ctrl:1
	s_nop 1
	v_add_f32_dpp v66, v66, v66 row_shr:8 row_mask:0xf bank_mask:0xf bound_ctrl:1
	s_nop 0
	v_readlane_b32 s9, v66, 15
	v_readlane_b32 s10, v66, 31
	v_readlane_b32 s11, v66, 47
	v_readlane_b32 vcc_lo, v66, 63
	s_nop 1
	v_mov_b32_e32 v66, s9
	v_add_f32_e32 v66, s10, v66
	v_add_f32_e32 v66, s11, v66
	v_add_f32_e32 v66, vcc_lo, v66
	v_mul_f32_e32 v66, 0x3a800000, v66
	v_add_f32_e32 v66, 0x3727c5ac, v66
	v_rsq_f32_e32 v118, v66
	s_nop 0
	v_mov_b32_e32 v119, v118
	v_pk_mul_f32 v[18:19], v[18:19], v[118:119]
	v_pk_mul_f32 v[20:21], v[20:21], v[118:119]
	v_pk_mul_f32 v[22:23], v[22:23], v[118:119]
	v_pk_mul_f32 v[24:25], v[24:25], v[118:119]
	v_pk_mul_f32 v[26:27], v[26:27], v[118:119]
	v_pk_mul_f32 v[28:29], v[28:29], v[118:119]
	v_pk_mul_f32 v[30:31], v[30:31], v[118:119]
	v_pk_mul_f32 v[32:33], v[32:33], v[118:119]
	v_pk_fma_f32 v[76:77], v[18:19], v[34:35], v[50:51]
	v_pk_fma_f32 v[78:79], v[20:21], v[36:37], v[52:53]
	v_pk_fma_f32 v[80:81], v[22:23], v[38:39], v[54:55]
	v_pk_fma_f32 v[82:83], v[24:25], v[40:41], v[56:57]
	v_pk_fma_f32 v[84:85], v[26:27], v[42:43], v[58:59]
	v_pk_fma_f32 v[86:87], v[28:29], v[44:45], v[60:61]
	v_pk_fma_f32 v[88:89], v[30:31], v[46:47], v[62:63]
	v_pk_fma_f32 v[90:91], v[32:33], v[48:49], v[64:65]
	v_cvt_pk_bf16_f32 v92, v76, v77
	v_cvt_pk_bf16_f32 v93, v78, v79
	v_cvt_pk_bf16_f32 v94, v80, v81
	v_cvt_pk_bf16_f32 v95, v82, v83
	v_cvt_pk_bf16_f32 v96, v84, v85
	v_cvt_pk_bf16_f32 v97, v86, v87
	v_cvt_pk_bf16_f32 v98, v88, v89
	v_cvt_pk_bf16_f32 v99, v90, v91
	global_store_dwordx2 v115, v[92:93], s[2:3] offset:0 sc1
	global_store_dwordx2 v115, v[94:95], s[2:3] offset:512 sc1
	global_store_dwordx2 v115, v[96:97], s[2:3] offset:1024 sc1
	global_store_dwordx2 v115, v[98:99], s[2:3] offset:1536 sc1
	s_add_u32 s2, s2, 0x400000
	s_addc_u32 s3, s3, 0
	v_readfirstlane_b32 s10, v244
	v_readlane_b32 s9, v254, 6
	s_lshr_b32 s10, s10, 6
	s_cmp_ge_u32 s10, 2
	s_cbranch_scc1 .Lln1_done
	s_lshl_b32 s9, s9, 1
	s_add_i32 s9, s9, s10
	s_lshl_b32 s11, s9, 12
	s_add_u32 s11, s11, 0x8000000
	s_add_u32 s0, s4, s11
	s_addc_u32 s1, s5, 0
	s_lshl_b32 s11, s9, 11
	s_add_u32 s11, s11, 0x79c0000
	s_add_u32 s2, s6, s11
	s_addc_u32 s3, s7, 0
	s_lshl_b32 s11, s9, 12
	s_add_u32 s11, s11, 0x1e482000
	s_add_u32 s10, s6, s11
	s_addc_u32 s11, s7, 0
	global_load_dwordx4 v[0:3], v114, s[0:1] offset:0 nt
	global_load_dwordx4 v[4:7], v114, s[0:1] offset:1024 nt
	global_load_dwordx4 v[8:11], v114, s[0:1] offset:2048 nt
	global_load_dwordx4 v[12:15], v114, s[0:1] offset:3072 nt
	global_load_dwordx4 v[18:21], v114, s[10:11] offset:0 nt
	global_load_dwordx4 v[22:25], v114, s[10:11] offset:1024 nt
	global_load_dwordx4 v[26:29], v114, s[10:11] offset:2048 nt
	global_load_dwordx4 v[30:33], v114, s[10:11] offset:3072 nt
	s_add_u32 s10, s10, 0x200000
	s_addc_u32 s11, s11, 0
	global_load_dwordx4 v[66:69], v114, s[10:11] offset:0 nt
	global_load_dwordx4 v[70:73], v114, s[10:11] offset:1024 nt
	global_load_dwordx4 v[74:77], v114, s[10:11] offset:2048 nt
	global_load_dwordx4 v[78:81], v114, s[10:11] offset:3072 nt
	s_add_u32 s10, s10, 0x200000
	s_addc_u32 s11, s11, 0
	global_load_dwordx4 v[82:85], v114, s[10:11] offset:0 nt
	global_load_dwordx4 v[86:89], v114, s[10:11] offset:1024 nt
	global_load_dwordx4 v[90:93], v114, s[10:11] offset:2048 nt
	global_load_dwordx4 v[94:97], v114, s[10:11] offset:3072 nt
	s_add_u32 s10, s10, 0x200000
	s_addc_u32 s11, s11, 0
	global_load_dwordx4 v[98:101], v114, s[10:11] offset:0 nt
	global_load_dwordx4 v[102:105], v114, s[10:11] offset:1024 nt
	global_load_dwordx4 v[106:109], v114, s[10:11] offset:2048 nt
	global_load_dwordx4 v[110:113], v114, s[10:11] offset:3072 nt
	s_add_u32 s10, s10, 0x200000
	s_addc_u32 s11, s11, 0
	s_waitcnt vmcnt(0)
; __device__ __forceinline__ void phase_ln(float* R, const float* __restrict__ g, const float* __restrict__ b, bf16_t* xbf, float samp_scale, const float* __restrict__ part, int nsplit, bool f32_all) {
;     ...
;     if (r >= MP) {
;       for (int sp = 0; sp < nsplit; ++sp) {
;         const float* prow = part + ((size_t)sp * MS + (r - MP)) * 1024;
; #pragma unroll
;         for (int i = 0; i < 4; ++i) v[i] = v[i] + *(const f32x4*)(prow + i * 256 + lane * 4);
;       }
;     }
;     float s = 0.f;
; #pragma unroll
;     for (int i = 0; i < 4; ++i) s += v[i][0] + v[i][1] + v[i][2] + v[i][3];
; #pragma unroll
;     for (int o = 32; o >= 1; o >>= 1) s += __shfl_xor(s, o);
;     const float mean = s * (1.f / 1024.f);
;     float ss = 0.f;
; #pragma unroll
;     for (int i = 0; i < 4; ++i) { v[i] = v[i] - mean; ss += v[i][0] * v[i][0] + v[i][1] * v[i][1] + v[i][2] * v[i][2] + v[i][3] * v[i][3]; }
; #pragma unroll
;     for (int o = 32; o >= 1; o >>= 1) ss += __shfl_xor(ss, o);
;     const float rstd = rsqrtf(ss * (1.f / 1024.f) + LN_EPS);
; #pragma unroll
;     for (int i = 0; i < 4; ++i) {
;       const f32x4 y = v[i] * rstd * gv[i] + bv[i];
;       if (r >= MP) *(f32x4*)(row + i * 256 + lane * 4) = y * samp_scale;
;       else if (f32_all) *(f32x4*)(row + i * 256 + lane * 4) = y;
;       if (xbf) {
;         u32x2 wv;
;         wv[0] = cvt_pk_bf16(y[0], y[1]); wv[1] = cvt_pk_bf16(y[2], y[3]);
;         *(u32x2*)(xbf + (size_t)r * 1024 + i * 256 + lane * 4) = wv;
;       }
;     }
	v_pk_add_f32 v[0:1], v[0:1], v[18:19]
	v_pk_add_f32 v[2:3], v[2:3], v[20:21]
	v_pk_add_f32 v[4:5], v[4:5], v[22:23]
	v_pk_add_f32 v[6:7], v[6:7], v[24:25]
	v_pk_add_f32 v[8:9], v[8:9], v[26:27]
	v_pk_add_f32 v[10:11], v[10:11], v[28:29]
	v_pk_add_f32 v[12:13], v[12:13], v[30:31]
	v_pk_add_f32 v[14:15], v[14:15], v[32:33]
	v_pk_add_f32 v[0:1], v[0:1], v[66:67]
	v_pk_add_f32 v[2:3], v[2:3], v[68:69]
	v_pk_add_f32 v[4:5], v[4:5], v[70:71]
	v_pk_add_f32 v[6:7], v[6:7], v[72:73]
	v_pk_add_f32 v[8:9], v[8:9], v[74:75]
	v_pk_add_f32 v[10:11], v[10:11], v[76:77]
	v_pk_add_f32 v[12:13], v[12:13], v[78:79]
	v_pk_add_f32 v[14:15], v[14:15], v[80:81]
	v_pk_add_f32 v[0:1], v[0:1], v[82:83]
	v_pk_add_f32 v[2:3], v[2:3], v[84:85]
	v_pk_add_f32 v[4:5], v[4:5], v[86:87]
	v_pk_add_f32 v[6:7], v[6:7], v[88:89]
	v_pk_add_f32 v[8:9], v[8:9], v[90:91]
	v_pk_add_f32 v[10:11], v[10:11], v[92:93]
	v_pk_add_f32 v[12:13], v[12:13], v[94:95]
	v_pk_add_f32 v[14:15], v[14:15], v[96:97]
	v_pk_add_f32 v[0:1], v[0:1], v[98:99]
	v_pk_add_f32 v[2:3], v[2:3], v[100:101]
	v_pk_add_f32 v[4:5], v[4:5], v[102:103]
	v_pk_add_f32 v[6:7], v[6:7], v[104:105]
	v_pk_add_f32 v[8:9], v[8:9], v[106:107]
	v_pk_add_f32 v[10:11], v[10:11], v[108:109]
	v_pk_add_f32 v[12:13], v[12:13], v[110:111]
	v_pk_add_f32 v[14:15], v[14:15], v[112:113]
	v_pk_add_f32 v[66:67], v[0:1], v[2:3]
	v_pk_add_f32 v[68:69], v[4:5], v[6:7]
	v_pk_add_f32 v[70:71], v[8:9], v[10:11]
	v_pk_add_f32 v[72:73], v[12:13], v[14:15]
	v_pk_add_f32 v[66:67], v[66:67], v[68:69]
	v_pk_add_f32 v[70:71], v[70:71], v[72:73]
	v_pk_add_f32 v[66:67], v[66:67], v[70:71]
	v_add_f32_e32 v66, v66, v67
	s_nop 1
	v_add_f32_dpp v66, v66, v66 row_shr:1 row_mask:0xf bank_mask:0xf bound_ctrl:1
	s_nop 1
	v_add_f32_dpp v66, v66, v66 row_shr:2 row_mask:0xf bank_mask:0xf bound_ctrl:1
	s_nop 1
	v_add_f32_dpp v66, v66, v66 row_shr:4 row_mask:0xf bank_mask:0xf bound_ctrl:1
	s_nop 1
	v_add_f32_dpp v66, v66, v66 row_shr:8 row_mask:0xf bank_mask:0xf bound_ctrl:1
	s_nop 0
	v_readlane_b32 s9, v66, 15
	v_readlane_b32 s10, v66, 31
	v_readlane_b32 s11, v66, 47
	v_readlane_b32 vcc_lo, v66, 63
	s_nop 1
	v_mov_b32_e32 v66, s9
	v_add_f32_e32 v66, s10, v66
	v_add_f32_e32 v66, s11, v66
	v_add_f32_e32 v66, vcc_lo, v66
	v_mul_f32_e32 v116, 0x3a800000, v66
	v_mov_b32_e32 v117, v116
	v_pk_add_f32 v[0:1], v[0:1], v[116:117] neg_lo:[0,1] neg_hi:[0,1]
	v_pk_add_f32 v[2:3], v[2:3], v[116:117] neg_lo:[0,1] neg_hi:[0,1]
	v_pk_add_f32 v[4:5], v[4:5], v[116:117] neg_lo:[0,1] neg_hi:[0,1]
	v_pk_add_f32 v[6:7], v[6:7], v[116:117] neg_lo:[0,1] neg_hi:[0,1]
	v_pk_add_f32 v[8:9], v[8:9], v[116:117] neg_lo:[0,1] neg_hi:[0,1]
	v_pk_add_f32 v[10:11], v[10:11], v[116:117] neg_lo:[0,1] neg_hi:[0,1]
	v_pk_add_f32 v[12:13], v[12:13], v[116:117] neg_lo:[0,1] neg_hi:[0,1]
	v_pk_add_f32 v[14:15], v[14:15], v[116:117] neg_lo:[0,1] neg_hi:[0,1]
	v_pk_mul_f32 v[66:67], v[0:1], v[0:1]
	v_pk_mul_f32 v[68:69], v[2:3], v[2:3]
	v_pk_fma_f32 v[66:67], v[4:5], v[4:5], v[66:67]
	v_pk_fma_f32 v[68:69], v[6:7], v[6:7], v[68:69]
	v_pk_fma_f32 v[66:67], v[8:9], v[8:9], v[66:67]
	v_pk_fma_f32 v[68:69], v[10:11], v[10:11], v[68:69]
	v_pk_fma_f32 v[66:67], v[12:13], v[12:13], v[66:67]
	v_pk_fma_f32 v[68:69], v[14:15], v[14:15], v[68:69]
	v_pk_add_f32 v[66:67], v[66:67], v[68:69]
	v_add_f32_e32 v66, v66, v67
	s_nop 1
	v_add_f32_dpp v66, v66, v66 row_shr:1 row_mask:0xf bank_mask:0xf bound_ctrl:1
	s_nop 1
	v_add_f32_dpp v66, v66, v66 row_shr:2 row_mask:0xf bank_mask:0xf bound_ctrl:1
	s_nop 1
	v_add_f32_dpp v66, v66, v66 row_shr:4 row_mask:0xf bank_mask:0xf bound_ctrl:1
	s_nop 1
	v_add_f32_dpp v66, v66, v66 row_shr:8 row_mask:0xf bank_mask:0xf bound_ctrl:1
	s_nop 0
	v_readlane_b32 s9, v66, 15
	v_readlane_b32 s10, v66, 31
	v_readlane_b32 s11, v66, 47
	v_readlane_b32 vcc_lo, v66, 63
	s_nop 1
	v_mov_b32_e32 v66, s9
	v_add_f32_e32 v66, s10, v66
	v_add_f32_e32 v66, s11, v66
	v_add_f32_e32 v66, vcc_lo, v66
	v_mul_f32_e32 v66, 0x3a800000, v66
	v_add_f32_e32 v66, 0x3727c5ac, v66
	v_rsq_f32_e32 v118, v66
	s_nop 0
	v_mov_b32_e32 v119, v118
	v_pk_mul_f32 v[0:1], v[0:1], v[118:119]
	v_pk_mul_f32 v[2:3], v[2:3], v[118:119]
	v_pk_mul_f32 v[4:5], v[4:5], v[118:119]
	v_pk_mul_f32 v[6:7], v[6:7], v[118:119]
	v_pk_mul_f32 v[8:9], v[8:9], v[118:119]
	v_pk_mul_f32 v[10:11], v[10:11], v[118:119]
	v_pk_mul_f32 v[12:13], v[12:13], v[118:119]
	v_pk_mul_f32 v[14:15], v[14:15], v[118:119]
	v_pk_fma_f32 v[76:77], v[0:1], v[34:35], v[50:51]
	v_pk_fma_f32 v[78:79], v[2:3], v[36:37], v[52:53]
	v_pk_fma_f32 v[80:81], v[4:5], v[38:39], v[54:55]
	v_pk_fma_f32 v[82:83], v[6:7], v[40:41], v[56:57]
	v_pk_fma_f32 v[84:85], v[8:9], v[42:43], v[58:59]
	v_pk_fma_f32 v[86:87], v[10:11], v[44:45], v[60:61]
	v_pk_fma_f32 v[88:89], v[12:13], v[46:47], v[62:63]
	v_pk_fma_f32 v[90:91], v[14:15], v[48:49], v[64:65]
	s_mov_b32 s9, 0x3fb504f3
	v_mov_b32_e32 v120, s9
	v_mov_b32_e32 v121, s9
	v_pk_mul_f32 v[0:1], v[76:77], v[120:121]
	v_pk_mul_f32 v[2:3], v[78:79], v[120:121]
	v_pk_mul_f32 v[4:5], v[80:81], v[120:121]
	v_pk_mul_f32 v[6:7], v[82:83], v[120:121]
	v_pk_mul_f32 v[8:9], v[84:85], v[120:121]
	v_pk_mul_f32 v[10:11], v[86:87], v[120:121]
	v_pk_mul_f32 v[12:13], v[88:89], v[120:121]
	v_pk_mul_f32 v[14:15], v[90:91], v[120:121]
	global_store_dwordx4 v114, v[0:3], s[0:1] offset:0 sc1
	global_store_dwordx4 v114, v[4:7], s[0:1] offset:1024 sc1
	global_store_dwordx4 v114, v[8:11], s[0:1] offset:2048 sc1
	global_store_dwordx4 v114, v[12:15], s[0:1] offset:3072 sc1
	v_cvt_pk_bf16_f32 v92, v76, v77
	v_cvt_pk_bf16_f32 v93, v78, v79
	v_cvt_pk_bf16_f32 v94, v80, v81
	v_cvt_pk_bf16_f32 v95, v82, v83
	v_cvt_pk_bf16_f32 v96, v84, v85
	v_cvt_pk_bf16_f32 v97, v86, v87
	v_cvt_pk_bf16_f32 v98, v88, v89
	v_cvt_pk_bf16_f32 v99, v90, v91
	global_store_dwordx2 v115, v[92:93], s[2:3] offset:0 sc1
	global_store_dwordx2 v115, v[94:95], s[2:3] offset:512 sc1
	global_store_dwordx2 v115, v[96:97], s[2:3] offset:1024 sc1
	global_store_dwordx2 v115, v[98:99], s[2:3] offset:1536 sc1

; __device__ __forceinline__ int otid() { int t = threadIdx.x; asm volatile("" : "+v"(t)); return t; }
; __device__ __forceinline__ void phase_ln(float* R, const float* __restrict__ g, const float* __restrict__ b, bf16_t* xbf, float samp_scale, const float* __restrict__ part, int nsplit, bool f32_all) {
;   const int tid = otid(), lane = tid & 63, gw = blockIdx.x * 8 + (tid >> 6), nw = gridDim.x * 8;
;   f32x4 gv[4], bv[4];
; #pragma unroll
;   for (int i = 0; i < 4; ++i) { gv[i] = *(const f32x4*)(g + i * 256 + lane * 4); bv[i] = *(const f32x4*)(b + i * 256 + lane * 4); }
;   for (int r = gw; r < MT; r += nw) {
;     float* row = R + (size_t)r * 1024;
;     f32x4 v[4];
; #pragma unroll
;     for (int i = 0; i < 4; ++i) v[i] = *(const f32x4*)(row + i * 256 + lane * 4);
;     if (r >= MP) {
;       for (int sp = 0; sp < nsplit; ++sp) {
;         const float* prow = part + ((size_t)sp * MS + (r - MP)) * 1024;
; #pragma unroll
;         for (int i = 0; i < 4; ++i) v[i] = v[i] + *(const f32x4*)(prow + i * 256 + lane * 4);
;       }
;     }
;     float s = 0.f;
; #pragma unroll
;     for (int i = 0; i < 4; ++i) s += v[i][0] + v[i][1] + v[i][2] + v[i][3];
; #pragma unroll
;     for (int o = 32; o >= 1; o >>= 1) s += __shfl_xor(s, o);
;     const float mean = s * (1.f / 1024.f);
;     float ss = 0.f;
; #pragma unroll
;     for (int i = 0; i < 4; ++i) { v[i] = v[i] - mean; ss += v[i][0] * v[i][0] + v[i][1] * v[i][1] + v[i][2] * v[i][2] + v[i][3] * v[i][3]; }
; #pragma unroll
;     for (int o = 32; o >= 1; o >>= 1) ss += __shfl_xor(ss, o);
;     const float rstd = rsqrtf(ss * (1.f / 1024.f) + LN_EPS);
; #pragma unroll
;     for (int i = 0; i < 4; ++i) {
;       const f32x4 y = v[i] * rstd * gv[i] + bv[i];
;       if (r >= MP) *(f32x4*)(row + i * 256 + lane * 4) = y * samp_scale;
;       else if (f32_all) *(f32x4*)(row + i * 256 + lane * 4) = y;
;       if (xbf) {
;         u32x2 wv;
;         wv[0] = cvt_pk_bf16(y[0], y[1]); wv[1] = cvt_pk_bf16(y[2], y[3]);
;         *(u32x2*)(xbf + (size_t)r * 1024 + i * 256 + lane * 4) = wv;
;       }
;     }
.LBB0_3944:
	s_or_b64 exec, exec, s[0:1]
	v_readlane_b32 s0, v254, 51
	s_nop 0
	s_cmp_lg_u32 s0, 0
	s_cbranch_scc1 .Lln2_orig
	v_readlane_b32 s6, v254, 2
	v_readlane_b32 s7, v254, 3
	v_readlane_b32 s8, v255, 22
	s_waitcnt lgkmcnt(0)
	s_barrier
	s_load_dwordx4 s[0:3], s[6:7], 0x98
	s_load_dwordx4 s[4:7], s[6:7], 0xa8
	v_readlane_b32 s9, v254, 15
	v_readfirstlane_b32 s10, v244
	v_lshlrev_b32_e32 v114, 4, v252
	v_lshlrev_b32_e32 v115, 3, v252
	s_lshr_b32 s10, s10, 6
	s_add_i32 s9, s9, s10
	s_lshl_b32 s11, s8, 12
	s_waitcnt lgkmcnt(0)
	s_add_u32 s0, s0, s11
	s_addc_u32 s1, s1, 0
	s_add_u32 s2, s2, s11
	s_addc_u32 s3, s3, 0
	global_load_dwordx4 v[34:37], v114, s[0:1] offset:0 nt
	global_load_dwordx4 v[38:41], v114, s[0:1] offset:1024 nt
	global_load_dwordx4 v[42:45], v114, s[0:1] offset:2048 nt
	global_load_dwordx4 v[46:49], v114, s[0:1] offset:3072 nt
	global_load_dwordx4 v[50:53], v114, s[2:3] offset:0
	global_load_dwordx4 v[54:57], v114, s[2:3] offset:1024
	global_load_dwordx4 v[58:61], v114, s[2:3] offset:2048
	global_load_dwordx4 v[62:65], v114, s[2:3] offset:3072
	s_lshl_b32 s11, s9, 12
	s_add_u32 s0, s4, s11
	s_addc_u32 s1, s5, 0
	s_lshl_b32 s11, s9, 11
	s_add_u32 s11, s11, 0x39c0000
	s_add_u32 s2, s6, s11
	s_addc_u32 s3, s7, 0
	global_load_dwordx4 v[0:3], v114, s[0:1] offset:0 nt
	global_load_dwordx4 v[4:7], v114, s[0:1] offset:1024 nt
	global_load_dwordx4 v[8:11], v114, s[0:1] offset:2048 nt
	global_load_dwordx4 v[12:15], v114, s[0:1] offset:3072 nt
	s_add_u32 s0, s0, 0x800000
	s_addc_u32 s1, s1, 0
	global_load_dwordx4 v[18:21], v114, s[0:1] offset:0 nt
	global_load_dwordx4 v[22:25], v114, s[0:1] offset:1024 nt
	global_load_dwordx4 v[26:29], v114, s[0:1] offset:2048 nt
	global_load_dwordx4 v[30:33], v114, s[0:1] offset:3072 nt
	s_waitcnt vmcnt(4)
	v_pk_add_f32 v[66:67], v[0:1], v[2:3]
	v_pk_add_f32 v[68:69], v[4:5], v[6:7]
	v_pk_add_f32 v[70:71], v[8:9], v[10:11]
	v_pk_add_f32 v[72:73], v[12:13], v[14:15]
	v_pk_add_f32 v[66:67], v[66:67], v[68:69]
	v_pk_add_f32 v[70:71], v[70:71], v[72:73]
	v_pk_add_f32 v[66:67], v[66:67], v[70:71]
	v_add_f32_e32 v66, v66, v67
	s_nop 1
	v_add_f32_dpp v66, v66, v66 row_shr:1 row_mask:0xf bank_mask:0xf bound_ctrl:1
	s_nop 1
	v_add_f32_dpp v66, v66, v66 row_shr:2 row_mask:0xf bank_mask:0xf bound_ctrl:1
	s_nop 1
	v_add_f32_dpp v66, v66, v66 row_shr:4 row_mask:0xf bank_mask:0xf bound_ctrl:1
	s_nop 1
	v_add_f32_dpp v66, v66, v66 row_shr:8 row_mask:0xf bank_mask:0xf bound_ctrl:1
	s_nop 0
	v_readlane_b32 s9, v66, 15
	v_readlane_b32 s10, v66, 31
	v_readlane_b32 s11, v66, 47
	v_readlane_b32 vcc_lo, v66, 63
	s_nop 1
	v_mov_b32_e32 v66, s9
	v_add_f32_e32 v66, s10, v66
	v_add_f32_e32 v66, s11, v66
	v_add_f32_e32 v66, vcc_lo, v66
	v_mul_f32_e32 v116, 0x3a800000, v66
	v_mov_b32_e32 v117, v116
	v_pk_add_f32 v[0:1], v[0:1], v[116:117] neg_lo:[0,1] neg_hi:[0,1]
	v_pk_add_f32 v[2:3], v[2:3], v[116:117] neg_lo:[0,1] neg_hi:[0,1]
	v_pk_add_f32 v[4:5], v[4:5], v[116:117] neg_lo:[0,1] neg_hi:[0,1]
	v_pk_add_f32 v[6:7], v[6:7], v[116:117] neg_lo:[0,1] neg_hi:[0,1]
	v_pk_add_f32 v[8:9], v[8:9], v[116:117] neg_lo:[0,1] neg_hi:[0,1]
	v_pk_add_f32 v[10:11], v[10:11], v[116:117] neg_lo:[0,1] neg_hi:[0,1]
	v_pk_add_f32 v[12:13], v[12:13], v[116:117] neg_lo:[0,1] neg_hi:[0,1]
	v_pk_add_f32 v[14:15], v[14:15], v[116:117] neg_lo:[0,1] neg_hi:[0,1]
	v_pk_mul_f32 v[66:67], v[0:1], v[0:1]
	v_pk_mul_f32 v[68:69], v[2:3], v[2:3]
	v_pk_fma_f32 v[66:67], v[4:5], v[4:5], v[66:67]
	v_pk_fma_f32 v[68:69], v[6:7], v[6:7], v[68:69]
	v_pk_fma_f32 v[66:67], v[8:9], v[8:9], v[66:67]
	v_pk_fma_f32 v[68:69], v[10:11], v[10:11], v[68:69]
	v_pk_fma_f32 v[66:67], v[12:13], v[12:13], v[66:67]
	v_pk_fma_f32 v[68:69], v[14:15], v[14:15], v[68:69]
	v_pk_add_f32 v[66:67], v[66:67], v[68:69]
	v_add_f32_e32 v66, v66, v67
	s_nop 1
	v_add_f32_dpp v66, v66, v66 row_shr:1 row_mask:0xf bank_mask:0xf bound_ctrl:1
	s_nop 1
	v_add_f32_dpp v66, v66, v66 row_shr:2 row_mask:0xf bank_mask:0xf bound_ctrl:1
	s_nop 1
	v_add_f32_dpp v66, v66, v66 row_shr:4 row_mask:0xf bank_mask:0xf bound_ctrl:1
	s_nop 1
	v_add_f32_dpp v66, v66, v66 row_shr:8 row_mask:0xf bank_mask:0xf bound_ctrl:1
	s_nop 0
	v_readlane_b32 s9, v66, 15
	v_readlane_b32 s10, v66, 31
	v_readlane_b32 s11, v66, 47
	v_readlane_b32 vcc_lo, v66, 63
	s_nop 1
	v_mov_b32_e32 v66, s9
	v_add_f32_e32 v66, s10, v66
	v_add_f32_e32 v66, s11, v66
	v_add_f32_e32 v66, vcc_lo, v66
	v_mul_f32_e32 v66, 0x3a800000, v66
	v_add_f32_e32 v66, 0x3727c5ac, v66
	v_rsq_f32_e32 v118, v66
	s_nop 0
	v_mov_b32_e32 v119, v118
	v_pk_mul_f32 v[0:1], v[0:1], v[118:119]
	v_pk_mul_f32 v[2:3], v[2:3], v[118:119]
	v_pk_mul_f32 v[4:5], v[4:5], v[118:119]
	v_pk_mul_f32 v[6:7], v[6:7], v[118:119]
	v_pk_mul_f32 v[8:9], v[8:9], v[118:119]
	v_pk_mul_f32 v[10:11], v[10:11], v[118:119]
	v_pk_mul_f32 v[12:13], v[12:13], v[118:119]
	v_pk_mul_f32 v[14:15], v[14:15], v[118:119]
	v_pk_fma_f32 v[76:77], v[0:1], v[34:35], v[50:51]
	v_pk_fma_f32 v[78:79], v[2:3], v[36:37], v[52:53]
	v_pk_fma_f32 v[80:81], v[4:5], v[38:39], v[54:55]
	v_pk_fma_f32 v[82:83], v[6:7], v[40:41], v[56:57]
	v_pk_fma_f32 v[84:85], v[8:9], v[42:43], v[58:59]
	v_pk_fma_f32 v[86:87], v[10:11], v[44:45], v[60:61]
	v_pk_fma_f32 v[88:89], v[12:13], v[46:47], v[62:63]
	v_pk_fma_f32 v[90:91], v[14:15], v[48:49], v[64:65]
	s_cmp_lg_u32 s8, 0
	s_cbranch_scc1 .Lln2_f32_0
	v_cvt_pk_bf16_f32 v92, v76, v77
	v_cvt_pk_bf16_f32 v93, v78, v79
	v_cvt_pk_bf16_f32 v94, v80, v81
	v_cvt_pk_bf16_f32 v95, v82, v83
	v_cvt_pk_bf16_f32 v96, v84, v85
	v_cvt_pk_bf16_f32 v97, v86, v87
	v_cvt_pk_bf16_f32 v98, v88, v89
	v_cvt_pk_bf16_f32 v99, v90, v91
	global_store_dwordx2 v115, v[92:93], s[2:3] offset:0 sc1
	global_store_dwordx2 v115, v[94:95], s[2:3] offset:512 sc1
	global_store_dwordx2 v115, v[96:97], s[2:3] offset:1024 sc1
	global_store_dwordx2 v115, v[98:99], s[2:3] offset:1536 sc1
	s_branch .Lln2_st_0

; __device__ __forceinline__ void phase_ln(float* R, const float* __restrict__ g, const float* __restrict__ b, bf16_t* xbf, float samp_scale, const float* __restrict__ part, int nsplit, bool f32_all) {
;     ...
;   for (int r = gw; r < MT; r += nw) {
;     float* row = R + (size_t)r * 1024;
;     f32x4 v[4];
; #pragma unroll
;     for (int i = 0; i < 4; ++i) v[i] = *(const f32x4*)(row + i * 256 + lane * 4);
;     if (r >= MP) {
;       for (int sp = 0; sp < nsplit; ++sp) {
;         const float* prow = part + ((size_t)sp * MS + (r - MP)) * 1024;
; #pragma unroll
;         for (int i = 0; i < 4; ++i) v[i] = v[i] + *(const f32x4*)(prow + i * 256 + lane * 4);
;       }
;     }
;     float s = 0.f;
; #pragma unroll
;     for (int i = 0; i < 4; ++i) s += v[i][0] + v[i][1] + v[i][2] + v[i][3];
; #pragma unroll
;     for (int o = 32; o >= 1; o >>= 1) s += __shfl_xor(s, o);
;     const float mean = s * (1.f / 1024.f);
;     float ss = 0.f;
; #pragma unroll
;     for (int i = 0; i < 4; ++i) { v[i] = v[i] - mean; ss += v[i][0] * v[i][0] + v[i][1] * v[i][1] + v[i][2] * v[i][2] + v[i][3] * v[i][3]; }
; #pragma unroll
;     for (int o = 32; o >= 1; o >>= 1) ss += __shfl_xor(ss, o);
;     const float rstd = rsqrtf(ss * (1.f / 1024.f) + LN_EPS);
; #pragma unroll
;     for (int i = 0; i < 4; ++i) {
;       const f32x4 y = v[i] * rstd * gv[i] + bv[i];
;       if (r >= MP) *(f32x4*)(row + i * 256 + lane * 4) = y * samp_scale;
;       else if (f32_all) *(f32x4*)(row + i * 256 + lane * 4) = y;
;       if (xbf) {
;         u32x2 wv;
;         wv[0] = cvt_pk_bf16(y[0], y[1]); wv[1] = cvt_pk_bf16(y[2], y[3]);
;         *(u32x2*)(xbf + (size_t)r * 1024 + i * 256 + lane * 4) = wv;
;       }
;     }
.Lln2_st_0:
	s_add_u32 s2, s2, 0x400000
	s_addc_u32 s3, s3, 0
	s_add_u32 s0, s0, 0x800000
	s_addc_u32 s1, s1, 0
	global_load_dwordx4 v[0:3], v114, s[0:1] offset:0 nt
	global_load_dwordx4 v[4:7], v114, s[0:1] offset:1024 nt
	global_load_dwordx4 v[8:11], v114, s[0:1] offset:2048 nt
	global_load_dwordx4 v[12:15], v114, s[0:1] offset:3072 nt
	s_waitcnt vmcnt(8)
	v_pk_add_f32 v[66:67], v[18:19], v[20:21]
	v_pk_add_f32 v[68:69], v[22:23], v[24:25]
	v_pk_add_f32 v[70:71], v[26:27], v[28:29]
	v_pk_add_f32 v[72:73], v[30:31], v[32:33]
	v_pk_add_f32 v[66:67], v[66:67], v[68:69]
	v_pk_add_f32 v[70:71], v[70:71], v[72:73]
	v_pk_add_f32 v[66:67], v[66:67], v[70:71]
	v_add_f32_e32 v66, v66, v67
	s_nop 1
	v_add_f32_dpp v66, v66, v66 row_shr:1 row_mask:0xf bank_mask:0xf bound_ctrl:1
	s_nop 1
	v_add_f32_dpp v66, v66, v66 row_shr:2 row_mask:0xf bank_mask:0xf bound_ctrl:1
	s_nop 1
	v_add_f32_dpp v66, v66, v66 row_shr:4 row_mask:0xf bank_mask:0xf bound_ctrl:1
	s_nop 1
	v_add_f32_dpp v66, v66, v66 row_shr:8 row_mask:0xf bank_mask:0xf bound_ctrl:1
	s_nop 0
	v_readlane_b32 s9, v66, 15
	v_readlane_b32 s10, v66, 31
	v_readlane_b32 s11, v66, 47
	v_readlane_b32 vcc_lo, v66, 63
	s_nop 1
	v_mov_b32_e32 v66, s9
	v_add_f32_e32 v66, s10, v66
	v_add_f32_e32 v66, s11, v66
	v_add_f32_e32 v66, vcc_lo, v66
	v_mul_f32_e32 v116, 0x3a800000, v66
	v_mov_b32_e32 v117, v116
	v_pk_add_f32 v[18:19], v[18:19], v[116:117] neg_lo:[0,1] neg_hi:[0,1]
	v_pk_add_f32 v[20:21], v[20:21], v[116:117] neg_lo:[0,1] neg_hi:[0,1]
	v_pk_add_f32 v[22:23], v[22:23], v[116:117] neg_lo:[0,1] neg_hi:[0,1]
	v_pk_add_f32 v[24:25], v[24:25], v[116:117] neg_lo:[0,1] neg_hi:[0,1]
	v_pk_add_f32 v[26:27], v[26:27], v[116:117] neg_lo:[0,1] neg_hi:[0,1]
	v_pk_add_f32 v[28:29], v[28:29], v[116:117] neg_lo:[0,1] neg_hi:[0,1]
	v_pk_add_f32 v[30:31], v[30:31], v[116:117] neg_lo:[0,1] neg_hi:[0,1]
	v_pk_add_f32 v[32:33], v[32:33], v[116:117] neg_lo:[0,1] neg_hi:[0,1]
	v_pk_mul_f32 v[66:67], v[18:19], v[18:19]
	v_pk_mul_f32 v[68:69], v[20:21], v[20:21]
	v_pk_fma_f32 v[66:67], v[22:23], v[22:23], v[66:67]
	v_pk_fma_f32 v[68:69], v[24:25], v[24:25], v[68:69]
	v_pk_fma_f32 v[66:67], v[26:27], v[26:27], v[66:67]
	v_pk_fma_f32 v[68:69], v[28:29], v[28:29], v[68:69]
	v_pk_fma_f32 v[66:67], v[30:31], v[30:31], v[66:67]
	v_pk_fma_f32 v[68:69], v[32:33], v[32:33], v[68:69]
	v_pk_add_f32 v[66:67], v[66:67], v[68:69]
	v_add_f32_e32 v66, v66, v67
	s_nop 1
	v_add_f32_dpp v66, v66, v66 row_shr:1 row_mask:0xf bank_mask:0xf bound_ctrl:1
	s_nop 1
	v_add_f32_dpp v66, v66, v66 row_shr:2 row_mask:0xf bank_mask:0xf bound_ctrl:1
	s_nop 1
	v_add_f32_dpp v66, v66, v66 row_shr:4 row_mask:0xf bank_mask:0xf bound_ctrl:1
	s_nop 1
	v_add_f32_dpp v66, v66, v66 row_shr:8 row_mask:0xf bank_mask:0xf bound_ctrl:1
	s_nop 0
	v_readlane_b32 s9, v66, 15
	v_readlane_b32 s10, v66, 31
	v_readlane_b32 s11, v66, 47
	v_readlane_b32 vcc_lo, v66, 63
	s_nop 1
	v_mov_b32_e32 v66, s9
	v_add_f32_e32 v66, s10, v66
	v_add_f32_e32 v66, s11, v66
	v_add_f32_e32 v66, vcc_lo, v66
	v_mul_f32_e32 v66, 0x3a800000, v66
	v_add_f32_e32 v66, 0x3727c5ac, v66
	v_rsq_f32_e32 v118, v66
	s_nop 0
	v_mov_b32_e32 v119, v118
	v_pk_mul_f32 v[18:19], v[18:19], v[118:119]
	v_pk_mul_f32 v[20:21], v[20:21], v[118:119]
	v_pk_mul_f32 v[22:23], v[22:23], v[118:119]
	v_pk_mul_f32 v[24:25], v[24:25], v[118:119]
	v_pk_mul_f32 v[26:27], v[26:27], v[118:119]
	v_pk_mul_f32 v[28:29], v[28:29], v[118:119]
	v_pk_mul_f32 v[30:31], v[30:31], v[118:119]
	v_pk_mul_f32 v[32:33], v[32:33], v[118:119]
	v_pk_fma_f32 v[76:77], v[18:19], v[34:35], v[50:51]
	v_pk_fma_f32 v[78:79], v[20:21], v[36:37], v[52:53]
	v_pk_fma_f32 v[80:81], v[22:23], v[38:39], v[54:55]
	v_pk_fma_f32 v[82:83], v[24:25], v[40:41], v[56:57]
	v_pk_fma_f32 v[84:85], v[26:27], v[42:43], v[58:59]
	v_pk_fma_f32 v[86:87], v[28:29], v[44:45], v[60:61]
	v_pk_fma_f32 v[88:89], v[30:31], v[46:47], v[62:63]
	v_pk_fma_f32 v[90:91], v[32:33], v[48:49], v[64:65]
	s_cmp_lg_u32 s8, 0
	s_cbranch_scc1 .Lln2_f32_1
	v_cvt_pk_bf16_f32 v92, v76, v77
	v_cvt_pk_bf16_f32 v93, v78, v79
	v_cvt_pk_bf16_f32 v94, v80, v81
	v_cvt_pk_bf16_f32 v95, v82, v83
	v_cvt_pk_bf16_f32 v96, v84, v85
	v_cvt_pk_bf16_f32 v97, v86, v87
	v_cvt_pk_bf16_f32 v98, v88, v89
	v_cvt_pk_bf16_f32 v99, v90, v91
	global_store_dwordx2 v115, v[92:93], s[2:3] offset:0 sc1
	global_store_dwordx2 v115, v[94:95], s[2:3] offset:512 sc1
	global_store_dwordx2 v115, v[96:97], s[2:3] offset:1024 sc1
	global_store_dwordx2 v115, v[98:99], s[2:3] offset:1536 sc1
	s_branch .Lln2_st_1

; __device__ __forceinline__ void phase_ln(float* R, const float* __restrict__ g, const float* __restrict__ b, bf16_t* xbf, float samp_scale, const float* __restrict__ part, int nsplit, bool f32_all) {
;     ...
;   for (int r = gw; r < MT; r += nw) {
;     float* row = R + (size_t)r * 1024;
;     f32x4 v[4];
; #pragma unroll
;     for (int i = 0; i < 4; ++i) v[i] = *(const f32x4*)(row + i * 256 + lane * 4);
;     if (r >= MP) {
;       for (int sp = 0; sp < nsplit; ++sp) {
;         const float* prow = part + ((size_t)sp * MS + (r - MP)) * 1024;
; #pragma unroll
;         for (int i = 0; i < 4; ++i) v[i] = v[i] + *(const f32x4*)(prow + i * 256 + lane * 4);
;       }
;     }
;     float s = 0.f;
; #pragma unroll
;     for (int i = 0; i < 4; ++i) s += v[i][0] + v[i][1] + v[i][2] + v[i][3];
; #pragma unroll
;     for (int o = 32; o >= 1; o >>= 1) s += __shfl_xor(s, o);
;     const float mean = s * (1.f / 1024.f);
;     float ss = 0.f;
; #pragma unroll
;     for (int i = 0; i < 4; ++i) { v[i] = v[i] - mean; ss += v[i][0] * v[i][0] + v[i][1] * v[i][1] + v[i][2] * v[i][2] + v[i][3] * v[i][3]; }
; #pragma unroll
;     for (int o = 32; o >= 1; o >>= 1) ss += __shfl_xor(ss, o);
;     const float rstd = rsqrtf(ss * (1.f / 1024.f) + LN_EPS);
; #pragma unroll
;     for (int i = 0; i < 4; ++i) {
;       const f32x4 y = v[i] * rstd * gv[i] + bv[i];
;       if (r >= MP) *(f32x4*)(row + i * 256 + lane * 4) = y * samp_scale;
;       else if (f32_all) *(f32x4*)(row + i * 256 + lane * 4) = y;
;       if (xbf) {
;         u32x2 wv;
;         wv[0] = cvt_pk_bf16(y[0], y[1]); wv[1] = cvt_pk_bf16(y[2], y[3]);
;         *(u32x2*)(xbf + (size_t)r * 1024 + i * 256 + lane * 4) = wv;
;       }
;     }
.Lln2_st_1:
	s_add_u32 s2, s2, 0x400000
	s_addc_u32 s3, s3, 0
	s_add_u32 s0, s0, 0x800000
	s_addc_u32 s1, s1, 0
	global_load_dwordx4 v[18:21], v114, s[0:1] offset:0 nt
	global_load_dwordx4 v[22:25], v114, s[0:1] offset:1024 nt
	global_load_dwordx4 v[26:29], v114, s[0:1] offset:2048 nt
	global_load_dwordx4 v[30:33], v114, s[0:1] offset:3072 nt
	s_waitcnt vmcnt(8)
	v_pk_add_f32 v[66:67], v[0:1], v[2:3]
	v_pk_add_f32 v[68:69], v[4:5], v[6:7]
	v_pk_add_f32 v[70:71], v[8:9], v[10:11]
	v_pk_add_f32 v[72:73], v[12:13], v[14:15]
	v_pk_add_f32 v[66:67], v[66:67], v[68:69]
	v_pk_add_f32 v[70:71], v[70:71], v[72:73]
	v_pk_add_f32 v[66:67], v[66:67], v[70:71]
	v_add_f32_e32 v66, v66, v67
	s_nop 1
	v_add_f32_dpp v66, v66, v66 row_shr:1 row_mask:0xf bank_mask:0xf bound_ctrl:1
	s_nop 1
	v_add_f32_dpp v66, v66, v66 row_shr:2 row_mask:0xf bank_mask:0xf bound_ctrl:1
	s_nop 1
	v_add_f32_dpp v66, v66, v66 row_shr:4 row_mask:0xf bank_mask:0xf bound_ctrl:1
	s_nop 1
	v_add_f32_dpp v66, v66, v66 row_shr:8 row_mask:0xf bank_mask:0xf bound_ctrl:1
	s_nop 0
	v_readlane_b32 s9, v66, 15
	v_readlane_b32 s10, v66, 31
	v_readlane_b32 s11, v66, 47
	v_readlane_b32 vcc_lo, v66, 63
	s_nop 1
	v_mov_b32_e32 v66, s9
	v_add_f32_e32 v66, s10, v66
	v_add_f32_e32 v66, s11, v66
	v_add_f32_e32 v66, vcc_lo, v66
	v_mul_f32_e32 v116, 0x3a800000, v66
	v_mov_b32_e32 v117, v116
	v_pk_add_f32 v[0:1], v[0:1], v[116:117] neg_lo:[0,1] neg_hi:[0,1]
	v_pk_add_f32 v[2:3], v[2:3], v[116:117] neg_lo:[0,1] neg_hi:[0,1]
	v_pk_add_f32 v[4:5], v[4:5], v[116:117] neg_lo:[0,1] neg_hi:[0,1]
	v_pk_add_f32 v[6:7], v[6:7], v[116:117] neg_lo:[0,1] neg_hi:[0,1]
	v_pk_add_f32 v[8:9], v[8:9], v[116:117] neg_lo:[0,1] neg_hi:[0,1]
	v_pk_add_f32 v[10:11], v[10:11], v[116:117] neg_lo:[0,1] neg_hi:[0,1]
	v_pk_add_f32 v[12:13], v[12:13], v[116:117] neg_lo:[0,1] neg_hi:[0,1]
	v_pk_add_f32 v[14:15], v[14:15], v[116:117] neg_lo:[0,1] neg_hi:[0,1]
	v_pk_mul_f32 v[66:67], v[0:1], v[0:1]
	v_pk_mul_f32 v[68:69], v[2:3], v[2:3]
	v_pk_fma_f32 v[66:67], v[4:5], v[4:5], v[66:67]
	v_pk_fma_f32 v[68:69], v[6:7], v[6:7], v[68:69]
	v_pk_fma_f32 v[66:67], v[8:9], v[8:9], v[66:67]
	v_pk_fma_f32 v[68:69], v[10:11], v[10:11], v[68:69]
	v_pk_fma_f32 v[66:67], v[12:13], v[12:13], v[66:67]
	v_pk_fma_f32 v[68:69], v[14:15], v[14:15], v[68:69]
	v_pk_add_f32 v[66:67], v[66:67], v[68:69]
	v_add_f32_e32 v66, v66, v67
	s_nop 1
	v_add_f32_dpp v66, v66, v66 row_shr:1 row_mask:0xf bank_mask:0xf bound_ctrl:1
	s_nop 1
	v_add_f32_dpp v66, v66, v66 row_shr:2 row_mask:0xf bank_mask:0xf bound_ctrl:1
	s_nop 1
	v_add_f32_dpp v66, v66, v66 row_shr:4 row_mask:0xf bank_mask:0xf bound_ctrl:1
	s_nop 1
	v_add_f32_dpp v66, v66, v66 row_shr:8 row_mask:0xf bank_mask:0xf bound_ctrl:1
	s_nop 0
	v_readlane_b32 s9, v66, 15
	v_readlane_b32 s10, v66, 31
	v_readlane_b32 s11, v66, 47
	v_readlane_b32 vcc_lo, v66, 63
	s_nop 1
	v_mov_b32_e32 v66, s9
	v_add_f32_e32 v66, s10, v66
	v_add_f32_e32 v66, s11, v66
	v_add_f32_e32 v66, vcc_lo, v66
	v_mul_f32_e32 v66, 0x3a800000, v66
	v_add_f32_e32 v66, 0x3727c5ac, v66
	v_rsq_f32_e32 v118, v66
	s_nop 0
	v_mov_b32_e32 v119, v118
	v_pk_mul_f32 v[0:1], v[0:1], v[118:119]
	v_pk_mul_f32 v[2:3], v[2:3], v[118:119]
	v_pk_mul_f32 v[4:5], v[4:5], v[118:119]
	v_pk_mul_f32 v[6:7], v[6:7], v[118:119]
	v_pk_mul_f32 v[8:9], v[8:9], v[118:119]
	v_pk_mul_f32 v[10:11], v[10:11], v[118:119]
	v_pk_mul_f32 v[12:13], v[12:13], v[118:119]
	v_pk_mul_f32 v[14:15], v[14:15], v[118:119]
	v_pk_fma_f32 v[76:77], v[0:1], v[34:35], v[50:51]
	v_pk_fma_f32 v[78:79], v[2:3], v[36:37], v[52:53]
	v_pk_fma_f32 v[80:81], v[4:5], v[38:39], v[54:55]
	v_pk_fma_f32 v[82:83], v[6:7], v[40:41], v[56:57]
	v_pk_fma_f32 v[84:85], v[8:9], v[42:43], v[58:59]
	v_pk_fma_f32 v[86:87], v[10:11], v[44:45], v[60:61]
	v_pk_fma_f32 v[88:89], v[12:13], v[46:47], v[62:63]
	v_pk_fma_f32 v[90:91], v[14:15], v[48:49], v[64:65]
	s_cmp_lg_u32 s8, 0
	s_cbranch_scc1 .Lln2_f32_2
	v_cvt_pk_bf16_f32 v92, v76, v77
	v_cvt_pk_bf16_f32 v93, v78, v79
	v_cvt_pk_bf16_f32 v94, v80, v81
	v_cvt_pk_bf16_f32 v95, v82, v83
	v_cvt_pk_bf16_f32 v96, v84, v85
	v_cvt_pk_bf16_f32 v97, v86, v87
	v_cvt_pk_bf16_f32 v98, v88, v89
	v_cvt_pk_bf16_f32 v99, v90, v91
	global_store_dwordx2 v115, v[92:93], s[2:3] offset:0 sc1
	global_store_dwordx2 v115, v[94:95], s[2:3] offset:512 sc1
	global_store_dwordx2 v115, v[96:97], s[2:3] offset:1024 sc1
	global_store_dwordx2 v115, v[98:99], s[2:3] offset:1536 sc1
	s_branch .Lln2_st_2

; __device__ __forceinline__ void phase_ln(float* R, const float* __restrict__ g, const float* __restrict__ b, bf16_t* xbf, float samp_scale, const float* __restrict__ part, int nsplit, bool f32_all) {
;     ...
;   for (int r = gw; r < MT; r += nw) {
;     float* row = R + (size_t)r * 1024;
;     f32x4 v[4];
; #pragma unroll
;     for (int i = 0; i < 4; ++i) v[i] = *(const f32x4*)(row + i * 256 + lane * 4);
;     if (r >= MP) {
;       for (int sp = 0; sp < nsplit; ++sp) {
;         const float* prow = part + ((size_t)sp * MS + (r - MP)) * 1024;
; #pragma unroll
;         for (int i = 0; i < 4; ++i) v[i] = v[i] + *(const f32x4*)(prow + i * 256 + lane * 4);
;       }
;     }
.Lln2_st_15:
	s_add_u32 s2, s2, 0x400000
	s_addc_u32 s3, s3, 0
	v_readfirstlane_b32 s10, v244
	v_readlane_b32 s9, v254, 6
	s_lshr_b32 s10, s10, 6
	s_cmp_ge_u32 s10, 2
	s_cbranch_scc1 .Lln2_done
	s_lshl_b32 s9, s9, 1
	s_add_i32 s9, s9, s10
	s_lshl_b32 s11, s9, 12
	s_add_u32 s11, s11, 0x8000000
	s_add_u32 s0, s4, s11
	s_addc_u32 s1, s5, 0
	s_lshl_b32 s11, s9, 11
	s_add_u32 s11, s11, 0x79c0000
	s_add_u32 s2, s6, s11
	s_addc_u32 s3, s7, 0
	s_lshl_b32 s11, s9, 12
	s_add_u32 s11, s11, 0x1e482000
	s_add_u32 s10, s6, s11
	s_addc_u32 s11, s7, 0
	global_load_dwordx4 v[0:3], v114, s[0:1] offset:0 nt
	global_load_dwordx4 v[4:7], v114, s[0:1] offset:1024 nt
	global_load_dwordx4 v[8:11], v114, s[0:1] offset:2048 nt
	global_load_dwordx4 v[12:15], v114, s[0:1] offset:3072 nt
	global_load_dwordx4 v[18:21], v114, s[10:11] offset:0 nt
	global_load_dwordx4 v[22:25], v114, s[10:11] offset:1024 nt
	global_load_dwordx4 v[26:29], v114, s[10:11] offset:2048 nt
	global_load_dwordx4 v[30:33], v114, s[10:11] offset:3072 nt
	s_add_u32 s10, s10, 0x200000
	s_addc_u32 s11, s11, 0
	global_load_dwordx4 v[66:69], v114, s[10:11] offset:0 nt
	global_load_dwordx4 v[70:73], v114, s[10:11] offset:1024 nt
	global_load_dwordx4 v[74:77], v114, s[10:11] offset:2048 nt
	global_load_dwordx4 v[78:81], v114, s[10:11] offset:3072 nt
	s_add_u32 s10, s10, 0x200000
	s_addc_u32 s11, s11, 0
	global_load_dwordx4 v[82:85], v114, s[10:11] offset:0 nt
	global_load_dwordx4 v[86:89], v114, s[10:11] offset:1024 nt
	global_load_dwordx4 v[90:93], v114, s[10:11] offset:2048 nt
	global_load_dwordx4 v[94:97], v114, s[10:11] offset:3072 nt
	s_add_u32 s10, s10, 0x200000
	s_addc_u32 s11, s11, 0
	global_load_dwordx4 v[98:101], v114, s[10:11] offset:0 nt
	global_load_dwordx4 v[102:105], v114, s[10:11] offset:1024 nt
	global_load_dwordx4 v[106:109], v114, s[10:11] offset:2048 nt
	global_load_dwordx4 v[110:113], v114, s[10:11] offset:3072 nt
	s_add_u32 s10, s10, 0x200000
	s_addc_u32 s11, s11, 0
	s_waitcnt vmcnt(0)
	v_pk_add_f32 v[0:1], v[0:1], v[18:19]
	v_pk_add_f32 v[2:3], v[2:3], v[20:21]
	v_pk_add_f32 v[4:5], v[4:5], v[22:23]
	v_pk_add_f32 v[6:7], v[6:7], v[24:25]
	v_pk_add_f32 v[8:9], v[8:9], v[26:27]
	v_pk_add_f32 v[10:11], v[10:11], v[28:29]
	v_pk_add_f32 v[12:13], v[12:13], v[30:31]
	v_pk_add_f32 v[14:15], v[14:15], v[32:33]
	v_pk_add_f32 v[0:1], v[0:1], v[66:67]
	v_pk_add_f32 v[2:3], v[2:3], v[68:69]
	v_pk_add_f32 v[4:5], v[4:5], v[70:71]
	v_pk_add_f32 v[6:7], v[6:7], v[72:73]
	v_pk_add_f32 v[8:9], v[8:9], v[74:75]
	v_pk_add_f32 v[10:11], v[10:11], v[76:77]
	v_pk_add_f32 v[12:13], v[12:13], v[78:79]
	v_pk_add_f32 v[14:15], v[14:15], v[80:81]
	v_pk_add_f32 v[0:1], v[0:1], v[82:83]
	v_pk_add_f32 v[2:3], v[2:3], v[84:85]
	v_pk_add_f32 v[4:5], v[4:5], v[86:87]
	v_pk_add_f32 v[6:7], v[6:7], v[88:89]
	v_pk_add_f32 v[8:9], v[8:9], v[90:91]
	v_pk_add_f32 v[10:11], v[10:11], v[92:93]
	v_pk_add_f32 v[12:13], v[12:13], v[94:95]
	v_pk_add_f32 v[14:15], v[14:15], v[96:97]
	v_pk_add_f32 v[0:1], v[0:1], v[98:99]
	v_pk_add_f32 v[2:3], v[2:3], v[100:101]
	v_pk_add_f32 v[4:5], v[4:5], v[102:103]
	v_pk_add_f32 v[6:7], v[6:7], v[104:105]
	v_pk_add_f32 v[8:9], v[8:9], v[106:107]
	v_pk_add_f32 v[10:11], v[10:11], v[108:109]
	v_pk_add_f32 v[12:13], v[12:13], v[110:111]
	v_pk_add_f32 v[14:15], v[14:15], v[112:113]
	global_load_dwordx4 v[18:21], v114, s[10:11] offset:0 nt
	global_load_dwordx4 v[22:25], v114, s[10:11] offset:1024 nt
	global_load_dwordx4 v[26:29], v114, s[10:11] offset:2048 nt
	global_load_dwordx4 v[30:33], v114, s[10:11] offset:3072 nt
	s_add_u32 s10, s10, 0x200000
	s_addc_u32 s11, s11, 0
	global_load_dwordx4 v[66:69], v114, s[10:11] offset:0 nt
	global_load_dwordx4 v[70:73], v114, s[10:11] offset:1024 nt
	global_load_dwordx4 v[74:77], v114, s[10:11] offset:2048 nt
	global_load_dwordx4 v[78:81], v114, s[10:11] offset:3072 nt
	s_add_u32 s10, s10, 0x200000
	s_addc_u32 s11, s11, 0
	global_load_dwordx4 v[82:85], v114, s[10:11] offset:0 nt
	global_load_dwordx4 v[86:89], v114, s[10:11] offset:1024 nt
	global_load_dwordx4 v[90:93], v114, s[10:11] offset:2048 nt
	global_load_dwordx4 v[94:97], v114, s[10:11] offset:3072 nt
	s_add_u32 s10, s10, 0x200000
	s_addc_u32 s11, s11, 0
	global_load_dwordx4 v[98:101], v114, s[10:11] offset:0 nt
	global_load_dwordx4 v[102:105], v114, s[10:11] offset:1024 nt
	global_load_dwordx4 v[106:109], v114, s[10:11] offset:2048 nt
	global_load_dwordx4 v[110:113], v114, s[10:11] offset:3072 nt
	s_add_u32 s10, s10, 0x200000
	s_addc_u32 s11, s11, 0
	s_waitcnt vmcnt(0)
; __device__ __forceinline__ void phase_ln(float* R, const float* __restrict__ g, const float* __restrict__ b, bf16_t* xbf, float samp_scale, const float* __restrict__ part, int nsplit, bool f32_all) {
;     ...
;     if (r >= MP) {
;       for (int sp = 0; sp < nsplit; ++sp) {
;         const float* prow = part + ((size_t)sp * MS + (r - MP)) * 1024;
; #pragma unroll
;         for (int i = 0; i < 4; ++i) v[i] = v[i] + *(const f32x4*)(prow + i * 256 + lane * 4);
;       }
;     }
;     float s = 0.f;
; #pragma unroll
;     for (int i = 0; i < 4; ++i) s += v[i][0] + v[i][1] + v[i][2] + v[i][3];
; #pragma unroll
;     for (int o = 32; o >= 1; o >>= 1) s += __shfl_xor(s, o);
;     const float mean = s * (1.f / 1024.f);
;     float ss = 0.f;
; #pragma unroll
;     for (int i = 0; i < 4; ++i) { v[i] = v[i] - mean; ss += v[i][0] * v[i][0] + v[i][1] * v[i][1] + v[i][2] * v[i][2] + v[i][3] * v[i][3]; }
; #pragma unroll
;     for (int o = 32; o >= 1; o >>= 1) ss += __shfl_xor(ss, o);
;     const float rstd = rsqrtf(ss * (1.f / 1024.f) + LN_EPS);
; #pragma unroll
;     for (int i = 0; i < 4; ++i) {
;       const f32x4 y = v[i] * rstd * gv[i] + bv[i];
;       if (r >= MP) *(f32x4*)(row + i * 256 + lane * 4) = y * samp_scale;
;       else if (f32_all) *(f32x4*)(row + i * 256 + lane * 4) = y;
;       if (xbf) {
;         u32x2 wv;
;         wv[0] = cvt_pk_bf16(y[0], y[1]); wv[1] = cvt_pk_bf16(y[2], y[3]);
;         *(u32x2*)(xbf + (size_t)r * 1024 + i * 256 + lane * 4) = wv;
;       }
;     }
	v_pk_add_f32 v[0:1], v[0:1], v[18:19]
	v_pk_add_f32 v[2:3], v[2:3], v[20:21]
	v_pk_add_f32 v[4:5], v[4:5], v[22:23]
	v_pk_add_f32 v[6:7], v[6:7], v[24:25]
	v_pk_add_f32 v[8:9], v[8:9], v[26:27]
	v_pk_add_f32 v[10:11], v[10:11], v[28:29]
	v_pk_add_f32 v[12:13], v[12:13], v[30:31]
	v_pk_add_f32 v[14:15], v[14:15], v[32:33]
	v_pk_add_f32 v[0:1], v[0:1], v[66:67]
	v_pk_add_f32 v[2:3], v[2:3], v[68:69]
	v_pk_add_f32 v[4:5], v[4:5], v[70:71]
	v_pk_add_f32 v[6:7], v[6:7], v[72:73]
	v_pk_add_f32 v[8:9], v[8:9], v[74:75]
	v_pk_add_f32 v[10:11], v[10:11], v[76:77]
	v_pk_add_f32 v[12:13], v[12:13], v[78:79]
	v_pk_add_f32 v[14:15], v[14:15], v[80:81]
	v_pk_add_f32 v[0:1], v[0:1], v[82:83]
	v_pk_add_f32 v[2:3], v[2:3], v[84:85]
	v_pk_add_f32 v[4:5], v[4:5], v[86:87]
	v_pk_add_f32 v[6:7], v[6:7], v[88:89]
	v_pk_add_f32 v[8:9], v[8:9], v[90:91]
	v_pk_add_f32 v[10:11], v[10:11], v[92:93]
	v_pk_add_f32 v[12:13], v[12:13], v[94:95]
	v_pk_add_f32 v[14:15], v[14:15], v[96:97]
	v_pk_add_f32 v[0:1], v[0:1], v[98:99]
	v_pk_add_f32 v[2:3], v[2:3], v[100:101]
	v_pk_add_f32 v[4:5], v[4:5], v[102:103]
	v_pk_add_f32 v[6:7], v[6:7], v[104:105]
	v_pk_add_f32 v[8:9], v[8:9], v[106:107]
	v_pk_add_f32 v[10:11], v[10:11], v[108:109]
	v_pk_add_f32 v[12:13], v[12:13], v[110:111]
	v_pk_add_f32 v[14:15], v[14:15], v[112:113]
	v_pk_add_f32 v[66:67], v[0:1], v[2:3]
	v_pk_add_f32 v[68:69], v[4:5], v[6:7]
	v_pk_add_f32 v[70:71], v[8:9], v[10:11]
	v_pk_add_f32 v[72:73], v[12:13], v[14:15]
	v_pk_add_f32 v[66:67], v[66:67], v[68:69]
	v_pk_add_f32 v[70:71], v[70:71], v[72:73]
	v_pk_add_f32 v[66:67], v[66:67], v[70:71]
	v_add_f32_e32 v66, v66, v67
	s_nop 1
	v_add_f32_dpp v66, v66, v66 row_shr:1 row_mask:0xf bank_mask:0xf bound_ctrl:1
	s_nop 1
	v_add_f32_dpp v66, v66, v66 row_shr:2 row_mask:0xf bank_mask:0xf bound_ctrl:1
	s_nop 1
	v_add_f32_dpp v66, v66, v66 row_shr:4 row_mask:0xf bank_mask:0xf bound_ctrl:1
	s_nop 1
	v_add_f32_dpp v66, v66, v66 row_shr:8 row_mask:0xf bank_mask:0xf bound_ctrl:1
	s_nop 0
	v_readlane_b32 s9, v66, 15
	v_readlane_b32 s10, v66, 31
	v_readlane_b32 s11, v66, 47
	v_readlane_b32 vcc_lo, v66, 63
	s_nop 1
	v_mov_b32_e32 v66, s9
	v_add_f32_e32 v66, s10, v66
	v_add_f32_e32 v66, s11, v66
	v_add_f32_e32 v66, vcc_lo, v66
	v_mul_f32_e32 v116, 0x3a800000, v66
	v_mov_b32_e32 v117, v116
	v_pk_add_f32 v[0:1], v[0:1], v[116:117] neg_lo:[0,1] neg_hi:[0,1]
	v_pk_add_f32 v[2:3], v[2:3], v[116:117] neg_lo:[0,1] neg_hi:[0,1]
	v_pk_add_f32 v[4:5], v[4:5], v[116:117] neg_lo:[0,1] neg_hi:[0,1]
	v_pk_add_f32 v[6:7], v[6:7], v[116:117] neg_lo:[0,1] neg_hi:[0,1]
	v_pk_add_f32 v[8:9], v[8:9], v[116:117] neg_lo:[0,1] neg_hi:[0,1]
	v_pk_add_f32 v[10:11], v[10:11], v[116:117] neg_lo:[0,1] neg_hi:[0,1]
	v_pk_add_f32 v[12:13], v[12:13], v[116:117] neg_lo:[0,1] neg_hi:[0,1]
	v_pk_add_f32 v[14:15], v[14:15], v[116:117] neg_lo:[0,1] neg_hi:[0,1]
	v_pk_mul_f32 v[66:67], v[0:1], v[0:1]
	v_pk_mul_f32 v[68:69], v[2:3], v[2:3]
	v_pk_fma_f32 v[66:67], v[4:5], v[4:5], v[66:67]
	v_pk_fma_f32 v[68:69], v[6:7], v[6:7], v[68:69]
	v_pk_fma_f32 v[66:67], v[8:9], v[8:9], v[66:67]
	v_pk_fma_f32 v[68:69], v[10:11], v[10:11], v[68:69]
	v_pk_fma_f32 v[66:67], v[12:13], v[12:13], v[66:67]
	v_pk_fma_f32 v[68:69], v[14:15], v[14:15], v[68:69]
	v_pk_add_f32 v[66:67], v[66:67], v[68:69]
	v_add_f32_e32 v66, v66, v67
	s_nop 1
	v_add_f32_dpp v66, v66, v66 row_shr:1 row_mask:0xf bank_mask:0xf bound_ctrl:1
	s_nop 1
	v_add_f32_dpp v66, v66, v66 row_shr:2 row_mask:0xf bank_mask:0xf bound_ctrl:1
	s_nop 1
	v_add_f32_dpp v66, v66, v66 row_shr:4 row_mask:0xf bank_mask:0xf bound_ctrl:1
	s_nop 1
	v_add_f32_dpp v66, v66, v66 row_shr:8 row_mask:0xf bank_mask:0xf bound_ctrl:1
	s_nop 0
	v_readlane_b32 s9, v66, 15
	v_readlane_b32 s10, v66, 31
	v_readlane_b32 s11, v66, 47
	v_readlane_b32 vcc_lo, v66, 63
	s_nop 1
	v_mov_b32_e32 v66, s9
	v_add_f32_e32 v66, s10, v66
	v_add_f32_e32 v66, s11, v66
	v_add_f32_e32 v66, vcc_lo, v66
	v_mul_f32_e32 v66, 0x3a800000, v66
	v_add_f32_e32 v66, 0x3727c5ac, v66
	v_rsq_f32_e32 v118, v66
	s_nop 0
	v_mov_b32_e32 v119, v118
	v_pk_mul_f32 v[0:1], v[0:1], v[118:119]
	v_pk_mul_f32 v[2:3], v[2:3], v[118:119]
	v_pk_mul_f32 v[4:5], v[4:5], v[118:119]
	v_pk_mul_f32 v[6:7], v[6:7], v[118:119]
	v_pk_mul_f32 v[8:9], v[8:9], v[118:119]
	v_pk_mul_f32 v[10:11], v[10:11], v[118:119]
	v_pk_mul_f32 v[12:13], v[12:13], v[118:119]
	v_pk_mul_f32 v[14:15], v[14:15], v[118:119]
	v_pk_fma_f32 v[76:77], v[0:1], v[34:35], v[50:51]
	v_pk_fma_f32 v[78:79], v[2:3], v[36:37], v[52:53]
	v_pk_fma_f32 v[80:81], v[4:5], v[38:39], v[54:55]
	v_pk_fma_f32 v[82:83], v[6:7], v[40:41], v[56:57]
	v_pk_fma_f32 v[84:85], v[8:9], v[42:43], v[58:59]
	v_pk_fma_f32 v[86:87], v[10:11], v[44:45], v[60:61]
	v_pk_fma_f32 v[88:89], v[12:13], v[46:47], v[62:63]
	v_pk_fma_f32 v[90:91], v[14:15], v[48:49], v[64:65]
	s_cmp_lg_u32 s8, 0
	s_cselect_b32 s9, 1.0, 0x3fb504f3
	v_mov_b32_e32 v120, s9
	v_mov_b32_e32 v121, s9
	v_pk_mul_f32 v[0:1], v[76:77], v[120:121]
	v_pk_mul_f32 v[2:3], v[78:79], v[120:121]
	v_pk_mul_f32 v[4:5], v[80:81], v[120:121]
	v_pk_mul_f32 v[6:7], v[82:83], v[120:121]
	v_pk_mul_f32 v[8:9], v[84:85], v[120:121]
	v_pk_mul_f32 v[10:11], v[86:87], v[120:121]
	v_pk_mul_f32 v[12:13], v[88:89], v[120:121]
	v_pk_mul_f32 v[14:15], v[90:91], v[120:121]
	global_store_dwordx4 v114, v[0:3], s[0:1] offset:0 sc1
	global_store_dwordx4 v114, v[4:7], s[0:1] offset:1024 sc1
	global_store_dwordx4 v114, v[8:11], s[0:1] offset:2048 sc1
	global_store_dwordx4 v114, v[12:15], s[0:1] offset:3072 sc1
	s_cmp_lg_u32 s8, 0
	s_cbranch_scc1 .Lln2_done
	v_cvt_pk_bf16_f32 v92, v76, v77
	v_cvt_pk_bf16_f32 v93, v78, v79
	v_cvt_pk_bf16_f32 v94, v80, v81
	v_cvt_pk_bf16_f32 v95, v82, v83
	v_cvt_pk_bf16_f32 v96, v84, v85
	v_cvt_pk_bf16_f32 v97, v86, v87
	v_cvt_pk_bf16_f32 v98, v88, v89
	v_cvt_pk_bf16_f32 v99, v90, v91
	global_store_dwordx2 v115, v[92:93], s[2:3] offset:0 sc1
	global_store_dwordx2 v115, v[94:95], s[2:3] offset:512 sc1
	global_store_dwordx2 v115, v[96:97], s[2:3] offset:1024 sc1
	global_store_dwordx2 v115, v[98:99], s[2:3] offset:1536 sc1
